# baseline (speedup 1.0000x reference)
.LBB0_65:
	ds_read_b128 v[128:131], v173
	ds_read_b128 v[132:135], v173 offset:1024
	ds_read_b128 v[158:161], v173 offset:2048
	ds_read_b128 v[178:181], v173 offset:3072
	ds_read_b128 v[182:185], v174
	ds_read_b128 v[186:189], v174 offset:1024
	ds_read_b128 v[190:193], v174 offset:2048
	ds_read_b128 v[194:197], v174 offset:3072
	s_add_u32 s3, s14, 0xfff80080
	s_addc_u32 s34, s15, -1
	s_cmp_eq_u32 s37, 28
	s_cselect_b32 s91, s0, s34
	s_cselect_b32 s90, s1, s3
	s_cselect_b32 s35, s7, s36
	s_cselect_b32 s34, s13, s24
	s_add_i32 m0, s27, 0xc000
	ds_read_b128 v[198:201], v175
	ds_read_b128 v[202:205], v175 offset:1024
	ds_read_b128 v[206:209], v175 offset:2048
	ds_read_b128 v[210:213], v175 offset:3072
	ds_read_b128 v[214:217], v175 offset:4096
	ds_read_b128 v[218:221], v175 offset:5120
	ds_read_b128 v[222:225], v175 offset:6144
	ds_read_b128 v[230:233], v175 offset:7168
	global_load_lds_dwordx4 v148, s[14:15]
	s_add_i32 m0, s27, 0xe000
	s_nop 0
	global_load_lds_dwordx4 v150, s[14:15]
	s_waitcnt vmcnt(8)
	s_waitcnt lgkmcnt(0)
	s_barrier
	s_setprio 1
	s_waitcnt lgkmcnt(0)
	v_mfma_f32_16x16x32_bf16 v[124:127], v[128:131], v[198:201], v[124:127]
	v_mfma_f32_16x16x32_bf16 v[120:123], v[158:161], v[198:201], v[120:123]
	v_mfma_f32_16x16x32_bf16 v[108:111], v[128:131], v[206:209], v[108:111]
	v_mfma_f32_16x16x32_bf16 v[104:107], v[158:161], v[206:209], v[104:107]
	v_mfma_f32_16x16x32_bf16 v[92:95], v[128:131], v[214:217], v[92:95]
	v_mfma_f32_16x16x32_bf16 v[88:91], v[158:161], v[214:217], v[88:91]
	v_mfma_f32_16x16x32_bf16 v[76:79], v[128:131], v[222:225], v[76:79]
	v_mfma_f32_16x16x32_bf16 v[72:75], v[158:161], v[222:225], v[72:75]
	v_mfma_f32_16x16x32_bf16 v[124:127], v[132:135], v[202:205], v[124:127]
	v_mfma_f32_16x16x32_bf16 v[120:123], v[178:181], v[202:205], v[120:123]
	v_mfma_f32_16x16x32_bf16 v[108:111], v[132:135], v[210:213], v[108:111]
	v_mfma_f32_16x16x32_bf16 v[104:107], v[178:181], v[210:213], v[104:107]
	v_mfma_f32_16x16x32_bf16 v[92:95], v[132:135], v[218:221], v[92:95]
	v_mfma_f32_16x16x32_bf16 v[88:91], v[178:181], v[218:221], v[88:91]
	v_mfma_f32_16x16x32_bf16 v[76:79], v[132:135], v[230:233], v[76:79]
	v_mfma_f32_16x16x32_bf16 v[72:75], v[178:181], v[230:233], v[72:75]
	v_mfma_f32_16x16x32_bf16 v[116:119], v[182:185], v[198:201], v[116:119]
	v_mfma_f32_16x16x32_bf16 v[112:115], v[190:193], v[198:201], v[112:115]
	v_mfma_f32_16x16x32_bf16 v[100:103], v[182:185], v[206:209], v[100:103]
	v_mfma_f32_16x16x32_bf16 v[96:99], v[190:193], v[206:209], v[96:99]
	v_mfma_f32_16x16x32_bf16 v[84:87], v[182:185], v[214:217], v[84:87]
	v_mfma_f32_16x16x32_bf16 v[80:83], v[190:193], v[214:217], v[80:83]
	v_mfma_f32_16x16x32_bf16 v[68:71], v[182:185], v[222:225], v[68:71]
	v_mfma_f32_16x16x32_bf16 v[64:67], v[190:193], v[222:225], v[64:67]
	v_mfma_f32_16x16x32_bf16 v[116:119], v[186:189], v[202:205], v[116:119]
	v_mfma_f32_16x16x32_bf16 v[112:115], v[194:197], v[202:205], v[112:115]
	v_mfma_f32_16x16x32_bf16 v[100:103], v[186:189], v[210:213], v[100:103]
	v_mfma_f32_16x16x32_bf16 v[96:99], v[194:197], v[210:213], v[96:99]
	v_mfma_f32_16x16x32_bf16 v[84:87], v[186:189], v[218:221], v[84:87]
	v_mfma_f32_16x16x32_bf16 v[80:83], v[194:197], v[218:221], v[80:83]
	v_mfma_f32_16x16x32_bf16 v[68:71], v[186:189], v[230:233], v[68:71]
	v_mfma_f32_16x16x32_bf16 v[64:67], v[194:197], v[230:233], v[64:67]
	s_setprio 0
	s_barrier
	s_add_i32 s3, s78, s25
	s_mov_b32 m0, s3
	ds_read_b128 v[198:201], v175 offset:16384
	ds_read_b128 v[202:205], v175 offset:17408
	ds_read_b128 v[206:209], v175 offset:18432
	ds_read_b128 v[210:213], v175 offset:19456
	ds_read_b128 v[214:217], v175 offset:20480
	ds_read_b128 v[218:221], v175 offset:21504
	ds_read_b128 v[222:225], v175 offset:22528
	ds_read_b128 v[230:233], v175 offset:23552
	global_load_lds_dwordx4 v138, s[34:35]
	s_add_i32 m0, s3, 0x2000
	s_add_u32 s42, s34, 0x80000
	s_addc_u32 s43, s35, 0
	s_add_i32 s3, s79, s25
	global_load_lds_dwordx4 v142, s[34:35]
	s_mov_b32 m0, s3
	s_nop 0
	global_load_lds_dwordx4 v138, s[42:43]
	s_add_i32 m0, s3, 0x2000
	s_nop 0
	global_load_lds_dwordx4 v142, s[42:43]
	s_mov_b32 m0, s27
	s_nop 0
	global_load_lds_dwordx4 v136, s[90:91]
	s_mov_b32 m0, s30
	s_nop 0
	global_load_lds_dwordx4 v140, s[90:91]
	s_waitcnt vmcnt(8)
	s_waitcnt lgkmcnt(0)
	s_barrier
	s_setprio 1
	s_waitcnt lgkmcnt(0)
	v_mfma_f32_16x16x32_bf16 v[60:63], v[128:131], v[198:201], v[60:63]
	v_mfma_f32_16x16x32_bf16 v[56:59], v[158:161], v[198:201], v[56:59]
	v_mfma_f32_16x16x32_bf16 v[44:47], v[128:131], v[206:209], v[44:47]
	v_mfma_f32_16x16x32_bf16 v[40:43], v[158:161], v[206:209], v[40:43]
	v_mfma_f32_16x16x32_bf16 v[28:31], v[128:131], v[214:217], v[28:31]
	v_mfma_f32_16x16x32_bf16 v[24:27], v[158:161], v[214:217], v[24:27]
	v_mfma_f32_16x16x32_bf16 v[12:15], v[128:131], v[222:225], v[12:15]
	v_mfma_f32_16x16x32_bf16 v[8:11], v[158:161], v[222:225], v[8:11]
	v_mfma_f32_16x16x32_bf16 v[60:63], v[132:135], v[202:205], v[60:63]
	v_mfma_f32_16x16x32_bf16 v[56:59], v[178:181], v[202:205], v[56:59]
	v_mfma_f32_16x16x32_bf16 v[44:47], v[132:135], v[210:213], v[44:47]
	v_mfma_f32_16x16x32_bf16 v[40:43], v[178:181], v[210:213], v[40:43]
	v_mfma_f32_16x16x32_bf16 v[28:31], v[132:135], v[218:221], v[28:31]
	v_mfma_f32_16x16x32_bf16 v[24:27], v[178:181], v[218:221], v[24:27]
	v_mfma_f32_16x16x32_bf16 v[12:15], v[132:135], v[230:233], v[12:15]
	v_mfma_f32_16x16x32_bf16 v[8:11], v[178:181], v[230:233], v[8:11]
	v_mfma_f32_16x16x32_bf16 v[52:55], v[182:185], v[198:201], v[52:55]
	v_mfma_f32_16x16x32_bf16 v[48:51], v[190:193], v[198:201], v[48:51]
	v_mfma_f32_16x16x32_bf16 v[36:39], v[182:185], v[206:209], v[36:39]
	v_mfma_f32_16x16x32_bf16 v[32:35], v[190:193], v[206:209], v[32:35]
	v_mfma_f32_16x16x32_bf16 v[20:23], v[182:185], v[214:217], v[20:23]
	v_mfma_f32_16x16x32_bf16 v[16:19], v[190:193], v[214:217], v[16:19]
	v_mfma_f32_16x16x32_bf16 v[4:7], v[182:185], v[222:225], v[4:7]
	v_mfma_f32_16x16x32_bf16 v[0:3], v[190:193], v[222:225], v[0:3]
	v_mfma_f32_16x16x32_bf16 v[52:55], v[186:189], v[202:205], v[52:55]
	v_mfma_f32_16x16x32_bf16 v[48:51], v[194:197], v[202:205], v[48:51]
	v_mfma_f32_16x16x32_bf16 v[36:39], v[186:189], v[210:213], v[36:39]
	v_mfma_f32_16x16x32_bf16 v[32:35], v[194:197], v[210:213], v[32:35]
	v_mfma_f32_16x16x32_bf16 v[20:23], v[186:189], v[218:221], v[20:23]
	v_mfma_f32_16x16x32_bf16 v[16:19], v[194:197], v[218:221], v[16:19]
	v_mfma_f32_16x16x32_bf16 v[4:7], v[186:189], v[230:233], v[4:7]
	v_mfma_f32_16x16x32_bf16 v[0:3], v[194:197], v[230:233], v[0:3]
	s_setprio 0
	s_barrier
	s_add_i32 s3, 0, 0x18000
	v_add_u32_e32 v144, s3, v165
	s_add_i32 s44, 0, 0x1c000
	ds_read_b128 v[128:131], v144
	ds_read_b128 v[132:135], v144 offset:1024
	ds_read_b128 v[158:161], v144 offset:2048
	ds_read_b128 v[178:181], v144 offset:3072
	v_add_u32_e32 v144, s44, v165
	ds_read_b128 v[182:185], v144
	ds_read_b128 v[186:189], v144 offset:1024
	ds_read_b128 v[190:193], v144 offset:2048
	ds_read_b128 v[194:197], v144 offset:3072
	s_add_u32 s42, s90, 0x80000
	s_addc_u32 s43, s91, 0
	s_mov_b32 m0, s31
	ds_read_b128 v[198:201], v175 offset:32768
	ds_read_b128 v[202:205], v175 offset:33792
	ds_read_b128 v[206:209], v175 offset:34816
	ds_read_b128 v[210:213], v175 offset:35840
	ds_read_b128 v[214:217], v175 offset:36864
	ds_read_b128 v[218:221], v175 offset:37888
	ds_read_b128 v[222:225], v175 offset:38912
	ds_read_b128 v[230:233], v175 offset:39936
	global_load_lds_dwordx4 v136, s[42:43]
	s_mov_b32 m0, s33
	s_nop 0
	global_load_lds_dwordx4 v140, s[42:43]
	s_waitcnt vmcnt(8)
	s_waitcnt lgkmcnt(0)
	s_barrier
	s_setprio 1
	s_waitcnt lgkmcnt(0)
	v_mfma_f32_16x16x32_bf16 v[124:127], v[128:131], v[198:201], v[124:127]
	v_mfma_f32_16x16x32_bf16 v[120:123], v[158:161], v[198:201], v[120:123]
	v_mfma_f32_16x16x32_bf16 v[108:111], v[128:131], v[206:209], v[108:111]
	v_mfma_f32_16x16x32_bf16 v[104:107], v[158:161], v[206:209], v[104:107]
	v_mfma_f32_16x16x32_bf16 v[92:95], v[128:131], v[214:217], v[92:95]
	v_mfma_f32_16x16x32_bf16 v[88:91], v[158:161], v[214:217], v[88:91]
	v_mfma_f32_16x16x32_bf16 v[76:79], v[128:131], v[222:225], v[76:79]
	v_mfma_f32_16x16x32_bf16 v[72:75], v[158:161], v[222:225], v[72:75]
	v_mfma_f32_16x16x32_bf16 v[124:127], v[132:135], v[202:205], v[124:127]
	v_mfma_f32_16x16x32_bf16 v[120:123], v[178:181], v[202:205], v[120:123]
	v_mfma_f32_16x16x32_bf16 v[108:111], v[132:135], v[210:213], v[108:111]
	v_mfma_f32_16x16x32_bf16 v[104:107], v[178:181], v[210:213], v[104:107]
	v_mfma_f32_16x16x32_bf16 v[92:95], v[132:135], v[218:221], v[92:95]
	v_mfma_f32_16x16x32_bf16 v[88:91], v[178:181], v[218:221], v[88:91]
	v_mfma_f32_16x16x32_bf16 v[76:79], v[132:135], v[230:233], v[76:79]
	v_mfma_f32_16x16x32_bf16 v[72:75], v[178:181], v[230:233], v[72:75]
	v_mfma_f32_16x16x32_bf16 v[116:119], v[182:185], v[198:201], v[116:119]
	v_mfma_f32_16x16x32_bf16 v[112:115], v[190:193], v[198:201], v[112:115]
	v_mfma_f32_16x16x32_bf16 v[100:103], v[182:185], v[206:209], v[100:103]
	v_mfma_f32_16x16x32_bf16 v[96:99], v[190:193], v[206:209], v[96:99]
	v_mfma_f32_16x16x32_bf16 v[84:87], v[182:185], v[214:217], v[84:87]
	v_mfma_f32_16x16x32_bf16 v[80:83], v[190:193], v[214:217], v[80:83]
	v_mfma_f32_16x16x32_bf16 v[68:71], v[182:185], v[222:225], v[68:71]
	v_mfma_f32_16x16x32_bf16 v[64:67], v[190:193], v[222:225], v[64:67]
	v_mfma_f32_16x16x32_bf16 v[116:119], v[186:189], v[202:205], v[116:119]
	v_mfma_f32_16x16x32_bf16 v[112:115], v[194:197], v[202:205], v[112:115]
	v_mfma_f32_16x16x32_bf16 v[100:103], v[186:189], v[210:213], v[100:103]
	v_mfma_f32_16x16x32_bf16 v[96:99], v[194:197], v[210:213], v[96:99]
	v_mfma_f32_16x16x32_bf16 v[84:87], v[186:189], v[218:221], v[84:87]
	v_mfma_f32_16x16x32_bf16 v[80:83], v[194:197], v[218:221], v[80:83]
	v_mfma_f32_16x16x32_bf16 v[68:71], v[186:189], v[230:233], v[68:71]
	v_mfma_f32_16x16x32_bf16 v[64:67], v[194:197], v[230:233], v[64:67]
	s_setprio 0
	s_barrier
	s_add_i32 s3, s3, s25
	s_add_u32 s34, s34, 0x80
	s_addc_u32 s35, s35, 0
	s_mov_b32 m0, s3
	ds_read_b128 v[198:201], v175 offset:49152
	ds_read_b128 v[202:205], v175 offset:50176
	ds_read_b128 v[206:209], v175 offset:51200
	ds_read_b128 v[210:213], v175 offset:52224
	ds_read_b128 v[214:217], v175 offset:53248
	ds_read_b128 v[218:221], v175 offset:54272
	ds_read_b128 v[222:225], v175 offset:55296
	ds_read_b128 v[230:233], v175 offset:56320
	global_load_lds_dwordx4 v138, s[34:35]
	s_add_i32 m0, s3, 0x2000
	s_add_i32 s3, s44, s25
	global_load_lds_dwordx4 v142, s[34:35]
	s_add_u32 s34, s34, 0x80000
	s_addc_u32 s35, s35, 0
	s_mov_b32 m0, s3
	s_nop 0
	global_load_lds_dwordx4 v138, s[34:35]
	s_add_i32 m0, s3, 0x2000
	s_nop 0
	global_load_lds_dwordx4 v142, s[34:35]
	s_add_u32 s90, s90, 0x80
	s_addc_u32 s91, s91, 0
	s_mov_b32 m0, s58
	s_nop 0
	global_load_lds_dwordx4 v136, s[90:91]
	s_mov_b32 m0, s59
	s_nop 0
	global_load_lds_dwordx4 v140, s[90:91]
	s_waitcnt vmcnt(8)
	s_waitcnt lgkmcnt(0)
	s_barrier
	s_setprio 1
	s_waitcnt lgkmcnt(0)
	v_mfma_f32_16x16x32_bf16 v[60:63], v[128:131], v[198:201], v[60:63]
	v_mfma_f32_16x16x32_bf16 v[56:59], v[158:161], v[198:201], v[56:59]
	v_mfma_f32_16x16x32_bf16 v[44:47], v[128:131], v[206:209], v[44:47]
	v_mfma_f32_16x16x32_bf16 v[40:43], v[158:161], v[206:209], v[40:43]
	v_mfma_f32_16x16x32_bf16 v[28:31], v[128:131], v[214:217], v[28:31]
	v_mfma_f32_16x16x32_bf16 v[24:27], v[158:161], v[214:217], v[24:27]
	v_mfma_f32_16x16x32_bf16 v[12:15], v[128:131], v[222:225], v[12:15]
	v_mfma_f32_16x16x32_bf16 v[8:11], v[158:161], v[222:225], v[8:11]
	v_mfma_f32_16x16x32_bf16 v[60:63], v[132:135], v[202:205], v[60:63]
	v_mfma_f32_16x16x32_bf16 v[56:59], v[178:181], v[202:205], v[56:59]
	v_mfma_f32_16x16x32_bf16 v[44:47], v[132:135], v[210:213], v[44:47]
	v_mfma_f32_16x16x32_bf16 v[40:43], v[178:181], v[210:213], v[40:43]
	v_mfma_f32_16x16x32_bf16 v[28:31], v[132:135], v[218:221], v[28:31]
	v_mfma_f32_16x16x32_bf16 v[24:27], v[178:181], v[218:221], v[24:27]
	v_mfma_f32_16x16x32_bf16 v[12:15], v[132:135], v[230:233], v[12:15]
	v_mfma_f32_16x16x32_bf16 v[8:11], v[178:181], v[230:233], v[8:11]
	v_mfma_f32_16x16x32_bf16 v[52:55], v[182:185], v[198:201], v[52:55]
	v_mfma_f32_16x16x32_bf16 v[48:51], v[190:193], v[198:201], v[48:51]
	v_mfma_f32_16x16x32_bf16 v[36:39], v[182:185], v[206:209], v[36:39]
	v_mfma_f32_16x16x32_bf16 v[32:35], v[190:193], v[206:209], v[32:35]
	v_mfma_f32_16x16x32_bf16 v[20:23], v[182:185], v[214:217], v[20:23]
	v_mfma_f32_16x16x32_bf16 v[16:19], v[190:193], v[214:217], v[16:19]
	v_mfma_f32_16x16x32_bf16 v[4:7], v[182:185], v[222:225], v[4:7]
	v_mfma_f32_16x16x32_bf16 v[0:3], v[190:193], v[222:225], v[0:3]
	v_mfma_f32_16x16x32_bf16 v[52:55], v[186:189], v[202:205], v[52:55]
	v_mfma_f32_16x16x32_bf16 v[48:51], v[194:197], v[202:205], v[48:51]
	v_mfma_f32_16x16x32_bf16 v[36:39], v[186:189], v[210:213], v[36:39]
	v_mfma_f32_16x16x32_bf16 v[32:35], v[194:197], v[210:213], v[32:35]
	v_mfma_f32_16x16x32_bf16 v[20:23], v[186:189], v[218:221], v[20:23]
	v_mfma_f32_16x16x32_bf16 v[16:19], v[194:197], v[218:221], v[16:19]
	v_mfma_f32_16x16x32_bf16 v[4:7], v[186:189], v[230:233], v[4:7]
	v_mfma_f32_16x16x32_bf16 v[0:3], v[194:197], v[230:233], v[0:3]
	s_setprio 0
	s_add_i32 s37, s37, 2
	s_add_u32 s14, s14, 0x100
	s_addc_u32 s15, s15, 0
	s_add_u32 s24, s24, 0x100
	s_addc_u32 s36, s36, 0
	s_cmp_gt_u32 s37, 29
	s_barrier
	s_cbranch_scc0 .LBB0_65
	s_and_b64 vcc, exec, s[48:49]
	s_cbranch_vccz .LBB0_68
	s_barrier

.LBB0_539:
	ds_read_b128 v[144:147], v153
	ds_read_b128 v[156:159], v153 offset:1024
	ds_read_b128 v[160:163], v153 offset:2048
	ds_read_b128 v[164:167], v153 offset:3072
	ds_read_b128 v[168:171], v154
	ds_read_b128 v[172:175], v154 offset:1024
	ds_read_b128 v[176:179], v154 offset:2048
	ds_read_b128 v[180:183], v154 offset:3072
	s_add_u32 s3, s86, 0xfffc0080
	s_addc_u32 s37, s87, -1
	s_cmp_eq_u32 s36, 12
	s_cselect_b32 s91, s0, s37
	s_cselect_b32 s90, s1, s3
	s_cselect_b32 s89, s17, s35
	s_cselect_b32 s88, s27, s33
	s_add_i32 m0, s19, 0xc000
	ds_read_b128 v[184:187], v155
	ds_read_b128 v[188:191], v155 offset:1024
	ds_read_b128 v[192:195], v155 offset:2048
	ds_read_b128 v[196:199], v155 offset:3072
	ds_read_b128 v[200:203], v155 offset:4096
	ds_read_b128 v[204:207], v155 offset:5120
	ds_read_b128 v[208:211], v155 offset:6144
	ds_read_b128 v[212:215], v155 offset:7168
	global_load_lds_dwordx4 v136, s[86:87]
	s_add_i32 m0, s19, 0xe000
	s_nop 0
	global_load_lds_dwordx4 v138, s[86:87]
	s_waitcnt vmcnt(8)
	s_waitcnt lgkmcnt(0)
	s_barrier
	s_setprio 1
	s_waitcnt lgkmcnt(0)
	v_mfma_f32_16x16x32_bf16 v[124:127], v[144:147], v[184:187], v[124:127]
	v_mfma_f32_16x16x32_bf16 v[120:123], v[160:163], v[184:187], v[120:123]
	v_mfma_f32_16x16x32_bf16 v[108:111], v[144:147], v[192:195], v[108:111]
	v_mfma_f32_16x16x32_bf16 v[104:107], v[160:163], v[192:195], v[104:107]
	v_mfma_f32_16x16x32_bf16 v[92:95], v[144:147], v[200:203], v[92:95]
	v_mfma_f32_16x16x32_bf16 v[88:91], v[160:163], v[200:203], v[88:91]
	v_mfma_f32_16x16x32_bf16 v[76:79], v[144:147], v[208:211], v[76:79]
	v_mfma_f32_16x16x32_bf16 v[72:75], v[160:163], v[208:211], v[72:75]
	v_mfma_f32_16x16x32_bf16 v[124:127], v[156:159], v[188:191], v[124:127]
	v_mfma_f32_16x16x32_bf16 v[120:123], v[164:167], v[188:191], v[120:123]
	v_mfma_f32_16x16x32_bf16 v[108:111], v[156:159], v[196:199], v[108:111]
	v_mfma_f32_16x16x32_bf16 v[104:107], v[164:167], v[196:199], v[104:107]
	v_mfma_f32_16x16x32_bf16 v[92:95], v[156:159], v[204:207], v[92:95]
	v_mfma_f32_16x16x32_bf16 v[88:91], v[164:167], v[204:207], v[88:91]
	v_mfma_f32_16x16x32_bf16 v[76:79], v[156:159], v[212:215], v[76:79]
	v_mfma_f32_16x16x32_bf16 v[72:75], v[164:167], v[212:215], v[72:75]
	v_mfma_f32_16x16x32_bf16 v[116:119], v[168:171], v[184:187], v[116:119]
	v_mfma_f32_16x16x32_bf16 v[112:115], v[176:179], v[184:187], v[112:115]
	v_mfma_f32_16x16x32_bf16 v[100:103], v[168:171], v[192:195], v[100:103]
	v_mfma_f32_16x16x32_bf16 v[96:99], v[176:179], v[192:195], v[96:99]
	v_mfma_f32_16x16x32_bf16 v[84:87], v[168:171], v[200:203], v[84:87]
	v_mfma_f32_16x16x32_bf16 v[80:83], v[176:179], v[200:203], v[80:83]
	v_mfma_f32_16x16x32_bf16 v[68:71], v[168:171], v[208:211], v[68:71]
	v_mfma_f32_16x16x32_bf16 v[64:67], v[176:179], v[208:211], v[64:67]
	v_mfma_f32_16x16x32_bf16 v[116:119], v[172:175], v[188:191], v[116:119]
	v_mfma_f32_16x16x32_bf16 v[112:115], v[180:183], v[188:191], v[112:115]
	v_mfma_f32_16x16x32_bf16 v[100:103], v[172:175], v[196:199], v[100:103]
	v_mfma_f32_16x16x32_bf16 v[96:99], v[180:183], v[196:199], v[96:99]
	v_mfma_f32_16x16x32_bf16 v[84:87], v[172:175], v[204:207], v[84:87]
	v_mfma_f32_16x16x32_bf16 v[80:83], v[180:183], v[204:207], v[80:83]
	v_mfma_f32_16x16x32_bf16 v[68:71], v[172:175], v[212:215], v[68:71]
	v_mfma_f32_16x16x32_bf16 v[64:67], v[180:183], v[212:215], v[64:67]
	s_setprio 0
	s_barrier
	s_add_i32 s3, s57, s18
	s_mov_b32 m0, s3
	ds_read_b128 v[184:187], v155 offset:16384
	ds_read_b128 v[188:191], v155 offset:17408
	ds_read_b128 v[192:195], v155 offset:18432
	ds_read_b128 v[196:199], v155 offset:19456
	ds_read_b128 v[200:203], v155 offset:20480
	ds_read_b128 v[204:207], v155 offset:21504
	ds_read_b128 v[208:211], v155 offset:22528
	ds_read_b128 v[212:215], v155 offset:23552
	global_load_lds_dwordx4 v130, s[88:89]
	s_add_i32 m0, s3, 0x2000
	s_add_u32 s42, s88, 0x40000
	s_addc_u32 s43, s89, 0
	s_add_i32 s3, s58, s18
	global_load_lds_dwordx4 v134, s[88:89]
	s_mov_b32 m0, s3
	s_nop 0
	global_load_lds_dwordx4 v130, s[42:43]
	s_add_i32 m0, s3, 0x2000
	s_nop 0
	global_load_lds_dwordx4 v134, s[42:43]
	s_mov_b32 m0, s19
	s_nop 0
	global_load_lds_dwordx4 v128, s[90:91]
	s_mov_b32 m0, s25
	s_nop 0
	global_load_lds_dwordx4 v132, s[90:91]
	s_waitcnt vmcnt(8)
	s_waitcnt lgkmcnt(0)
	s_barrier
	s_setprio 1
	s_waitcnt lgkmcnt(0)
	v_mfma_f32_16x16x32_bf16 v[60:63], v[144:147], v[184:187], v[60:63]
	v_mfma_f32_16x16x32_bf16 v[56:59], v[160:163], v[184:187], v[56:59]
	v_mfma_f32_16x16x32_bf16 v[44:47], v[144:147], v[192:195], v[44:47]
	v_mfma_f32_16x16x32_bf16 v[40:43], v[160:163], v[192:195], v[40:43]
	v_mfma_f32_16x16x32_bf16 v[28:31], v[144:147], v[200:203], v[28:31]
	v_mfma_f32_16x16x32_bf16 v[24:27], v[160:163], v[200:203], v[24:27]
	v_mfma_f32_16x16x32_bf16 v[12:15], v[144:147], v[208:211], v[12:15]
	v_mfma_f32_16x16x32_bf16 v[8:11], v[160:163], v[208:211], v[8:11]
	v_mfma_f32_16x16x32_bf16 v[60:63], v[156:159], v[188:191], v[60:63]
	v_mfma_f32_16x16x32_bf16 v[56:59], v[164:167], v[188:191], v[56:59]
	v_mfma_f32_16x16x32_bf16 v[44:47], v[156:159], v[196:199], v[44:47]
	v_mfma_f32_16x16x32_bf16 v[40:43], v[164:167], v[196:199], v[40:43]
	v_mfma_f32_16x16x32_bf16 v[28:31], v[156:159], v[204:207], v[28:31]
	v_mfma_f32_16x16x32_bf16 v[24:27], v[164:167], v[204:207], v[24:27]
	v_mfma_f32_16x16x32_bf16 v[12:15], v[156:159], v[212:215], v[12:15]
	v_mfma_f32_16x16x32_bf16 v[8:11], v[164:167], v[212:215], v[8:11]
	v_mfma_f32_16x16x32_bf16 v[52:55], v[168:171], v[184:187], v[52:55]
	v_mfma_f32_16x16x32_bf16 v[48:51], v[176:179], v[184:187], v[48:51]
	v_mfma_f32_16x16x32_bf16 v[36:39], v[168:171], v[192:195], v[36:39]
	v_mfma_f32_16x16x32_bf16 v[32:35], v[176:179], v[192:195], v[32:35]
	v_mfma_f32_16x16x32_bf16 v[20:23], v[168:171], v[200:203], v[20:23]
	v_mfma_f32_16x16x32_bf16 v[16:19], v[176:179], v[200:203], v[16:19]
	v_mfma_f32_16x16x32_bf16 v[4:7], v[168:171], v[208:211], v[4:7]
	v_mfma_f32_16x16x32_bf16 v[0:3], v[176:179], v[208:211], v[0:3]
	v_mfma_f32_16x16x32_bf16 v[52:55], v[172:175], v[188:191], v[52:55]
	v_mfma_f32_16x16x32_bf16 v[48:51], v[180:183], v[188:191], v[48:51]
	v_mfma_f32_16x16x32_bf16 v[36:39], v[172:175], v[196:199], v[36:39]
	v_mfma_f32_16x16x32_bf16 v[32:35], v[180:183], v[196:199], v[32:35]
	v_mfma_f32_16x16x32_bf16 v[20:23], v[172:175], v[204:207], v[20:23]
	v_mfma_f32_16x16x32_bf16 v[16:19], v[180:183], v[204:207], v[16:19]
	v_mfma_f32_16x16x32_bf16 v[4:7], v[172:175], v[212:215], v[4:7]
	v_mfma_f32_16x16x32_bf16 v[0:3], v[180:183], v[212:215], v[0:3]
	s_setprio 0
	s_barrier
	s_add_i32 s3, 0, 0x18000
	s_add_i32 s37, 0, 0x1c000
	v_add_u32_e32 v164, s3, v151
	v_add_u32_e32 v180, s37, v151
	ds_read_b128 v[144:147], v164
	ds_read_b128 v[156:159], v164 offset:1024
	ds_read_b128 v[160:163], v164 offset:2048
	ds_read_b128 v[164:167], v164 offset:3072
	ds_read_b128 v[168:171], v180
	ds_read_b128 v[172:175], v180 offset:1024
	ds_read_b128 v[176:179], v180 offset:2048
	ds_read_b128 v[180:183], v180 offset:3072
	s_add_u32 s42, s90, 0x40000
	s_addc_u32 s43, s91, 0
	s_mov_b32 m0, s30
	ds_read_b128 v[184:187], v155 offset:32768
	ds_read_b128 v[188:191], v155 offset:33792
	ds_read_b128 v[192:195], v155 offset:34816
	ds_read_b128 v[196:199], v155 offset:35840
	ds_read_b128 v[200:203], v155 offset:36864
	ds_read_b128 v[204:207], v155 offset:37888
	ds_read_b128 v[208:211], v155 offset:38912
	ds_read_b128 v[212:215], v155 offset:39936
	global_load_lds_dwordx4 v128, s[42:43]
	v_lshl_add_u64 v[222:223], s[42:43], 0, v[132:133]
	s_mov_b32 m0, s31
	s_nop 0
	global_load_lds_dwordx4 v[222:223], off
	s_waitcnt vmcnt(8)
	s_waitcnt lgkmcnt(0)
	s_barrier
	s_setprio 1
	s_waitcnt lgkmcnt(0)
	v_mfma_f32_16x16x32_bf16 v[124:127], v[144:147], v[184:187], v[124:127]
	v_mfma_f32_16x16x32_bf16 v[120:123], v[160:163], v[184:187], v[120:123]
	v_mfma_f32_16x16x32_bf16 v[108:111], v[144:147], v[192:195], v[108:111]
	v_mfma_f32_16x16x32_bf16 v[104:107], v[160:163], v[192:195], v[104:107]
	v_mfma_f32_16x16x32_bf16 v[92:95], v[144:147], v[200:203], v[92:95]
	v_mfma_f32_16x16x32_bf16 v[88:91], v[160:163], v[200:203], v[88:91]
	v_mfma_f32_16x16x32_bf16 v[76:79], v[144:147], v[208:211], v[76:79]
	v_mfma_f32_16x16x32_bf16 v[72:75], v[160:163], v[208:211], v[72:75]
	v_mfma_f32_16x16x32_bf16 v[124:127], v[156:159], v[188:191], v[124:127]
	v_mfma_f32_16x16x32_bf16 v[120:123], v[164:167], v[188:191], v[120:123]
	v_mfma_f32_16x16x32_bf16 v[108:111], v[156:159], v[196:199], v[108:111]
	v_mfma_f32_16x16x32_bf16 v[104:107], v[164:167], v[196:199], v[104:107]
	v_mfma_f32_16x16x32_bf16 v[92:95], v[156:159], v[204:207], v[92:95]
	v_mfma_f32_16x16x32_bf16 v[88:91], v[164:167], v[204:207], v[88:91]
	v_mfma_f32_16x16x32_bf16 v[76:79], v[156:159], v[212:215], v[76:79]
	v_mfma_f32_16x16x32_bf16 v[72:75], v[164:167], v[212:215], v[72:75]
	v_mfma_f32_16x16x32_bf16 v[116:119], v[168:171], v[184:187], v[116:119]
	v_mfma_f32_16x16x32_bf16 v[112:115], v[176:179], v[184:187], v[112:115]
	v_mfma_f32_16x16x32_bf16 v[100:103], v[168:171], v[192:195], v[100:103]
	v_mfma_f32_16x16x32_bf16 v[96:99], v[176:179], v[192:195], v[96:99]
	v_mfma_f32_16x16x32_bf16 v[84:87], v[168:171], v[200:203], v[84:87]
	v_mfma_f32_16x16x32_bf16 v[80:83], v[176:179], v[200:203], v[80:83]
	v_mfma_f32_16x16x32_bf16 v[68:71], v[168:171], v[208:211], v[68:71]
	v_mfma_f32_16x16x32_bf16 v[64:67], v[176:179], v[208:211], v[64:67]
	v_mfma_f32_16x16x32_bf16 v[116:119], v[172:175], v[188:191], v[116:119]
	v_mfma_f32_16x16x32_bf16 v[112:115], v[180:183], v[188:191], v[112:115]
	v_mfma_f32_16x16x32_bf16 v[100:103], v[172:175], v[196:199], v[100:103]
	v_mfma_f32_16x16x32_bf16 v[96:99], v[180:183], v[196:199], v[96:99]
	v_mfma_f32_16x16x32_bf16 v[84:87], v[172:175], v[204:207], v[84:87]
	v_mfma_f32_16x16x32_bf16 v[80:83], v[180:183], v[204:207], v[80:83]
	v_mfma_f32_16x16x32_bf16 v[68:71], v[172:175], v[212:215], v[68:71]
	v_mfma_f32_16x16x32_bf16 v[64:67], v[180:183], v[212:215], v[64:67]
	s_setprio 0
	s_barrier
	s_add_i32 s3, s3, s18
	s_add_u32 s42, s88, 0x80
	s_addc_u32 s43, s89, 0
	s_mov_b32 m0, s3
	ds_read_b128 v[184:187], v155 offset:49152
	ds_read_b128 v[188:191], v155 offset:50176
	ds_read_b128 v[192:195], v155 offset:51200
	ds_read_b128 v[196:199], v155 offset:52224
	ds_read_b128 v[200:203], v155 offset:53248
	ds_read_b128 v[204:207], v155 offset:54272
	ds_read_b128 v[208:211], v155 offset:55296
	ds_read_b128 v[212:215], v155 offset:56320
	global_load_lds_dwordx4 v130, s[42:43]
	s_add_i32 m0, s3, 0x2000
	s_add_i32 s3, s37, s18
	global_load_lds_dwordx4 v134, s[42:43]
	s_add_u32 s42, s42, 0x40000
	s_addc_u32 s43, s43, 0
	s_mov_b32 m0, s3
	s_nop 0
	global_load_lds_dwordx4 v130, s[42:43]
	s_add_i32 m0, s3, 0x2000
	s_nop 0
	global_load_lds_dwordx4 v134, s[42:43]
	s_add_u32 s90, s90, 0x80
	s_addc_u32 s91, s91, 0
	s_mov_b32 m0, s49
	s_nop 0
	global_load_lds_dwordx4 v128, s[90:91]
	s_mov_b32 m0, s56
	s_nop 0
	global_load_lds_dwordx4 v132, s[90:91]
	s_waitcnt vmcnt(8)
	s_waitcnt lgkmcnt(0)
	s_barrier
	s_setprio 1
	s_waitcnt lgkmcnt(0)
	v_mfma_f32_16x16x32_bf16 v[60:63], v[144:147], v[184:187], v[60:63]
	v_mfma_f32_16x16x32_bf16 v[56:59], v[160:163], v[184:187], v[56:59]
	v_mfma_f32_16x16x32_bf16 v[44:47], v[144:147], v[192:195], v[44:47]
	v_mfma_f32_16x16x32_bf16 v[40:43], v[160:163], v[192:195], v[40:43]
	v_mfma_f32_16x16x32_bf16 v[28:31], v[144:147], v[200:203], v[28:31]
	v_mfma_f32_16x16x32_bf16 v[24:27], v[160:163], v[200:203], v[24:27]
	v_mfma_f32_16x16x32_bf16 v[12:15], v[144:147], v[208:211], v[12:15]
	v_mfma_f32_16x16x32_bf16 v[8:11], v[160:163], v[208:211], v[8:11]
	v_mfma_f32_16x16x32_bf16 v[60:63], v[156:159], v[188:191], v[60:63]
	v_mfma_f32_16x16x32_bf16 v[56:59], v[164:167], v[188:191], v[56:59]
	v_mfma_f32_16x16x32_bf16 v[44:47], v[156:159], v[196:199], v[44:47]
	v_mfma_f32_16x16x32_bf16 v[40:43], v[164:167], v[196:199], v[40:43]
	v_mfma_f32_16x16x32_bf16 v[28:31], v[156:159], v[204:207], v[28:31]
	v_mfma_f32_16x16x32_bf16 v[24:27], v[164:167], v[204:207], v[24:27]
	v_mfma_f32_16x16x32_bf16 v[12:15], v[156:159], v[212:215], v[12:15]
	v_mfma_f32_16x16x32_bf16 v[8:11], v[164:167], v[212:215], v[8:11]
	v_mfma_f32_16x16x32_bf16 v[52:55], v[168:171], v[184:187], v[52:55]
	v_mfma_f32_16x16x32_bf16 v[48:51], v[176:179], v[184:187], v[48:51]
	v_mfma_f32_16x16x32_bf16 v[36:39], v[168:171], v[192:195], v[36:39]
	v_mfma_f32_16x16x32_bf16 v[32:35], v[176:179], v[192:195], v[32:35]
	v_mfma_f32_16x16x32_bf16 v[20:23], v[168:171], v[200:203], v[20:23]
	v_mfma_f32_16x16x32_bf16 v[16:19], v[176:179], v[200:203], v[16:19]
	v_mfma_f32_16x16x32_bf16 v[4:7], v[168:171], v[208:211], v[4:7]
	v_mfma_f32_16x16x32_bf16 v[0:3], v[176:179], v[208:211], v[0:3]
	v_mfma_f32_16x16x32_bf16 v[52:55], v[172:175], v[188:191], v[52:55]
	v_mfma_f32_16x16x32_bf16 v[48:51], v[180:183], v[188:191], v[48:51]
	v_mfma_f32_16x16x32_bf16 v[36:39], v[172:175], v[196:199], v[36:39]
	v_mfma_f32_16x16x32_bf16 v[32:35], v[180:183], v[196:199], v[32:35]
	v_mfma_f32_16x16x32_bf16 v[20:23], v[172:175], v[204:207], v[20:23]
	v_mfma_f32_16x16x32_bf16 v[16:19], v[180:183], v[204:207], v[16:19]
	v_mfma_f32_16x16x32_bf16 v[4:7], v[172:175], v[212:215], v[4:7]
	v_mfma_f32_16x16x32_bf16 v[0:3], v[180:183], v[212:215], v[0:3]
	s_setprio 0
	s_add_i32 s36, s36, 2
	s_add_u32 s86, s86, 0x100
	s_addc_u32 s87, s87, 0
	s_add_u32 s33, s33, 0x100
	s_addc_u32 s35, s35, 0
	s_cmp_gt_u32 s36, 13
	s_barrier
	s_cbranch_scc0 .LBB0_539
	s_and_b64 vcc, exec, s[12:13]
	s_cbranch_vccz .LBB0_542
	s_barrier

.LBB0_563:
	ds_read_b128 v[144:147], v157
	ds_read_b128 v[148:151], v157 offset:1024
	ds_read_b128 v[160:163], v157 offset:2048
	ds_read_b128 v[164:167], v157 offset:3072
	ds_read_b128 v[168:171], v158
	ds_read_b128 v[172:175], v158 offset:1024
	ds_read_b128 v[176:179], v158 offset:2048
	ds_read_b128 v[180:183], v158 offset:3072
	s_add_u32 s3, s34, 0xfffe0080
	s_addc_u32 s42, s35, -1
	s_cmp_eq_u32 s37, 4
	s_cselect_b32 s91, s0, s42
	s_cselect_b32 s90, s1, s3
	s_cselect_b32 s89, s24, s36
	s_cselect_b32 s88, s27, s33
	s_add_i32 m0, s19, 0xc000
	ds_read_b128 v[184:187], v159
	ds_read_b128 v[188:191], v159 offset:1024
	ds_read_b128 v[192:195], v159 offset:2048
	ds_read_b128 v[196:199], v159 offset:3072
	ds_read_b128 v[200:203], v159 offset:4096
	ds_read_b128 v[204:207], v159 offset:5120
	ds_read_b128 v[208:211], v159 offset:6144
	ds_read_b128 v[212:215], v159 offset:7168
	global_load_lds_dwordx4 v136, s[34:35]
	s_add_i32 m0, s19, 0xe000
	s_nop 0
	global_load_lds_dwordx4 v138, s[34:35]
	s_waitcnt vmcnt(8)
	s_waitcnt lgkmcnt(0)
	s_barrier
	s_setprio 1
	s_waitcnt lgkmcnt(0)
	v_mfma_f32_16x16x32_bf16 v[124:127], v[144:147], v[184:187], v[124:127]
	v_mfma_f32_16x16x32_bf16 v[120:123], v[160:163], v[184:187], v[120:123]
	v_mfma_f32_16x16x32_bf16 v[108:111], v[144:147], v[192:195], v[108:111]
	v_mfma_f32_16x16x32_bf16 v[104:107], v[160:163], v[192:195], v[104:107]
	v_mfma_f32_16x16x32_bf16 v[92:95], v[144:147], v[200:203], v[92:95]
	v_mfma_f32_16x16x32_bf16 v[88:91], v[160:163], v[200:203], v[88:91]
	v_mfma_f32_16x16x32_bf16 v[76:79], v[144:147], v[208:211], v[76:79]
	v_mfma_f32_16x16x32_bf16 v[72:75], v[160:163], v[208:211], v[72:75]
	v_mfma_f32_16x16x32_bf16 v[124:127], v[148:151], v[188:191], v[124:127]
	v_mfma_f32_16x16x32_bf16 v[120:123], v[164:167], v[188:191], v[120:123]
	v_mfma_f32_16x16x32_bf16 v[108:111], v[148:151], v[196:199], v[108:111]
	v_mfma_f32_16x16x32_bf16 v[104:107], v[164:167], v[196:199], v[104:107]
	v_mfma_f32_16x16x32_bf16 v[92:95], v[148:151], v[204:207], v[92:95]
	v_mfma_f32_16x16x32_bf16 v[88:91], v[164:167], v[204:207], v[88:91]
	v_mfma_f32_16x16x32_bf16 v[76:79], v[148:151], v[212:215], v[76:79]
	v_mfma_f32_16x16x32_bf16 v[72:75], v[164:167], v[212:215], v[72:75]
	v_mfma_f32_16x16x32_bf16 v[116:119], v[168:171], v[184:187], v[116:119]
	v_mfma_f32_16x16x32_bf16 v[112:115], v[176:179], v[184:187], v[112:115]
	v_mfma_f32_16x16x32_bf16 v[100:103], v[168:171], v[192:195], v[100:103]
	v_mfma_f32_16x16x32_bf16 v[96:99], v[176:179], v[192:195], v[96:99]
	v_mfma_f32_16x16x32_bf16 v[84:87], v[168:171], v[200:203], v[84:87]
	v_mfma_f32_16x16x32_bf16 v[80:83], v[176:179], v[200:203], v[80:83]
	v_mfma_f32_16x16x32_bf16 v[68:71], v[168:171], v[208:211], v[68:71]
	v_mfma_f32_16x16x32_bf16 v[64:67], v[176:179], v[208:211], v[64:67]
	v_mfma_f32_16x16x32_bf16 v[116:119], v[172:175], v[188:191], v[116:119]
	v_mfma_f32_16x16x32_bf16 v[112:115], v[180:183], v[188:191], v[112:115]
	v_mfma_f32_16x16x32_bf16 v[100:103], v[172:175], v[196:199], v[100:103]
	v_mfma_f32_16x16x32_bf16 v[96:99], v[180:183], v[196:199], v[96:99]
	v_mfma_f32_16x16x32_bf16 v[84:87], v[172:175], v[204:207], v[84:87]
	v_mfma_f32_16x16x32_bf16 v[80:83], v[180:183], v[204:207], v[80:83]
	v_mfma_f32_16x16x32_bf16 v[68:71], v[172:175], v[212:215], v[68:71]
	v_mfma_f32_16x16x32_bf16 v[64:67], v[180:183], v[212:215], v[64:67]
	s_setprio 0
	s_barrier
	s_add_i32 s3, s78, s18
	s_mov_b32 m0, s3
	ds_read_b128 v[184:187], v159 offset:16384
	ds_read_b128 v[188:191], v159 offset:17408
	ds_read_b128 v[192:195], v159 offset:18432
	ds_read_b128 v[196:199], v159 offset:19456
	ds_read_b128 v[200:203], v159 offset:20480
	ds_read_b128 v[204:207], v159 offset:21504
	ds_read_b128 v[208:211], v159 offset:22528
	ds_read_b128 v[212:215], v159 offset:23552
	global_load_lds_dwordx4 v130, s[88:89]
	s_add_i32 m0, s3, 0x2000
	s_add_u32 s42, s88, 0x20000
	s_addc_u32 s43, s89, 0
	s_add_i32 s3, s79, s18
	global_load_lds_dwordx4 v134, s[88:89]
	s_mov_b32 m0, s3
	s_nop 0
	global_load_lds_dwordx4 v130, s[42:43]
	s_add_i32 m0, s3, 0x2000
	s_nop 0
	global_load_lds_dwordx4 v134, s[42:43]
	s_mov_b32 m0, s19
	s_nop 0
	global_load_lds_dwordx4 v128, s[90:91]
	s_mov_b32 m0, s25
	s_nop 0
	global_load_lds_dwordx4 v132, s[90:91]
	s_waitcnt vmcnt(8)
	s_waitcnt lgkmcnt(0)
	s_barrier
	s_setprio 1
	s_waitcnt lgkmcnt(0)
	v_mfma_f32_16x16x32_bf16 v[60:63], v[144:147], v[184:187], v[60:63]
	v_mfma_f32_16x16x32_bf16 v[56:59], v[160:163], v[184:187], v[56:59]
	v_mfma_f32_16x16x32_bf16 v[44:47], v[144:147], v[192:195], v[44:47]
	v_mfma_f32_16x16x32_bf16 v[40:43], v[160:163], v[192:195], v[40:43]
	v_mfma_f32_16x16x32_bf16 v[28:31], v[144:147], v[200:203], v[28:31]
	v_mfma_f32_16x16x32_bf16 v[24:27], v[160:163], v[200:203], v[24:27]
	v_mfma_f32_16x16x32_bf16 v[12:15], v[144:147], v[208:211], v[12:15]
	v_mfma_f32_16x16x32_bf16 v[8:11], v[160:163], v[208:211], v[8:11]
	v_mfma_f32_16x16x32_bf16 v[60:63], v[148:151], v[188:191], v[60:63]
	v_mfma_f32_16x16x32_bf16 v[56:59], v[164:167], v[188:191], v[56:59]
	v_mfma_f32_16x16x32_bf16 v[44:47], v[148:151], v[196:199], v[44:47]
	v_mfma_f32_16x16x32_bf16 v[40:43], v[164:167], v[196:199], v[40:43]
	v_mfma_f32_16x16x32_bf16 v[28:31], v[148:151], v[204:207], v[28:31]
	v_mfma_f32_16x16x32_bf16 v[24:27], v[164:167], v[204:207], v[24:27]
	v_mfma_f32_16x16x32_bf16 v[12:15], v[148:151], v[212:215], v[12:15]
	v_mfma_f32_16x16x32_bf16 v[8:11], v[164:167], v[212:215], v[8:11]
	v_mfma_f32_16x16x32_bf16 v[52:55], v[168:171], v[184:187], v[52:55]
	v_mfma_f32_16x16x32_bf16 v[48:51], v[176:179], v[184:187], v[48:51]
	v_mfma_f32_16x16x32_bf16 v[36:39], v[168:171], v[192:195], v[36:39]
	v_mfma_f32_16x16x32_bf16 v[32:35], v[176:179], v[192:195], v[32:35]
	v_mfma_f32_16x16x32_bf16 v[20:23], v[168:171], v[200:203], v[20:23]
	v_mfma_f32_16x16x32_bf16 v[16:19], v[176:179], v[200:203], v[16:19]
	v_mfma_f32_16x16x32_bf16 v[4:7], v[168:171], v[208:211], v[4:7]
	v_mfma_f32_16x16x32_bf16 v[0:3], v[176:179], v[208:211], v[0:3]
	v_mfma_f32_16x16x32_bf16 v[52:55], v[172:175], v[188:191], v[52:55]
	v_mfma_f32_16x16x32_bf16 v[48:51], v[180:183], v[188:191], v[48:51]
	v_mfma_f32_16x16x32_bf16 v[36:39], v[172:175], v[196:199], v[36:39]
	v_mfma_f32_16x16x32_bf16 v[32:35], v[180:183], v[196:199], v[32:35]
	v_mfma_f32_16x16x32_bf16 v[20:23], v[172:175], v[204:207], v[20:23]
	v_mfma_f32_16x16x32_bf16 v[16:19], v[180:183], v[204:207], v[16:19]
	v_mfma_f32_16x16x32_bf16 v[4:7], v[172:175], v[212:215], v[4:7]
	v_mfma_f32_16x16x32_bf16 v[0:3], v[180:183], v[212:215], v[0:3]
	s_setprio 0
	s_barrier
	s_add_i32 s3, 0, 0x18000
	s_add_i32 s44, 0, 0x1c000
	v_add_u32_e32 v164, s3, v155
	v_add_u32_e32 v180, s44, v155
	ds_read_b128 v[144:147], v164
	ds_read_b128 v[148:151], v164 offset:1024
	ds_read_b128 v[160:163], v164 offset:2048
	ds_read_b128 v[164:167], v164 offset:3072
	ds_read_b128 v[168:171], v180
	ds_read_b128 v[172:175], v180 offset:1024
	ds_read_b128 v[176:179], v180 offset:2048
	ds_read_b128 v[180:183], v180 offset:3072
	s_add_u32 s42, s90, 0x20000
	s_addc_u32 s43, s91, 0
	s_mov_b32 m0, s30
	ds_read_b128 v[184:187], v159 offset:32768
	ds_read_b128 v[188:191], v159 offset:33792
	ds_read_b128 v[192:195], v159 offset:34816
	ds_read_b128 v[196:199], v159 offset:35840
	ds_read_b128 v[200:203], v159 offset:36864
	ds_read_b128 v[204:207], v159 offset:37888
	ds_read_b128 v[208:211], v159 offset:38912
	ds_read_b128 v[212:215], v159 offset:39936
	global_load_lds_dwordx4 v128, s[42:43]
	v_lshl_add_u64 v[222:223], s[42:43], 0, v[132:133]
	s_mov_b32 m0, s31
	s_nop 0
	global_load_lds_dwordx4 v[222:223], off
	s_waitcnt vmcnt(8)
	s_waitcnt lgkmcnt(0)
	s_barrier
	s_setprio 1
	s_waitcnt lgkmcnt(0)
	v_mfma_f32_16x16x32_bf16 v[124:127], v[144:147], v[184:187], v[124:127]
	v_mfma_f32_16x16x32_bf16 v[120:123], v[160:163], v[184:187], v[120:123]
	v_mfma_f32_16x16x32_bf16 v[108:111], v[144:147], v[192:195], v[108:111]
	v_mfma_f32_16x16x32_bf16 v[104:107], v[160:163], v[192:195], v[104:107]
	v_mfma_f32_16x16x32_bf16 v[92:95], v[144:147], v[200:203], v[92:95]
	v_mfma_f32_16x16x32_bf16 v[88:91], v[160:163], v[200:203], v[88:91]
	v_mfma_f32_16x16x32_bf16 v[76:79], v[144:147], v[208:211], v[76:79]
	v_mfma_f32_16x16x32_bf16 v[72:75], v[160:163], v[208:211], v[72:75]
	v_mfma_f32_16x16x32_bf16 v[124:127], v[148:151], v[188:191], v[124:127]
	v_mfma_f32_16x16x32_bf16 v[120:123], v[164:167], v[188:191], v[120:123]
	v_mfma_f32_16x16x32_bf16 v[108:111], v[148:151], v[196:199], v[108:111]
	v_mfma_f32_16x16x32_bf16 v[104:107], v[164:167], v[196:199], v[104:107]
	v_mfma_f32_16x16x32_bf16 v[92:95], v[148:151], v[204:207], v[92:95]
	v_mfma_f32_16x16x32_bf16 v[88:91], v[164:167], v[204:207], v[88:91]
	v_mfma_f32_16x16x32_bf16 v[76:79], v[148:151], v[212:215], v[76:79]
	v_mfma_f32_16x16x32_bf16 v[72:75], v[164:167], v[212:215], v[72:75]
	v_mfma_f32_16x16x32_bf16 v[116:119], v[168:171], v[184:187], v[116:119]
	v_mfma_f32_16x16x32_bf16 v[112:115], v[176:179], v[184:187], v[112:115]
	v_mfma_f32_16x16x32_bf16 v[100:103], v[168:171], v[192:195], v[100:103]
	v_mfma_f32_16x16x32_bf16 v[96:99], v[176:179], v[192:195], v[96:99]
	v_mfma_f32_16x16x32_bf16 v[84:87], v[168:171], v[200:203], v[84:87]
	v_mfma_f32_16x16x32_bf16 v[80:83], v[176:179], v[200:203], v[80:83]
	v_mfma_f32_16x16x32_bf16 v[68:71], v[168:171], v[208:211], v[68:71]
	v_mfma_f32_16x16x32_bf16 v[64:67], v[176:179], v[208:211], v[64:67]
	v_mfma_f32_16x16x32_bf16 v[116:119], v[172:175], v[188:191], v[116:119]
	v_mfma_f32_16x16x32_bf16 v[112:115], v[180:183], v[188:191], v[112:115]
	v_mfma_f32_16x16x32_bf16 v[100:103], v[172:175], v[196:199], v[100:103]
	v_mfma_f32_16x16x32_bf16 v[96:99], v[180:183], v[196:199], v[96:99]
	v_mfma_f32_16x16x32_bf16 v[84:87], v[172:175], v[204:207], v[84:87]
	v_mfma_f32_16x16x32_bf16 v[80:83], v[180:183], v[204:207], v[80:83]
	v_mfma_f32_16x16x32_bf16 v[68:71], v[172:175], v[212:215], v[68:71]
	v_mfma_f32_16x16x32_bf16 v[64:67], v[180:183], v[212:215], v[64:67]
	s_setprio 0
	s_barrier
	s_add_i32 s3, s3, s18
	s_add_u32 s42, s88, 0x80
	s_addc_u32 s43, s89, 0
	s_mov_b32 m0, s3
	ds_read_b128 v[184:187], v159 offset:49152
	ds_read_b128 v[188:191], v159 offset:50176
	ds_read_b128 v[192:195], v159 offset:51200
	ds_read_b128 v[196:199], v159 offset:52224
	ds_read_b128 v[200:203], v159 offset:53248
	ds_read_b128 v[204:207], v159 offset:54272
	ds_read_b128 v[208:211], v159 offset:55296
	ds_read_b128 v[212:215], v159 offset:56320
	global_load_lds_dwordx4 v130, s[42:43]
	s_add_i32 m0, s3, 0x2000
	s_add_i32 s3, s44, s18
	global_load_lds_dwordx4 v134, s[42:43]
	s_add_u32 s42, s42, 0x20000
	s_addc_u32 s43, s43, 0
	s_mov_b32 m0, s3
	s_nop 0
	global_load_lds_dwordx4 v130, s[42:43]
	s_add_i32 m0, s3, 0x2000
	s_nop 0
	global_load_lds_dwordx4 v134, s[42:43]
	s_add_u32 s90, s90, 0x80
	s_addc_u32 s91, s91, 0
	s_mov_b32 m0, s58
	s_nop 0
	global_load_lds_dwordx4 v128, s[90:91]
	s_mov_b32 m0, s59
	s_nop 0
	global_load_lds_dwordx4 v132, s[90:91]
	s_waitcnt vmcnt(8)
	s_waitcnt lgkmcnt(0)
	s_barrier
	s_setprio 1
	s_waitcnt lgkmcnt(0)
	v_mfma_f32_16x16x32_bf16 v[60:63], v[144:147], v[184:187], v[60:63]
	v_mfma_f32_16x16x32_bf16 v[56:59], v[160:163], v[184:187], v[56:59]
	v_mfma_f32_16x16x32_bf16 v[44:47], v[144:147], v[192:195], v[44:47]
	v_mfma_f32_16x16x32_bf16 v[40:43], v[160:163], v[192:195], v[40:43]
	v_mfma_f32_16x16x32_bf16 v[28:31], v[144:147], v[200:203], v[28:31]
	v_mfma_f32_16x16x32_bf16 v[24:27], v[160:163], v[200:203], v[24:27]
	v_mfma_f32_16x16x32_bf16 v[12:15], v[144:147], v[208:211], v[12:15]
	v_mfma_f32_16x16x32_bf16 v[8:11], v[160:163], v[208:211], v[8:11]
	v_mfma_f32_16x16x32_bf16 v[60:63], v[148:151], v[188:191], v[60:63]
	v_mfma_f32_16x16x32_bf16 v[56:59], v[164:167], v[188:191], v[56:59]
	v_mfma_f32_16x16x32_bf16 v[44:47], v[148:151], v[196:199], v[44:47]
	v_mfma_f32_16x16x32_bf16 v[40:43], v[164:167], v[196:199], v[40:43]
	v_mfma_f32_16x16x32_bf16 v[28:31], v[148:151], v[204:207], v[28:31]
	v_mfma_f32_16x16x32_bf16 v[24:27], v[164:167], v[204:207], v[24:27]
	v_mfma_f32_16x16x32_bf16 v[12:15], v[148:151], v[212:215], v[12:15]
	v_mfma_f32_16x16x32_bf16 v[8:11], v[164:167], v[212:215], v[8:11]
	v_mfma_f32_16x16x32_bf16 v[52:55], v[168:171], v[184:187], v[52:55]
	v_mfma_f32_16x16x32_bf16 v[48:51], v[176:179], v[184:187], v[48:51]
	v_mfma_f32_16x16x32_bf16 v[36:39], v[168:171], v[192:195], v[36:39]
	v_mfma_f32_16x16x32_bf16 v[32:35], v[176:179], v[192:195], v[32:35]
	v_mfma_f32_16x16x32_bf16 v[20:23], v[168:171], v[200:203], v[20:23]
	v_mfma_f32_16x16x32_bf16 v[16:19], v[176:179], v[200:203], v[16:19]
	v_mfma_f32_16x16x32_bf16 v[4:7], v[168:171], v[208:211], v[4:7]
	v_mfma_f32_16x16x32_bf16 v[0:3], v[176:179], v[208:211], v[0:3]
	v_mfma_f32_16x16x32_bf16 v[52:55], v[172:175], v[188:191], v[52:55]
	v_mfma_f32_16x16x32_bf16 v[48:51], v[180:183], v[188:191], v[48:51]
	v_mfma_f32_16x16x32_bf16 v[36:39], v[172:175], v[196:199], v[36:39]
	v_mfma_f32_16x16x32_bf16 v[32:35], v[180:183], v[196:199], v[32:35]
	v_mfma_f32_16x16x32_bf16 v[20:23], v[172:175], v[204:207], v[20:23]
	v_mfma_f32_16x16x32_bf16 v[16:19], v[180:183], v[204:207], v[16:19]
	v_mfma_f32_16x16x32_bf16 v[4:7], v[172:175], v[212:215], v[4:7]
	v_mfma_f32_16x16x32_bf16 v[0:3], v[180:183], v[212:215], v[0:3]
	s_setprio 0
	s_add_i32 s37, s37, 2
	s_add_u32 s34, s34, 0x100
	s_addc_u32 s35, s35, 0
	s_add_u32 s33, s33, 0x100
	s_addc_u32 s36, s36, 0
	s_cmp_gt_u32 s37, 5
	s_barrier
	s_cbranch_scc0 .LBB0_563
	s_and_b64 vcc, exec, s[14:15]
	s_cbranch_vccz .LBB0_566
	s_barrier

.LBB0_639:
	ds_read_b128 v[140:143], v149
	ds_read_b128 v[152:155], v149 offset:1024
	ds_read_b128 v[156:159], v149 offset:2048
	ds_read_b128 v[160:163], v149 offset:3072
	ds_read_b128 v[164:167], v150
	ds_read_b128 v[168:171], v150 offset:1024
	ds_read_b128 v[172:175], v150 offset:2048
	ds_read_b128 v[176:179], v150 offset:3072
	s_add_u32 s3, s86, 0xfff80080
	s_addc_u32 s33, s87, -1
	s_cmp_eq_u32 s27, 28
	s_cselect_b32 s91, s0, s33
	s_cselect_b32 s90, s1, s3
	s_cselect_b32 s89, s15, s24
	s_cselect_b32 s88, s17, s19
	s_add_i32 m0, s30, 0xc000
	ds_read_b128 v[180:183], v151
	ds_read_b128 v[184:187], v151 offset:1024
	ds_read_b128 v[188:191], v151 offset:2048
	ds_read_b128 v[192:195], v151 offset:3072
	ds_read_b128 v[196:199], v151 offset:4096
	ds_read_b128 v[200:203], v151 offset:5120
	ds_read_b128 v[204:207], v151 offset:6144
	ds_read_b128 v[208:211], v151 offset:7168
	global_load_lds_dwordx4 v132, s[86:87]
	s_add_i32 m0, s30, 0xe000
	s_nop 0
	global_load_lds_dwordx4 v134, s[86:87]
	s_waitcnt vmcnt(8)
	s_waitcnt lgkmcnt(0)
	s_barrier
	s_setprio 1
	s_waitcnt lgkmcnt(0)
	v_mfma_f32_16x16x32_bf16 v[124:127], v[140:143], v[180:183], v[124:127]
	v_mfma_f32_16x16x32_bf16 v[120:123], v[156:159], v[180:183], v[120:123]
	v_mfma_f32_16x16x32_bf16 v[108:111], v[140:143], v[188:191], v[108:111]
	v_mfma_f32_16x16x32_bf16 v[104:107], v[156:159], v[188:191], v[104:107]
	v_mfma_f32_16x16x32_bf16 v[92:95], v[140:143], v[196:199], v[92:95]
	v_mfma_f32_16x16x32_bf16 v[88:91], v[156:159], v[196:199], v[88:91]
	v_mfma_f32_16x16x32_bf16 v[76:79], v[140:143], v[204:207], v[76:79]
	v_mfma_f32_16x16x32_bf16 v[72:75], v[156:159], v[204:207], v[72:75]
	v_mfma_f32_16x16x32_bf16 v[124:127], v[152:155], v[184:187], v[124:127]
	v_mfma_f32_16x16x32_bf16 v[120:123], v[160:163], v[184:187], v[120:123]
	v_mfma_f32_16x16x32_bf16 v[108:111], v[152:155], v[192:195], v[108:111]
	v_mfma_f32_16x16x32_bf16 v[104:107], v[160:163], v[192:195], v[104:107]
	v_mfma_f32_16x16x32_bf16 v[92:95], v[152:155], v[200:203], v[92:95]
	v_mfma_f32_16x16x32_bf16 v[88:91], v[160:163], v[200:203], v[88:91]
	v_mfma_f32_16x16x32_bf16 v[76:79], v[152:155], v[208:211], v[76:79]
	v_mfma_f32_16x16x32_bf16 v[72:75], v[160:163], v[208:211], v[72:75]
	v_mfma_f32_16x16x32_bf16 v[116:119], v[164:167], v[180:183], v[116:119]
	v_mfma_f32_16x16x32_bf16 v[112:115], v[172:175], v[180:183], v[112:115]
	v_mfma_f32_16x16x32_bf16 v[100:103], v[164:167], v[188:191], v[100:103]
	v_mfma_f32_16x16x32_bf16 v[96:99], v[172:175], v[188:191], v[96:99]
	v_mfma_f32_16x16x32_bf16 v[84:87], v[164:167], v[196:199], v[84:87]
	v_mfma_f32_16x16x32_bf16 v[80:83], v[172:175], v[196:199], v[80:83]
	v_mfma_f32_16x16x32_bf16 v[68:71], v[164:167], v[204:207], v[68:71]
	v_mfma_f32_16x16x32_bf16 v[64:67], v[172:175], v[204:207], v[64:67]
	v_mfma_f32_16x16x32_bf16 v[116:119], v[168:171], v[184:187], v[116:119]
	v_mfma_f32_16x16x32_bf16 v[112:115], v[176:179], v[184:187], v[112:115]
	v_mfma_f32_16x16x32_bf16 v[100:103], v[168:171], v[192:195], v[100:103]
	v_mfma_f32_16x16x32_bf16 v[96:99], v[176:179], v[192:195], v[96:99]
	v_mfma_f32_16x16x32_bf16 v[84:87], v[168:171], v[200:203], v[84:87]
	v_mfma_f32_16x16x32_bf16 v[80:83], v[176:179], v[200:203], v[80:83]
	v_mfma_f32_16x16x32_bf16 v[68:71], v[168:171], v[208:211], v[68:71]
	v_mfma_f32_16x16x32_bf16 v[64:67], v[176:179], v[208:211], v[64:67]
	s_setprio 0
	s_barrier
	s_add_i32 s3, s59, s25
	s_mov_b32 m0, s3
	ds_read_b128 v[180:183], v151 offset:16384
	ds_read_b128 v[184:187], v151 offset:17408
	ds_read_b128 v[188:191], v151 offset:18432
	ds_read_b128 v[192:195], v151 offset:19456
	ds_read_b128 v[196:199], v151 offset:20480
	ds_read_b128 v[200:203], v151 offset:21504
	ds_read_b128 v[204:207], v151 offset:22528
	ds_read_b128 v[208:211], v151 offset:23552
	global_load_lds_dwordx4 v128, s[88:89]
	s_add_i32 m0, s3, 0x2000
	s_add_u32 s36, s88, 0x80000
	s_addc_u32 s37, s89, 0
	s_add_i32 s3, s68, s25
	global_load_lds_dwordx4 v130, s[88:89]
	s_mov_b32 m0, s3
	s_nop 0
	global_load_lds_dwordx4 v128, s[36:37]
	s_add_i32 m0, s3, 0x2000
	s_nop 0
	global_load_lds_dwordx4 v130, s[36:37]
	s_mov_b32 m0, s30
	s_nop 0
	global_load_lds_dwordx4 v128, s[90:91]
	s_mov_b32 m0, s31
	s_nop 0
	global_load_lds_dwordx4 v130, s[90:91]
	s_waitcnt vmcnt(8)
	s_waitcnt lgkmcnt(0)
	s_barrier
	s_setprio 1
	s_waitcnt lgkmcnt(0)
	v_mfma_f32_16x16x32_bf16 v[60:63], v[140:143], v[180:183], v[60:63]
	v_mfma_f32_16x16x32_bf16 v[56:59], v[156:159], v[180:183], v[56:59]
	v_mfma_f32_16x16x32_bf16 v[44:47], v[140:143], v[188:191], v[44:47]
	v_mfma_f32_16x16x32_bf16 v[40:43], v[156:159], v[188:191], v[40:43]
	v_mfma_f32_16x16x32_bf16 v[28:31], v[140:143], v[196:199], v[28:31]
	v_mfma_f32_16x16x32_bf16 v[24:27], v[156:159], v[196:199], v[24:27]
	v_mfma_f32_16x16x32_bf16 v[12:15], v[140:143], v[204:207], v[12:15]
	v_mfma_f32_16x16x32_bf16 v[8:11], v[156:159], v[204:207], v[8:11]
	v_mfma_f32_16x16x32_bf16 v[60:63], v[152:155], v[184:187], v[60:63]
	v_mfma_f32_16x16x32_bf16 v[56:59], v[160:163], v[184:187], v[56:59]
	v_mfma_f32_16x16x32_bf16 v[44:47], v[152:155], v[192:195], v[44:47]
	v_mfma_f32_16x16x32_bf16 v[40:43], v[160:163], v[192:195], v[40:43]
	v_mfma_f32_16x16x32_bf16 v[28:31], v[152:155], v[200:203], v[28:31]
	v_mfma_f32_16x16x32_bf16 v[24:27], v[160:163], v[200:203], v[24:27]
	v_mfma_f32_16x16x32_bf16 v[12:15], v[152:155], v[208:211], v[12:15]
	v_mfma_f32_16x16x32_bf16 v[8:11], v[160:163], v[208:211], v[8:11]
	v_mfma_f32_16x16x32_bf16 v[52:55], v[164:167], v[180:183], v[52:55]
	v_mfma_f32_16x16x32_bf16 v[48:51], v[172:175], v[180:183], v[48:51]
	v_mfma_f32_16x16x32_bf16 v[36:39], v[164:167], v[188:191], v[36:39]
	v_mfma_f32_16x16x32_bf16 v[32:35], v[172:175], v[188:191], v[32:35]
	v_mfma_f32_16x16x32_bf16 v[20:23], v[164:167], v[196:199], v[20:23]
	v_mfma_f32_16x16x32_bf16 v[16:19], v[172:175], v[196:199], v[16:19]
	v_mfma_f32_16x16x32_bf16 v[4:7], v[164:167], v[204:207], v[4:7]
	v_mfma_f32_16x16x32_bf16 v[0:3], v[172:175], v[204:207], v[0:3]
	v_mfma_f32_16x16x32_bf16 v[52:55], v[168:171], v[184:187], v[52:55]
	v_mfma_f32_16x16x32_bf16 v[48:51], v[176:179], v[184:187], v[48:51]
	v_mfma_f32_16x16x32_bf16 v[36:39], v[168:171], v[192:195], v[36:39]
	v_mfma_f32_16x16x32_bf16 v[32:35], v[176:179], v[192:195], v[32:35]
	v_mfma_f32_16x16x32_bf16 v[20:23], v[168:171], v[200:203], v[20:23]
	v_mfma_f32_16x16x32_bf16 v[16:19], v[176:179], v[200:203], v[16:19]
	v_mfma_f32_16x16x32_bf16 v[4:7], v[168:171], v[208:211], v[4:7]
	v_mfma_f32_16x16x32_bf16 v[0:3], v[176:179], v[208:211], v[0:3]
	s_setprio 0
	s_barrier
	s_add_i32 s3, 0, 0x18000
	s_add_i32 s33, 0, 0x1c000
	v_add_u32_e32 v160, s3, v147
	v_add_u32_e32 v176, s33, v147
	ds_read_b128 v[140:143], v160
	ds_read_b128 v[152:155], v160 offset:1024
	ds_read_b128 v[156:159], v160 offset:2048
	ds_read_b128 v[160:163], v160 offset:3072
	ds_read_b128 v[164:167], v176
	ds_read_b128 v[168:171], v176 offset:1024
	ds_read_b128 v[172:175], v176 offset:2048
	ds_read_b128 v[176:179], v176 offset:3072
	s_add_u32 s36, s90, 0x80000
	s_addc_u32 s37, s91, 0
	s_mov_b32 m0, s48
	ds_read_b128 v[180:183], v151 offset:32768
	ds_read_b128 v[184:187], v151 offset:33792
	ds_read_b128 v[188:191], v151 offset:34816
	ds_read_b128 v[192:195], v151 offset:35840
	ds_read_b128 v[196:199], v151 offset:36864
	ds_read_b128 v[200:203], v151 offset:37888
	ds_read_b128 v[204:207], v151 offset:38912
	ds_read_b128 v[208:211], v151 offset:39936
	global_load_lds_dwordx4 v128, s[36:37]
	v_lshl_add_u64 v[218:219], s[36:37], 0, v[130:131]
	s_mov_b32 m0, s49
	s_nop 0
	global_load_lds_dwordx4 v[218:219], off
	s_waitcnt vmcnt(8)
	s_waitcnt lgkmcnt(0)
	s_barrier
	s_setprio 1
	s_waitcnt lgkmcnt(0)
	v_mfma_f32_16x16x32_bf16 v[124:127], v[140:143], v[180:183], v[124:127]
	v_mfma_f32_16x16x32_bf16 v[120:123], v[156:159], v[180:183], v[120:123]
	v_mfma_f32_16x16x32_bf16 v[108:111], v[140:143], v[188:191], v[108:111]
	v_mfma_f32_16x16x32_bf16 v[104:107], v[156:159], v[188:191], v[104:107]
	v_mfma_f32_16x16x32_bf16 v[92:95], v[140:143], v[196:199], v[92:95]
	v_mfma_f32_16x16x32_bf16 v[88:91], v[156:159], v[196:199], v[88:91]
	v_mfma_f32_16x16x32_bf16 v[76:79], v[140:143], v[204:207], v[76:79]
	v_mfma_f32_16x16x32_bf16 v[72:75], v[156:159], v[204:207], v[72:75]
	v_mfma_f32_16x16x32_bf16 v[124:127], v[152:155], v[184:187], v[124:127]
	v_mfma_f32_16x16x32_bf16 v[120:123], v[160:163], v[184:187], v[120:123]
	v_mfma_f32_16x16x32_bf16 v[108:111], v[152:155], v[192:195], v[108:111]
	v_mfma_f32_16x16x32_bf16 v[104:107], v[160:163], v[192:195], v[104:107]
	v_mfma_f32_16x16x32_bf16 v[92:95], v[152:155], v[200:203], v[92:95]
	v_mfma_f32_16x16x32_bf16 v[88:91], v[160:163], v[200:203], v[88:91]
	v_mfma_f32_16x16x32_bf16 v[76:79], v[152:155], v[208:211], v[76:79]
	v_mfma_f32_16x16x32_bf16 v[72:75], v[160:163], v[208:211], v[72:75]
	v_mfma_f32_16x16x32_bf16 v[116:119], v[164:167], v[180:183], v[116:119]
	v_mfma_f32_16x16x32_bf16 v[112:115], v[172:175], v[180:183], v[112:115]
	v_mfma_f32_16x16x32_bf16 v[100:103], v[164:167], v[188:191], v[100:103]
	v_mfma_f32_16x16x32_bf16 v[96:99], v[172:175], v[188:191], v[96:99]
	v_mfma_f32_16x16x32_bf16 v[84:87], v[164:167], v[196:199], v[84:87]
	v_mfma_f32_16x16x32_bf16 v[80:83], v[172:175], v[196:199], v[80:83]
	v_mfma_f32_16x16x32_bf16 v[68:71], v[164:167], v[204:207], v[68:71]
	v_mfma_f32_16x16x32_bf16 v[64:67], v[172:175], v[204:207], v[64:67]
	v_mfma_f32_16x16x32_bf16 v[116:119], v[168:171], v[184:187], v[116:119]
	v_mfma_f32_16x16x32_bf16 v[112:115], v[176:179], v[184:187], v[112:115]
	v_mfma_f32_16x16x32_bf16 v[100:103], v[168:171], v[192:195], v[100:103]
	v_mfma_f32_16x16x32_bf16 v[96:99], v[176:179], v[192:195], v[96:99]
	v_mfma_f32_16x16x32_bf16 v[84:87], v[168:171], v[200:203], v[84:87]
	v_mfma_f32_16x16x32_bf16 v[80:83], v[176:179], v[200:203], v[80:83]
	v_mfma_f32_16x16x32_bf16 v[68:71], v[168:171], v[208:211], v[68:71]
	v_mfma_f32_16x16x32_bf16 v[64:67], v[176:179], v[208:211], v[64:67]
	s_setprio 0
	s_barrier
	s_add_i32 s3, s3, s25
	s_add_u32 s36, s88, 0x80
	s_addc_u32 s37, s89, 0
	s_mov_b32 m0, s3
	ds_read_b128 v[180:183], v151 offset:49152
	ds_read_b128 v[184:187], v151 offset:50176
	ds_read_b128 v[188:191], v151 offset:51200
	ds_read_b128 v[192:195], v151 offset:52224
	ds_read_b128 v[196:199], v151 offset:53248
	ds_read_b128 v[200:203], v151 offset:54272
	ds_read_b128 v[204:207], v151 offset:55296
	ds_read_b128 v[208:211], v151 offset:56320
	global_load_lds_dwordx4 v128, s[36:37]
	s_add_i32 m0, s3, 0x2000
	s_add_i32 s3, s33, s25
	global_load_lds_dwordx4 v130, s[36:37]
	s_add_u32 s36, s36, 0x80000
	s_addc_u32 s37, s37, 0
	s_mov_b32 m0, s3
	s_nop 0
	global_load_lds_dwordx4 v128, s[36:37]
	s_add_i32 m0, s3, 0x2000
	s_nop 0
	global_load_lds_dwordx4 v130, s[36:37]
	s_add_u32 s90, s90, 0x80
	s_addc_u32 s91, s91, 0
	s_mov_b32 m0, s57
	s_nop 0
	global_load_lds_dwordx4 v128, s[90:91]
	s_mov_b32 m0, s58
	s_nop 0
	global_load_lds_dwordx4 v130, s[90:91]
	s_waitcnt vmcnt(8)
	s_waitcnt lgkmcnt(0)
	s_barrier
	s_setprio 1
	s_waitcnt lgkmcnt(0)
	v_mfma_f32_16x16x32_bf16 v[60:63], v[140:143], v[180:183], v[60:63]
	v_mfma_f32_16x16x32_bf16 v[56:59], v[156:159], v[180:183], v[56:59]
	v_mfma_f32_16x16x32_bf16 v[44:47], v[140:143], v[188:191], v[44:47]
	v_mfma_f32_16x16x32_bf16 v[40:43], v[156:159], v[188:191], v[40:43]
	v_mfma_f32_16x16x32_bf16 v[28:31], v[140:143], v[196:199], v[28:31]
	v_mfma_f32_16x16x32_bf16 v[24:27], v[156:159], v[196:199], v[24:27]
	v_mfma_f32_16x16x32_bf16 v[12:15], v[140:143], v[204:207], v[12:15]
	v_mfma_f32_16x16x32_bf16 v[8:11], v[156:159], v[204:207], v[8:11]
	v_mfma_f32_16x16x32_bf16 v[60:63], v[152:155], v[184:187], v[60:63]
	v_mfma_f32_16x16x32_bf16 v[56:59], v[160:163], v[184:187], v[56:59]
	v_mfma_f32_16x16x32_bf16 v[44:47], v[152:155], v[192:195], v[44:47]
	v_mfma_f32_16x16x32_bf16 v[40:43], v[160:163], v[192:195], v[40:43]
	v_mfma_f32_16x16x32_bf16 v[28:31], v[152:155], v[200:203], v[28:31]
	v_mfma_f32_16x16x32_bf16 v[24:27], v[160:163], v[200:203], v[24:27]
	v_mfma_f32_16x16x32_bf16 v[12:15], v[152:155], v[208:211], v[12:15]
	v_mfma_f32_16x16x32_bf16 v[8:11], v[160:163], v[208:211], v[8:11]
	v_mfma_f32_16x16x32_bf16 v[52:55], v[164:167], v[180:183], v[52:55]
	v_mfma_f32_16x16x32_bf16 v[48:51], v[172:175], v[180:183], v[48:51]
	v_mfma_f32_16x16x32_bf16 v[36:39], v[164:167], v[188:191], v[36:39]
	v_mfma_f32_16x16x32_bf16 v[32:35], v[172:175], v[188:191], v[32:35]
	v_mfma_f32_16x16x32_bf16 v[20:23], v[164:167], v[196:199], v[20:23]
	v_mfma_f32_16x16x32_bf16 v[16:19], v[172:175], v[196:199], v[16:19]
	v_mfma_f32_16x16x32_bf16 v[4:7], v[164:167], v[204:207], v[4:7]
	v_mfma_f32_16x16x32_bf16 v[0:3], v[172:175], v[204:207], v[0:3]
	v_mfma_f32_16x16x32_bf16 v[52:55], v[168:171], v[184:187], v[52:55]
	v_mfma_f32_16x16x32_bf16 v[48:51], v[176:179], v[184:187], v[48:51]
	v_mfma_f32_16x16x32_bf16 v[36:39], v[168:171], v[192:195], v[36:39]
	v_mfma_f32_16x16x32_bf16 v[32:35], v[176:179], v[192:195], v[32:35]
	v_mfma_f32_16x16x32_bf16 v[20:23], v[168:171], v[200:203], v[20:23]
	v_mfma_f32_16x16x32_bf16 v[16:19], v[176:179], v[200:203], v[16:19]
	v_mfma_f32_16x16x32_bf16 v[4:7], v[168:171], v[208:211], v[4:7]
	v_mfma_f32_16x16x32_bf16 v[0:3], v[176:179], v[208:211], v[0:3]
	s_setprio 0
	s_add_i32 s27, s27, 2
	s_add_u32 s86, s86, 0x100
	s_addc_u32 s87, s87, 0
	s_add_u32 s19, s19, 0x100
	s_addc_u32 s24, s24, 0
	s_cmp_gt_u32 s27, 29
	s_barrier
	s_cbranch_scc0 .LBB0_639
	s_and_b64 vcc, exec, s[12:13]
	s_cbranch_vccz .LBB0_642
	s_barrier

.LBB0_770:
	ds_read_b128 v[154:157], v150
	ds_read_b128 v[158:161], v150 offset:1024
	ds_read_b128 v[162:165], v150 offset:2048
	ds_read_b128 v[166:169], v150 offset:3072
	ds_read_b128 v[170:173], v151
	ds_read_b128 v[174:177], v151 offset:1024
	ds_read_b128 v[178:181], v151 offset:2048
	ds_read_b128 v[182:185], v151 offset:3072
	s_add_u32 s3, s88, 0xfff80080
	s_addc_u32 s37, s89, -1
	s_cmp_eq_u32 s36, 28
	s_cselect_b32 s91, s0, s37
	s_cselect_b32 s90, s1, s3
	s_cselect_b32 s81, s17, s35
	s_cselect_b32 s80, s27, s33
	s_add_i32 m0, s19, 0xc000
	ds_read_b128 v[186:189], v152
	ds_read_b128 v[190:193], v152 offset:1024
	ds_read_b128 v[194:197], v152 offset:2048
	ds_read_b128 v[198:201], v152 offset:3072
	ds_read_b128 v[202:205], v152 offset:4096
	ds_read_b128 v[206:209], v152 offset:5120
	ds_read_b128 v[210:213], v152 offset:6144
	ds_read_b128 v[214:217], v152 offset:7168
	global_load_lds_dwordx4 v138, s[88:89]
	s_add_i32 m0, s19, 0xe000
	s_nop 0
	global_load_lds_dwordx4 v140, s[88:89]
	s_waitcnt vmcnt(8)
	s_waitcnt lgkmcnt(0)
	s_barrier
	s_setprio 1
	s_waitcnt lgkmcnt(0)
	v_mfma_f32_16x16x32_bf16 v[124:127], v[154:157], v[186:189], v[124:127]
	v_mfma_f32_16x16x32_bf16 v[120:123], v[162:165], v[186:189], v[120:123]
	v_mfma_f32_16x16x32_bf16 v[108:111], v[154:157], v[194:197], v[108:111]
	v_mfma_f32_16x16x32_bf16 v[104:107], v[162:165], v[194:197], v[104:107]
	v_mfma_f32_16x16x32_bf16 v[92:95], v[154:157], v[202:205], v[92:95]
	v_mfma_f32_16x16x32_bf16 v[88:91], v[162:165], v[202:205], v[88:91]
	v_mfma_f32_16x16x32_bf16 v[76:79], v[154:157], v[210:213], v[76:79]
	v_mfma_f32_16x16x32_bf16 v[72:75], v[162:165], v[210:213], v[72:75]
	v_mfma_f32_16x16x32_bf16 v[124:127], v[158:161], v[190:193], v[124:127]
	v_mfma_f32_16x16x32_bf16 v[120:123], v[166:169], v[190:193], v[120:123]
	v_mfma_f32_16x16x32_bf16 v[108:111], v[158:161], v[198:201], v[108:111]
	v_mfma_f32_16x16x32_bf16 v[104:107], v[166:169], v[198:201], v[104:107]
	v_mfma_f32_16x16x32_bf16 v[92:95], v[158:161], v[206:209], v[92:95]
	v_mfma_f32_16x16x32_bf16 v[88:91], v[166:169], v[206:209], v[88:91]
	v_mfma_f32_16x16x32_bf16 v[76:79], v[158:161], v[214:217], v[76:79]
	v_mfma_f32_16x16x32_bf16 v[72:75], v[166:169], v[214:217], v[72:75]
	v_mfma_f32_16x16x32_bf16 v[116:119], v[170:173], v[186:189], v[116:119]
	v_mfma_f32_16x16x32_bf16 v[112:115], v[178:181], v[186:189], v[112:115]
	v_mfma_f32_16x16x32_bf16 v[100:103], v[170:173], v[194:197], v[100:103]
	v_mfma_f32_16x16x32_bf16 v[96:99], v[178:181], v[194:197], v[96:99]
	v_mfma_f32_16x16x32_bf16 v[84:87], v[170:173], v[202:205], v[84:87]
	v_mfma_f32_16x16x32_bf16 v[80:83], v[178:181], v[202:205], v[80:83]
	v_mfma_f32_16x16x32_bf16 v[68:71], v[170:173], v[210:213], v[68:71]
	v_mfma_f32_16x16x32_bf16 v[64:67], v[178:181], v[210:213], v[64:67]
	v_mfma_f32_16x16x32_bf16 v[116:119], v[174:177], v[190:193], v[116:119]
	v_mfma_f32_16x16x32_bf16 v[112:115], v[182:185], v[190:193], v[112:115]
	v_mfma_f32_16x16x32_bf16 v[100:103], v[174:177], v[198:201], v[100:103]
	v_mfma_f32_16x16x32_bf16 v[96:99], v[182:185], v[198:201], v[96:99]
	v_mfma_f32_16x16x32_bf16 v[84:87], v[174:177], v[206:209], v[84:87]
	v_mfma_f32_16x16x32_bf16 v[80:83], v[182:185], v[206:209], v[80:83]
	v_mfma_f32_16x16x32_bf16 v[68:71], v[174:177], v[214:217], v[68:71]
	v_mfma_f32_16x16x32_bf16 v[64:67], v[182:185], v[214:217], v[64:67]
	s_setprio 0
	s_barrier
	s_add_i32 s3, s56, s18
	s_mov_b32 m0, s3
	ds_read_b128 v[186:189], v152 offset:16384
	ds_read_b128 v[190:193], v152 offset:17408
	ds_read_b128 v[194:197], v152 offset:18432
	ds_read_b128 v[198:201], v152 offset:19456
	ds_read_b128 v[202:205], v152 offset:20480
	ds_read_b128 v[206:209], v152 offset:21504
	ds_read_b128 v[210:213], v152 offset:22528
	ds_read_b128 v[214:217], v152 offset:23552
	global_load_lds_dwordx4 v130, s[80:81]
	s_add_i32 m0, s3, 0x2000
	s_add_u32 s42, s80, 0x80000
	s_addc_u32 s43, s81, 0
	s_add_i32 s3, s57, s18
	global_load_lds_dwordx4 v134, s[80:81]
	s_mov_b32 m0, s3
	s_nop 0
	global_load_lds_dwordx4 v130, s[42:43]
	s_add_i32 m0, s3, 0x2000
	s_nop 0
	global_load_lds_dwordx4 v134, s[42:43]
	s_mov_b32 m0, s19
	s_nop 0
	global_load_lds_dwordx4 v128, s[90:91]
	s_mov_b32 m0, s25
	s_nop 0
	global_load_lds_dwordx4 v132, s[90:91]
	s_waitcnt vmcnt(8)
	s_waitcnt lgkmcnt(0)
	s_barrier
	s_setprio 1
	s_waitcnt lgkmcnt(0)
	v_mfma_f32_16x16x32_bf16 v[60:63], v[154:157], v[186:189], v[60:63]
	v_mfma_f32_16x16x32_bf16 v[56:59], v[162:165], v[186:189], v[56:59]
	v_mfma_f32_16x16x32_bf16 v[44:47], v[154:157], v[194:197], v[44:47]
	v_mfma_f32_16x16x32_bf16 v[40:43], v[162:165], v[194:197], v[40:43]
	v_mfma_f32_16x16x32_bf16 v[28:31], v[154:157], v[202:205], v[28:31]
	v_mfma_f32_16x16x32_bf16 v[24:27], v[162:165], v[202:205], v[24:27]
	v_mfma_f32_16x16x32_bf16 v[12:15], v[154:157], v[210:213], v[12:15]
	v_mfma_f32_16x16x32_bf16 v[8:11], v[162:165], v[210:213], v[8:11]
	v_mfma_f32_16x16x32_bf16 v[60:63], v[158:161], v[190:193], v[60:63]
	v_mfma_f32_16x16x32_bf16 v[56:59], v[166:169], v[190:193], v[56:59]
	v_mfma_f32_16x16x32_bf16 v[44:47], v[158:161], v[198:201], v[44:47]
	v_mfma_f32_16x16x32_bf16 v[40:43], v[166:169], v[198:201], v[40:43]
	v_mfma_f32_16x16x32_bf16 v[28:31], v[158:161], v[206:209], v[28:31]
	v_mfma_f32_16x16x32_bf16 v[24:27], v[166:169], v[206:209], v[24:27]
	v_mfma_f32_16x16x32_bf16 v[12:15], v[158:161], v[214:217], v[12:15]
	v_mfma_f32_16x16x32_bf16 v[8:11], v[166:169], v[214:217], v[8:11]
	v_mfma_f32_16x16x32_bf16 v[52:55], v[170:173], v[186:189], v[52:55]
	v_mfma_f32_16x16x32_bf16 v[48:51], v[178:181], v[186:189], v[48:51]
	v_mfma_f32_16x16x32_bf16 v[36:39], v[170:173], v[194:197], v[36:39]
	v_mfma_f32_16x16x32_bf16 v[32:35], v[178:181], v[194:197], v[32:35]
	v_mfma_f32_16x16x32_bf16 v[20:23], v[170:173], v[202:205], v[20:23]
	v_mfma_f32_16x16x32_bf16 v[16:19], v[178:181], v[202:205], v[16:19]
	v_mfma_f32_16x16x32_bf16 v[4:7], v[170:173], v[210:213], v[4:7]
	v_mfma_f32_16x16x32_bf16 v[0:3], v[178:181], v[210:213], v[0:3]
	v_mfma_f32_16x16x32_bf16 v[52:55], v[174:177], v[190:193], v[52:55]
	v_mfma_f32_16x16x32_bf16 v[48:51], v[182:185], v[190:193], v[48:51]
	v_mfma_f32_16x16x32_bf16 v[36:39], v[174:177], v[198:201], v[36:39]
	v_mfma_f32_16x16x32_bf16 v[32:35], v[182:185], v[198:201], v[32:35]
	v_mfma_f32_16x16x32_bf16 v[20:23], v[174:177], v[206:209], v[20:23]
	v_mfma_f32_16x16x32_bf16 v[16:19], v[182:185], v[206:209], v[16:19]
	v_mfma_f32_16x16x32_bf16 v[4:7], v[174:177], v[214:217], v[4:7]
	v_mfma_f32_16x16x32_bf16 v[0:3], v[182:185], v[214:217], v[0:3]
	s_setprio 0
	s_barrier
	s_add_i32 s3, 0, 0x18000
	v_add_u32_e32 v153, s3, v149
	s_add_i32 s37, 0, 0x1c000
	ds_read_b128 v[154:157], v153
	ds_read_b128 v[158:161], v153 offset:1024
	ds_read_b128 v[162:165], v153 offset:2048
	ds_read_b128 v[166:169], v153 offset:3072
	v_add_u32_e32 v153, s37, v149
	ds_read_b128 v[170:173], v153
	ds_read_b128 v[174:177], v153 offset:1024
	ds_read_b128 v[178:181], v153 offset:2048
	ds_read_b128 v[182:185], v153 offset:3072
	s_add_u32 s42, s90, 0x80000
	s_addc_u32 s43, s91, 0
	s_mov_b32 m0, s30
	ds_read_b128 v[186:189], v152 offset:32768
	ds_read_b128 v[190:193], v152 offset:33792
	ds_read_b128 v[194:197], v152 offset:34816
	ds_read_b128 v[198:201], v152 offset:35840
	ds_read_b128 v[202:205], v152 offset:36864
	ds_read_b128 v[206:209], v152 offset:37888
	ds_read_b128 v[210:213], v152 offset:38912
	ds_read_b128 v[214:217], v152 offset:39936
	global_load_lds_dwordx4 v128, s[42:43]
	v_lshl_add_u64 v[224:225], s[42:43], 0, v[132:133]
	s_mov_b32 m0, s31
	s_nop 0
	global_load_lds_dwordx4 v[224:225], off
	s_waitcnt vmcnt(8)
	s_waitcnt lgkmcnt(0)
	s_barrier
	s_setprio 1
	s_waitcnt lgkmcnt(0)
	v_mfma_f32_16x16x32_bf16 v[124:127], v[154:157], v[186:189], v[124:127]
	v_mfma_f32_16x16x32_bf16 v[120:123], v[162:165], v[186:189], v[120:123]
	v_mfma_f32_16x16x32_bf16 v[108:111], v[154:157], v[194:197], v[108:111]
	v_mfma_f32_16x16x32_bf16 v[104:107], v[162:165], v[194:197], v[104:107]
	v_mfma_f32_16x16x32_bf16 v[92:95], v[154:157], v[202:205], v[92:95]
	v_mfma_f32_16x16x32_bf16 v[88:91], v[162:165], v[202:205], v[88:91]
	v_mfma_f32_16x16x32_bf16 v[76:79], v[154:157], v[210:213], v[76:79]
	v_mfma_f32_16x16x32_bf16 v[72:75], v[162:165], v[210:213], v[72:75]
	v_mfma_f32_16x16x32_bf16 v[124:127], v[158:161], v[190:193], v[124:127]
	v_mfma_f32_16x16x32_bf16 v[120:123], v[166:169], v[190:193], v[120:123]
	v_mfma_f32_16x16x32_bf16 v[108:111], v[158:161], v[198:201], v[108:111]
	v_mfma_f32_16x16x32_bf16 v[104:107], v[166:169], v[198:201], v[104:107]
	v_mfma_f32_16x16x32_bf16 v[92:95], v[158:161], v[206:209], v[92:95]
	v_mfma_f32_16x16x32_bf16 v[88:91], v[166:169], v[206:209], v[88:91]
	v_mfma_f32_16x16x32_bf16 v[76:79], v[158:161], v[214:217], v[76:79]
	v_mfma_f32_16x16x32_bf16 v[72:75], v[166:169], v[214:217], v[72:75]
	v_mfma_f32_16x16x32_bf16 v[116:119], v[170:173], v[186:189], v[116:119]
	v_mfma_f32_16x16x32_bf16 v[112:115], v[178:181], v[186:189], v[112:115]
	v_mfma_f32_16x16x32_bf16 v[100:103], v[170:173], v[194:197], v[100:103]
	v_mfma_f32_16x16x32_bf16 v[96:99], v[178:181], v[194:197], v[96:99]
	v_mfma_f32_16x16x32_bf16 v[84:87], v[170:173], v[202:205], v[84:87]
	v_mfma_f32_16x16x32_bf16 v[80:83], v[178:181], v[202:205], v[80:83]
	v_mfma_f32_16x16x32_bf16 v[68:71], v[170:173], v[210:213], v[68:71]
	v_mfma_f32_16x16x32_bf16 v[64:67], v[178:181], v[210:213], v[64:67]
	v_mfma_f32_16x16x32_bf16 v[116:119], v[174:177], v[190:193], v[116:119]
	v_mfma_f32_16x16x32_bf16 v[112:115], v[182:185], v[190:193], v[112:115]
	v_mfma_f32_16x16x32_bf16 v[100:103], v[174:177], v[198:201], v[100:103]
	v_mfma_f32_16x16x32_bf16 v[96:99], v[182:185], v[198:201], v[96:99]
	v_mfma_f32_16x16x32_bf16 v[84:87], v[174:177], v[206:209], v[84:87]
	v_mfma_f32_16x16x32_bf16 v[80:83], v[182:185], v[206:209], v[80:83]
	v_mfma_f32_16x16x32_bf16 v[68:71], v[174:177], v[214:217], v[68:71]
	v_mfma_f32_16x16x32_bf16 v[64:67], v[182:185], v[214:217], v[64:67]
	s_setprio 0
	s_barrier
	s_add_i32 s3, s3, s18
	s_add_u32 s42, s80, 0x80
	s_addc_u32 s43, s81, 0
	s_mov_b32 m0, s3
	ds_read_b128 v[186:189], v152 offset:49152
	ds_read_b128 v[190:193], v152 offset:50176
	ds_read_b128 v[194:197], v152 offset:51200
	ds_read_b128 v[198:201], v152 offset:52224
	ds_read_b128 v[202:205], v152 offset:53248
	ds_read_b128 v[206:209], v152 offset:54272
	ds_read_b128 v[210:213], v152 offset:55296
	ds_read_b128 v[214:217], v152 offset:56320
	global_load_lds_dwordx4 v130, s[42:43]
	s_add_i32 m0, s3, 0x2000
	s_add_i32 s3, s37, s18
	global_load_lds_dwordx4 v134, s[42:43]
	s_add_u32 s42, s42, 0x80000
	s_addc_u32 s43, s43, 0
	s_mov_b32 m0, s3
	s_nop 0
	global_load_lds_dwordx4 v130, s[42:43]
	s_add_i32 m0, s3, 0x2000
	s_nop 0
	global_load_lds_dwordx4 v134, s[42:43]
	s_add_u32 s90, s90, 0x80
	s_addc_u32 s91, s91, 0
	s_mov_b32 m0, s48
	s_nop 0
	global_load_lds_dwordx4 v128, s[90:91]
	s_mov_b32 m0, s49
	s_nop 0
	global_load_lds_dwordx4 v132, s[90:91]
	s_waitcnt vmcnt(8)
	s_waitcnt lgkmcnt(0)
	s_barrier
	s_setprio 1
	s_waitcnt lgkmcnt(0)
	v_mfma_f32_16x16x32_bf16 v[60:63], v[154:157], v[186:189], v[60:63]
	v_mfma_f32_16x16x32_bf16 v[56:59], v[162:165], v[186:189], v[56:59]
	v_mfma_f32_16x16x32_bf16 v[44:47], v[154:157], v[194:197], v[44:47]
	v_mfma_f32_16x16x32_bf16 v[40:43], v[162:165], v[194:197], v[40:43]
	v_mfma_f32_16x16x32_bf16 v[28:31], v[154:157], v[202:205], v[28:31]
	v_mfma_f32_16x16x32_bf16 v[24:27], v[162:165], v[202:205], v[24:27]
	v_mfma_f32_16x16x32_bf16 v[12:15], v[154:157], v[210:213], v[12:15]
	v_mfma_f32_16x16x32_bf16 v[8:11], v[162:165], v[210:213], v[8:11]
	v_mfma_f32_16x16x32_bf16 v[60:63], v[158:161], v[190:193], v[60:63]
	v_mfma_f32_16x16x32_bf16 v[56:59], v[166:169], v[190:193], v[56:59]
	v_mfma_f32_16x16x32_bf16 v[44:47], v[158:161], v[198:201], v[44:47]
	v_mfma_f32_16x16x32_bf16 v[40:43], v[166:169], v[198:201], v[40:43]
	v_mfma_f32_16x16x32_bf16 v[28:31], v[158:161], v[206:209], v[28:31]
	v_mfma_f32_16x16x32_bf16 v[24:27], v[166:169], v[206:209], v[24:27]
	v_mfma_f32_16x16x32_bf16 v[12:15], v[158:161], v[214:217], v[12:15]
	v_mfma_f32_16x16x32_bf16 v[8:11], v[166:169], v[214:217], v[8:11]
	v_mfma_f32_16x16x32_bf16 v[52:55], v[170:173], v[186:189], v[52:55]
	v_mfma_f32_16x16x32_bf16 v[48:51], v[178:181], v[186:189], v[48:51]
	v_mfma_f32_16x16x32_bf16 v[36:39], v[170:173], v[194:197], v[36:39]
	v_mfma_f32_16x16x32_bf16 v[32:35], v[178:181], v[194:197], v[32:35]
	v_mfma_f32_16x16x32_bf16 v[20:23], v[170:173], v[202:205], v[20:23]
	v_mfma_f32_16x16x32_bf16 v[16:19], v[178:181], v[202:205], v[16:19]
	v_mfma_f32_16x16x32_bf16 v[4:7], v[170:173], v[210:213], v[4:7]
	v_mfma_f32_16x16x32_bf16 v[0:3], v[178:181], v[210:213], v[0:3]
	v_mfma_f32_16x16x32_bf16 v[52:55], v[174:177], v[190:193], v[52:55]
	v_mfma_f32_16x16x32_bf16 v[48:51], v[182:185], v[190:193], v[48:51]
	v_mfma_f32_16x16x32_bf16 v[36:39], v[174:177], v[198:201], v[36:39]
	v_mfma_f32_16x16x32_bf16 v[32:35], v[182:185], v[198:201], v[32:35]
	v_mfma_f32_16x16x32_bf16 v[20:23], v[174:177], v[206:209], v[20:23]
	v_mfma_f32_16x16x32_bf16 v[16:19], v[182:185], v[206:209], v[16:19]
	v_mfma_f32_16x16x32_bf16 v[4:7], v[174:177], v[214:217], v[4:7]
	v_mfma_f32_16x16x32_bf16 v[0:3], v[182:185], v[214:217], v[0:3]
	s_setprio 0
	s_add_i32 s36, s36, 2
	s_add_u32 s88, s88, 0x100
	s_addc_u32 s89, s89, 0
	s_add_u32 s33, s33, 0x100
	s_addc_u32 s35, s35, 0
	s_cmp_gt_u32 s36, 29
	s_barrier
	s_cbranch_scc0 .LBB0_770
	s_and_b64 vcc, exec, s[14:15]
	s_cbranch_vccz .LBB0_773
	s_barrier

.LBB0_846:
	ds_read_b128 v[140:143], v149
	ds_read_b128 v[152:155], v149 offset:1024
	ds_read_b128 v[156:159], v149 offset:2048
	ds_read_b128 v[160:163], v149 offset:3072
	ds_read_b128 v[164:167], v150
	ds_read_b128 v[168:171], v150 offset:1024
	ds_read_b128 v[172:175], v150 offset:2048
	ds_read_b128 v[176:179], v150 offset:3072
	s_add_u32 s3, s84, 0xffe00080
	s_addc_u32 s37, s85, -1
	s_cmpk_eq_i32 s36, 0x7c
	s_cselect_b32 s87, s0, s37
	s_cselect_b32 s86, s1, s3
	s_cselect_b32 s81, s15, s33
	s_cselect_b32 s80, s17, s27
	s_add_i32 m0, s19, 0xc000
	ds_read_b128 v[180:183], v151
	ds_read_b128 v[184:187], v151 offset:1024
	ds_read_b128 v[188:191], v151 offset:2048
	ds_read_b128 v[192:195], v151 offset:3072
	ds_read_b128 v[196:199], v151 offset:4096
	ds_read_b128 v[200:203], v151 offset:5120
	ds_read_b128 v[204:207], v151 offset:6144
	ds_read_b128 v[208:211], v151 offset:7168
	global_load_lds_dwordx4 v132, s[84:85]
	s_add_i32 m0, s19, 0xe000
	s_nop 0
	global_load_lds_dwordx4 v134, s[84:85]
	s_waitcnt vmcnt(8)
	s_waitcnt lgkmcnt(0)
	s_barrier
	s_setprio 1
	s_waitcnt lgkmcnt(0)
	v_mfma_f32_16x16x32_bf16 v[124:127], v[140:143], v[180:183], v[124:127]
	v_mfma_f32_16x16x32_bf16 v[120:123], v[156:159], v[180:183], v[120:123]
	v_mfma_f32_16x16x32_bf16 v[112:115], v[140:143], v[188:191], v[112:115]
	v_mfma_f32_16x16x32_bf16 v[104:107], v[156:159], v[188:191], v[104:107]
	v_mfma_f32_16x16x32_bf16 v[96:99], v[140:143], v[196:199], v[96:99]
	v_mfma_f32_16x16x32_bf16 v[88:91], v[156:159], v[196:199], v[88:91]
	v_mfma_f32_16x16x32_bf16 v[80:83], v[140:143], v[204:207], v[80:83]
	v_mfma_f32_16x16x32_bf16 v[72:75], v[156:159], v[204:207], v[72:75]
	v_mfma_f32_16x16x32_bf16 v[124:127], v[152:155], v[184:187], v[124:127]
	v_mfma_f32_16x16x32_bf16 v[120:123], v[160:163], v[184:187], v[120:123]
	v_mfma_f32_16x16x32_bf16 v[112:115], v[152:155], v[192:195], v[112:115]
	v_mfma_f32_16x16x32_bf16 v[104:107], v[160:163], v[192:195], v[104:107]
	v_mfma_f32_16x16x32_bf16 v[96:99], v[152:155], v[200:203], v[96:99]
	v_mfma_f32_16x16x32_bf16 v[88:91], v[160:163], v[200:203], v[88:91]
	v_mfma_f32_16x16x32_bf16 v[80:83], v[152:155], v[208:211], v[80:83]
	v_mfma_f32_16x16x32_bf16 v[72:75], v[160:163], v[208:211], v[72:75]
	v_mfma_f32_16x16x32_bf16 v[116:119], v[164:167], v[180:183], v[116:119]
	v_mfma_f32_16x16x32_bf16 v[108:111], v[172:175], v[180:183], v[108:111]
	v_mfma_f32_16x16x32_bf16 v[100:103], v[164:167], v[188:191], v[100:103]
	v_mfma_f32_16x16x32_bf16 v[92:95], v[172:175], v[188:191], v[92:95]
	v_mfma_f32_16x16x32_bf16 v[84:87], v[164:167], v[196:199], v[84:87]
	v_mfma_f32_16x16x32_bf16 v[76:79], v[172:175], v[196:199], v[76:79]
	v_mfma_f32_16x16x32_bf16 v[68:71], v[164:167], v[204:207], v[68:71]
	v_mfma_f32_16x16x32_bf16 v[64:67], v[172:175], v[204:207], v[64:67]
	v_mfma_f32_16x16x32_bf16 v[116:119], v[168:171], v[184:187], v[116:119]
	v_mfma_f32_16x16x32_bf16 v[108:111], v[176:179], v[184:187], v[108:111]
	v_mfma_f32_16x16x32_bf16 v[100:103], v[168:171], v[192:195], v[100:103]
	v_mfma_f32_16x16x32_bf16 v[92:95], v[176:179], v[192:195], v[92:95]
	v_mfma_f32_16x16x32_bf16 v[84:87], v[168:171], v[200:203], v[84:87]
	v_mfma_f32_16x16x32_bf16 v[76:79], v[176:179], v[200:203], v[76:79]
	v_mfma_f32_16x16x32_bf16 v[68:71], v[168:171], v[208:211], v[68:71]
	v_mfma_f32_16x16x32_bf16 v[64:67], v[176:179], v[208:211], v[64:67]
	s_setprio 0
	s_barrier
	s_add_i32 s3, s57, s18
	s_mov_b32 m0, s3
	ds_read_b128 v[180:183], v151 offset:16384
	ds_read_b128 v[184:187], v151 offset:17408
	ds_read_b128 v[188:191], v151 offset:18432
	ds_read_b128 v[192:195], v151 offset:19456
	ds_read_b128 v[196:199], v151 offset:20480
	ds_read_b128 v[200:203], v151 offset:21504
	ds_read_b128 v[204:207], v151 offset:22528
	ds_read_b128 v[208:211], v151 offset:23552
	global_load_lds_dwordx4 v128, s[80:81]
	s_add_i32 m0, s3, 0x2000
	s_add_u32 s42, s80, 0x200000
	s_addc_u32 s43, s81, 0
	s_add_i32 s3, s58, s18
	global_load_lds_dwordx4 v130, s[80:81]
	s_mov_b32 m0, s3
	s_nop 0
	global_load_lds_dwordx4 v128, s[42:43]
	s_add_i32 m0, s3, 0x2000
	s_nop 0
	global_load_lds_dwordx4 v130, s[42:43]
	s_mov_b32 m0, s19
	s_nop 0
	global_load_lds_dwordx4 v128, s[86:87]
	s_mov_b32 m0, s25
	s_nop 0
	global_load_lds_dwordx4 v130, s[86:87]
	s_waitcnt vmcnt(8)
	s_waitcnt lgkmcnt(0)
	s_barrier
	s_setprio 1
	s_waitcnt lgkmcnt(0)
	v_mfma_f32_16x16x32_bf16 v[60:63], v[140:143], v[180:183], v[60:63]
	v_mfma_f32_16x16x32_bf16 v[56:59], v[156:159], v[180:183], v[56:59]
	v_mfma_f32_16x16x32_bf16 v[48:51], v[140:143], v[188:191], v[48:51]
	v_mfma_f32_16x16x32_bf16 v[40:43], v[156:159], v[188:191], v[40:43]
	v_mfma_f32_16x16x32_bf16 v[32:35], v[140:143], v[196:199], v[32:35]
	v_mfma_f32_16x16x32_bf16 v[24:27], v[156:159], v[196:199], v[24:27]
	v_mfma_f32_16x16x32_bf16 v[16:19], v[140:143], v[204:207], v[16:19]
	v_mfma_f32_16x16x32_bf16 v[8:11], v[156:159], v[204:207], v[8:11]
	v_mfma_f32_16x16x32_bf16 v[60:63], v[152:155], v[184:187], v[60:63]
	v_mfma_f32_16x16x32_bf16 v[56:59], v[160:163], v[184:187], v[56:59]
	v_mfma_f32_16x16x32_bf16 v[48:51], v[152:155], v[192:195], v[48:51]
	v_mfma_f32_16x16x32_bf16 v[40:43], v[160:163], v[192:195], v[40:43]
	v_mfma_f32_16x16x32_bf16 v[32:35], v[152:155], v[200:203], v[32:35]
	v_mfma_f32_16x16x32_bf16 v[24:27], v[160:163], v[200:203], v[24:27]
	v_mfma_f32_16x16x32_bf16 v[16:19], v[152:155], v[208:211], v[16:19]
	v_mfma_f32_16x16x32_bf16 v[8:11], v[160:163], v[208:211], v[8:11]
	v_mfma_f32_16x16x32_bf16 v[52:55], v[164:167], v[180:183], v[52:55]
	v_mfma_f32_16x16x32_bf16 v[44:47], v[172:175], v[180:183], v[44:47]
	v_mfma_f32_16x16x32_bf16 v[36:39], v[164:167], v[188:191], v[36:39]
	v_mfma_f32_16x16x32_bf16 v[28:31], v[172:175], v[188:191], v[28:31]
	v_mfma_f32_16x16x32_bf16 v[20:23], v[164:167], v[196:199], v[20:23]
	v_mfma_f32_16x16x32_bf16 v[12:15], v[172:175], v[196:199], v[12:15]
	v_mfma_f32_16x16x32_bf16 v[4:7], v[164:167], v[204:207], v[4:7]
	v_mfma_f32_16x16x32_bf16 v[0:3], v[172:175], v[204:207], v[0:3]
	v_mfma_f32_16x16x32_bf16 v[52:55], v[168:171], v[184:187], v[52:55]
	v_mfma_f32_16x16x32_bf16 v[44:47], v[176:179], v[184:187], v[44:47]
	v_mfma_f32_16x16x32_bf16 v[36:39], v[168:171], v[192:195], v[36:39]
	v_mfma_f32_16x16x32_bf16 v[28:31], v[176:179], v[192:195], v[28:31]
	v_mfma_f32_16x16x32_bf16 v[20:23], v[168:171], v[200:203], v[20:23]
	v_mfma_f32_16x16x32_bf16 v[12:15], v[176:179], v[200:203], v[12:15]
	v_mfma_f32_16x16x32_bf16 v[4:7], v[168:171], v[208:211], v[4:7]
	v_mfma_f32_16x16x32_bf16 v[0:3], v[176:179], v[208:211], v[0:3]
	s_setprio 0
	s_barrier
	s_add_i32 s3, 0, 0x18000
	s_add_i32 s37, 0, 0x1c000
	v_add_u32_e32 v160, s3, v147
	v_add_u32_e32 v176, s37, v147
	ds_read_b128 v[140:143], v160
	ds_read_b128 v[152:155], v160 offset:1024
	ds_read_b128 v[156:159], v160 offset:2048
	ds_read_b128 v[160:163], v160 offset:3072
	ds_read_b128 v[164:167], v176
	ds_read_b128 v[168:171], v176 offset:1024
	ds_read_b128 v[172:175], v176 offset:2048
	ds_read_b128 v[176:179], v176 offset:3072
	s_add_u32 s42, s86, 0x200000
	s_addc_u32 s43, s87, 0
	s_mov_b32 m0, s30
	ds_read_b128 v[180:183], v151 offset:32768
	ds_read_b128 v[184:187], v151 offset:33792
	ds_read_b128 v[188:191], v151 offset:34816
	ds_read_b128 v[192:195], v151 offset:35840
	ds_read_b128 v[196:199], v151 offset:36864
	ds_read_b128 v[200:203], v151 offset:37888
	ds_read_b128 v[204:207], v151 offset:38912
	ds_read_b128 v[208:211], v151 offset:39936
	global_load_lds_dwordx4 v128, s[42:43]
	v_lshl_add_u64 v[218:219], s[42:43], 0, v[130:131]
	s_mov_b32 m0, s31
	s_nop 0
	global_load_lds_dwordx4 v[218:219], off
	s_waitcnt vmcnt(8)
	s_waitcnt lgkmcnt(0)
	s_barrier
	s_setprio 1
	s_waitcnt lgkmcnt(0)
	v_mfma_f32_16x16x32_bf16 v[124:127], v[140:143], v[180:183], v[124:127]
	v_mfma_f32_16x16x32_bf16 v[120:123], v[156:159], v[180:183], v[120:123]
	v_mfma_f32_16x16x32_bf16 v[112:115], v[140:143], v[188:191], v[112:115]
	v_mfma_f32_16x16x32_bf16 v[104:107], v[156:159], v[188:191], v[104:107]
	v_mfma_f32_16x16x32_bf16 v[96:99], v[140:143], v[196:199], v[96:99]
	v_mfma_f32_16x16x32_bf16 v[88:91], v[156:159], v[196:199], v[88:91]
	v_mfma_f32_16x16x32_bf16 v[80:83], v[140:143], v[204:207], v[80:83]
	v_mfma_f32_16x16x32_bf16 v[72:75], v[156:159], v[204:207], v[72:75]
	v_mfma_f32_16x16x32_bf16 v[124:127], v[152:155], v[184:187], v[124:127]
	v_mfma_f32_16x16x32_bf16 v[120:123], v[160:163], v[184:187], v[120:123]
	v_mfma_f32_16x16x32_bf16 v[112:115], v[152:155], v[192:195], v[112:115]
	v_mfma_f32_16x16x32_bf16 v[104:107], v[160:163], v[192:195], v[104:107]
	v_mfma_f32_16x16x32_bf16 v[96:99], v[152:155], v[200:203], v[96:99]
	v_mfma_f32_16x16x32_bf16 v[88:91], v[160:163], v[200:203], v[88:91]
	v_mfma_f32_16x16x32_bf16 v[80:83], v[152:155], v[208:211], v[80:83]
	v_mfma_f32_16x16x32_bf16 v[72:75], v[160:163], v[208:211], v[72:75]
	v_mfma_f32_16x16x32_bf16 v[116:119], v[164:167], v[180:183], v[116:119]
	v_mfma_f32_16x16x32_bf16 v[108:111], v[172:175], v[180:183], v[108:111]
	v_mfma_f32_16x16x32_bf16 v[100:103], v[164:167], v[188:191], v[100:103]
	v_mfma_f32_16x16x32_bf16 v[92:95], v[172:175], v[188:191], v[92:95]
	v_mfma_f32_16x16x32_bf16 v[84:87], v[164:167], v[196:199], v[84:87]
	v_mfma_f32_16x16x32_bf16 v[76:79], v[172:175], v[196:199], v[76:79]
	v_mfma_f32_16x16x32_bf16 v[68:71], v[164:167], v[204:207], v[68:71]
	v_mfma_f32_16x16x32_bf16 v[64:67], v[172:175], v[204:207], v[64:67]
	v_mfma_f32_16x16x32_bf16 v[116:119], v[168:171], v[184:187], v[116:119]
	v_mfma_f32_16x16x32_bf16 v[108:111], v[176:179], v[184:187], v[108:111]
	v_mfma_f32_16x16x32_bf16 v[100:103], v[168:171], v[192:195], v[100:103]
	v_mfma_f32_16x16x32_bf16 v[92:95], v[176:179], v[192:195], v[92:95]
	v_mfma_f32_16x16x32_bf16 v[84:87], v[168:171], v[200:203], v[84:87]
	v_mfma_f32_16x16x32_bf16 v[76:79], v[176:179], v[200:203], v[76:79]
	v_mfma_f32_16x16x32_bf16 v[68:71], v[168:171], v[208:211], v[68:71]
	v_mfma_f32_16x16x32_bf16 v[64:67], v[176:179], v[208:211], v[64:67]
	s_setprio 0
	s_barrier
	s_add_i32 s3, s3, s18
	s_add_u32 s42, s80, 0x80
	s_addc_u32 s43, s81, 0
	s_mov_b32 m0, s3
	ds_read_b128 v[180:183], v151 offset:49152
	ds_read_b128 v[184:187], v151 offset:50176
	ds_read_b128 v[188:191], v151 offset:51200
	ds_read_b128 v[192:195], v151 offset:52224
	ds_read_b128 v[196:199], v151 offset:53248
	ds_read_b128 v[200:203], v151 offset:54272
	ds_read_b128 v[204:207], v151 offset:55296
	ds_read_b128 v[208:211], v151 offset:56320
	global_load_lds_dwordx4 v128, s[42:43]
	s_add_i32 m0, s3, 0x2000
	s_add_i32 s3, s37, s18
	global_load_lds_dwordx4 v130, s[42:43]
	s_add_u32 s42, s42, 0x200000
	s_addc_u32 s43, s43, 0
	s_mov_b32 m0, s3
	s_nop 0
	global_load_lds_dwordx4 v128, s[42:43]
	s_add_i32 m0, s3, 0x2000
	s_nop 0
	global_load_lds_dwordx4 v130, s[42:43]
	s_add_u32 s86, s86, 0x80
	s_addc_u32 s87, s87, 0
	s_mov_b32 m0, s49
	s_nop 0
	global_load_lds_dwordx4 v128, s[86:87]
	s_mov_b32 m0, s56
	s_nop 0
	global_load_lds_dwordx4 v130, s[86:87]
	s_waitcnt vmcnt(8)
	s_waitcnt lgkmcnt(0)
	s_barrier
	s_setprio 1
	s_waitcnt lgkmcnt(0)
	v_mfma_f32_16x16x32_bf16 v[60:63], v[140:143], v[180:183], v[60:63]
	v_mfma_f32_16x16x32_bf16 v[56:59], v[156:159], v[180:183], v[56:59]
	v_mfma_f32_16x16x32_bf16 v[48:51], v[140:143], v[188:191], v[48:51]
	v_mfma_f32_16x16x32_bf16 v[40:43], v[156:159], v[188:191], v[40:43]
	v_mfma_f32_16x16x32_bf16 v[32:35], v[140:143], v[196:199], v[32:35]
	v_mfma_f32_16x16x32_bf16 v[24:27], v[156:159], v[196:199], v[24:27]
	v_mfma_f32_16x16x32_bf16 v[16:19], v[140:143], v[204:207], v[16:19]
	v_mfma_f32_16x16x32_bf16 v[8:11], v[156:159], v[204:207], v[8:11]
	v_mfma_f32_16x16x32_bf16 v[60:63], v[152:155], v[184:187], v[60:63]
	v_mfma_f32_16x16x32_bf16 v[56:59], v[160:163], v[184:187], v[56:59]
	v_mfma_f32_16x16x32_bf16 v[48:51], v[152:155], v[192:195], v[48:51]
	v_mfma_f32_16x16x32_bf16 v[40:43], v[160:163], v[192:195], v[40:43]
	v_mfma_f32_16x16x32_bf16 v[32:35], v[152:155], v[200:203], v[32:35]
	v_mfma_f32_16x16x32_bf16 v[24:27], v[160:163], v[200:203], v[24:27]
	v_mfma_f32_16x16x32_bf16 v[16:19], v[152:155], v[208:211], v[16:19]
	v_mfma_f32_16x16x32_bf16 v[8:11], v[160:163], v[208:211], v[8:11]
	v_mfma_f32_16x16x32_bf16 v[52:55], v[164:167], v[180:183], v[52:55]
	v_mfma_f32_16x16x32_bf16 v[44:47], v[172:175], v[180:183], v[44:47]
	v_mfma_f32_16x16x32_bf16 v[36:39], v[164:167], v[188:191], v[36:39]
	v_mfma_f32_16x16x32_bf16 v[28:31], v[172:175], v[188:191], v[28:31]
	v_mfma_f32_16x16x32_bf16 v[20:23], v[164:167], v[196:199], v[20:23]
	v_mfma_f32_16x16x32_bf16 v[12:15], v[172:175], v[196:199], v[12:15]
	v_mfma_f32_16x16x32_bf16 v[4:7], v[164:167], v[204:207], v[4:7]
	v_mfma_f32_16x16x32_bf16 v[0:3], v[172:175], v[204:207], v[0:3]
	v_mfma_f32_16x16x32_bf16 v[52:55], v[168:171], v[184:187], v[52:55]
	v_mfma_f32_16x16x32_bf16 v[44:47], v[176:179], v[184:187], v[44:47]
	v_mfma_f32_16x16x32_bf16 v[36:39], v[168:171], v[192:195], v[36:39]
	v_mfma_f32_16x16x32_bf16 v[28:31], v[176:179], v[192:195], v[28:31]
	v_mfma_f32_16x16x32_bf16 v[20:23], v[168:171], v[200:203], v[20:23]
	v_mfma_f32_16x16x32_bf16 v[12:15], v[176:179], v[200:203], v[12:15]
	v_mfma_f32_16x16x32_bf16 v[4:7], v[168:171], v[208:211], v[4:7]
	v_mfma_f32_16x16x32_bf16 v[0:3], v[176:179], v[208:211], v[0:3]
	s_setprio 0
	s_add_i32 s36, s36, 2
	s_add_u32 s84, s84, 0x100
	s_addc_u32 s85, s85, 0
	s_add_u32 s27, s27, 0x100
	s_addc_u32 s33, s33, 0
	s_cmpk_gt_u32 s36, 0x7d
	s_barrier
	s_cbranch_scc0 .LBB0_846
	s_and_b64 vcc, exec, s[12:13]
	s_cbranch_vccz .LBB0_849
	s_barrier

.LBB0_919:
	ds_read_b128 v[128:131], v173
	ds_read_b128 v[132:135], v173 offset:1024
	ds_read_b128 v[158:161], v173 offset:2048
	ds_read_b128 v[178:181], v173 offset:3072
	ds_read_b128 v[182:185], v174
	ds_read_b128 v[186:189], v174 offset:1024
	ds_read_b128 v[190:193], v174 offset:2048
	ds_read_b128 v[194:197], v174 offset:3072
	s_add_u32 s3, s34, 0xfff80080
	s_addc_u32 s27, s35, -1
	s_cmp_eq_u32 s24, 28
	s_cselect_b32 vcc_hi, s0, s27
	s_cselect_b32 vcc_lo, s1, s3
	s_cselect_b32 s81, s15, s19
	s_cselect_b32 s80, s17, s18
	s_add_i32 m0, s30, 0xc000
	ds_read_b128 v[198:201], v175
	ds_read_b128 v[202:205], v175 offset:1024
	ds_read_b128 v[206:209], v175 offset:2048
	ds_read_b128 v[210:213], v175 offset:3072
	ds_read_b128 v[214:217], v175 offset:4096
	ds_read_b128 v[218:221], v175 offset:5120
	ds_read_b128 v[222:225], v175 offset:6144
	ds_read_b128 v[230:233], v175 offset:7168
	global_load_lds_dwordx4 v148, s[34:35]
	s_add_i32 m0, s30, 0xe000
	s_nop 0
	global_load_lds_dwordx4 v150, s[34:35]
	s_waitcnt vmcnt(8)
	s_waitcnt lgkmcnt(0)
	s_barrier
	s_setprio 1
	s_waitcnt lgkmcnt(0)
	v_mfma_f32_16x16x32_bf16 v[124:127], v[128:131], v[198:201], v[124:127]
	v_mfma_f32_16x16x32_bf16 v[120:123], v[158:161], v[198:201], v[120:123]
	v_mfma_f32_16x16x32_bf16 v[108:111], v[128:131], v[206:209], v[108:111]
	v_mfma_f32_16x16x32_bf16 v[104:107], v[158:161], v[206:209], v[104:107]
	v_mfma_f32_16x16x32_bf16 v[92:95], v[128:131], v[214:217], v[92:95]
	v_mfma_f32_16x16x32_bf16 v[88:91], v[158:161], v[214:217], v[88:91]
	v_mfma_f32_16x16x32_bf16 v[76:79], v[128:131], v[222:225], v[76:79]
	v_mfma_f32_16x16x32_bf16 v[72:75], v[158:161], v[222:225], v[72:75]
	v_mfma_f32_16x16x32_bf16 v[124:127], v[132:135], v[202:205], v[124:127]
	v_mfma_f32_16x16x32_bf16 v[120:123], v[178:181], v[202:205], v[120:123]
	v_mfma_f32_16x16x32_bf16 v[108:111], v[132:135], v[210:213], v[108:111]
	v_mfma_f32_16x16x32_bf16 v[104:107], v[178:181], v[210:213], v[104:107]
	v_mfma_f32_16x16x32_bf16 v[92:95], v[132:135], v[218:221], v[92:95]
	v_mfma_f32_16x16x32_bf16 v[88:91], v[178:181], v[218:221], v[88:91]
	v_mfma_f32_16x16x32_bf16 v[76:79], v[132:135], v[230:233], v[76:79]
	v_mfma_f32_16x16x32_bf16 v[72:75], v[178:181], v[230:233], v[72:75]
	v_mfma_f32_16x16x32_bf16 v[116:119], v[182:185], v[198:201], v[116:119]
	v_mfma_f32_16x16x32_bf16 v[112:115], v[190:193], v[198:201], v[112:115]
	v_mfma_f32_16x16x32_bf16 v[100:103], v[182:185], v[206:209], v[100:103]
	v_mfma_f32_16x16x32_bf16 v[96:99], v[190:193], v[206:209], v[96:99]
	v_mfma_f32_16x16x32_bf16 v[84:87], v[182:185], v[214:217], v[84:87]
	v_mfma_f32_16x16x32_bf16 v[80:83], v[190:193], v[214:217], v[80:83]
	v_mfma_f32_16x16x32_bf16 v[68:71], v[182:185], v[222:225], v[68:71]
	v_mfma_f32_16x16x32_bf16 v[64:67], v[190:193], v[222:225], v[64:67]
	v_mfma_f32_16x16x32_bf16 v[116:119], v[186:189], v[202:205], v[116:119]
	v_mfma_f32_16x16x32_bf16 v[112:115], v[194:197], v[202:205], v[112:115]
	v_mfma_f32_16x16x32_bf16 v[100:103], v[186:189], v[210:213], v[100:103]
	v_mfma_f32_16x16x32_bf16 v[96:99], v[194:197], v[210:213], v[96:99]
	v_mfma_f32_16x16x32_bf16 v[84:87], v[186:189], v[218:221], v[84:87]
	v_mfma_f32_16x16x32_bf16 v[80:83], v[194:197], v[218:221], v[80:83]
	v_mfma_f32_16x16x32_bf16 v[68:71], v[186:189], v[230:233], v[68:71]
	v_mfma_f32_16x16x32_bf16 v[64:67], v[194:197], v[230:233], v[64:67]
	s_setprio 0
	s_barrier
	s_add_i32 s3, s57, s25
	s_mov_b32 m0, s3
	ds_read_b128 v[198:201], v175 offset:16384
	ds_read_b128 v[202:205], v175 offset:17408
	ds_read_b128 v[206:209], v175 offset:18432
	ds_read_b128 v[210:213], v175 offset:19456
	ds_read_b128 v[214:217], v175 offset:20480
	ds_read_b128 v[218:221], v175 offset:21504
	ds_read_b128 v[222:225], v175 offset:22528
	ds_read_b128 v[230:233], v175 offset:23552
	global_load_lds_dwordx4 v138, s[80:81]
	s_add_i32 m0, s3, 0x2000
	s_add_u32 s36, s80, 0x80000
	s_addc_u32 s37, s81, 0
	s_add_i32 s3, s76, s25
	global_load_lds_dwordx4 v142, s[80:81]
	s_mov_b32 m0, s3
	s_nop 0
	global_load_lds_dwordx4 v138, s[36:37]
	s_add_i32 m0, s3, 0x2000
	s_nop 0
	global_load_lds_dwordx4 v142, s[36:37]
	s_mov_b32 m0, s30
	s_nop 0
	global_load_lds_dwordx4 v136, vcc
	s_mov_b32 m0, s31
	s_nop 0
	global_load_lds_dwordx4 v140, vcc
	s_waitcnt vmcnt(8)
	s_waitcnt lgkmcnt(0)
	s_barrier
	s_setprio 1
	s_waitcnt lgkmcnt(0)
	v_mfma_f32_16x16x32_bf16 v[60:63], v[128:131], v[198:201], v[60:63]
	v_mfma_f32_16x16x32_bf16 v[56:59], v[158:161], v[198:201], v[56:59]
	v_mfma_f32_16x16x32_bf16 v[44:47], v[128:131], v[206:209], v[44:47]
	v_mfma_f32_16x16x32_bf16 v[40:43], v[158:161], v[206:209], v[40:43]
	v_mfma_f32_16x16x32_bf16 v[28:31], v[128:131], v[214:217], v[28:31]
	v_mfma_f32_16x16x32_bf16 v[24:27], v[158:161], v[214:217], v[24:27]
	v_mfma_f32_16x16x32_bf16 v[12:15], v[128:131], v[222:225], v[12:15]
	v_mfma_f32_16x16x32_bf16 v[8:11], v[158:161], v[222:225], v[8:11]
	v_mfma_f32_16x16x32_bf16 v[60:63], v[132:135], v[202:205], v[60:63]
	v_mfma_f32_16x16x32_bf16 v[56:59], v[178:181], v[202:205], v[56:59]
	v_mfma_f32_16x16x32_bf16 v[44:47], v[132:135], v[210:213], v[44:47]
	v_mfma_f32_16x16x32_bf16 v[40:43], v[178:181], v[210:213], v[40:43]
	v_mfma_f32_16x16x32_bf16 v[28:31], v[132:135], v[218:221], v[28:31]
	v_mfma_f32_16x16x32_bf16 v[24:27], v[178:181], v[218:221], v[24:27]
	v_mfma_f32_16x16x32_bf16 v[12:15], v[132:135], v[230:233], v[12:15]
	v_mfma_f32_16x16x32_bf16 v[8:11], v[178:181], v[230:233], v[8:11]
	v_mfma_f32_16x16x32_bf16 v[52:55], v[182:185], v[198:201], v[52:55]
	v_mfma_f32_16x16x32_bf16 v[48:51], v[190:193], v[198:201], v[48:51]
	v_mfma_f32_16x16x32_bf16 v[36:39], v[182:185], v[206:209], v[36:39]
	v_mfma_f32_16x16x32_bf16 v[32:35], v[190:193], v[206:209], v[32:35]
	v_mfma_f32_16x16x32_bf16 v[20:23], v[182:185], v[214:217], v[20:23]
	v_mfma_f32_16x16x32_bf16 v[16:19], v[190:193], v[214:217], v[16:19]
	v_mfma_f32_16x16x32_bf16 v[4:7], v[182:185], v[222:225], v[4:7]
	v_mfma_f32_16x16x32_bf16 v[0:3], v[190:193], v[222:225], v[0:3]
	v_mfma_f32_16x16x32_bf16 v[52:55], v[186:189], v[202:205], v[52:55]
	v_mfma_f32_16x16x32_bf16 v[48:51], v[194:197], v[202:205], v[48:51]
	v_mfma_f32_16x16x32_bf16 v[36:39], v[186:189], v[210:213], v[36:39]
	v_mfma_f32_16x16x32_bf16 v[32:35], v[194:197], v[210:213], v[32:35]
	v_mfma_f32_16x16x32_bf16 v[20:23], v[186:189], v[218:221], v[20:23]
	v_mfma_f32_16x16x32_bf16 v[16:19], v[194:197], v[218:221], v[16:19]
	v_mfma_f32_16x16x32_bf16 v[4:7], v[186:189], v[230:233], v[4:7]
	v_mfma_f32_16x16x32_bf16 v[0:3], v[194:197], v[230:233], v[0:3]
	s_setprio 0
	s_barrier
	s_add_i32 s3, 0, 0x18000
	v_add_u32_e32 v144, s3, v165
	s_add_i32 s27, 0, 0x1c000
	ds_read_b128 v[128:131], v144
	ds_read_b128 v[132:135], v144 offset:1024
	ds_read_b128 v[158:161], v144 offset:2048
	ds_read_b128 v[178:181], v144 offset:3072
	v_add_u32_e32 v144, s27, v165
	ds_read_b128 v[182:185], v144
	ds_read_b128 v[186:189], v144 offset:1024
	ds_read_b128 v[190:193], v144 offset:2048
	ds_read_b128 v[194:197], v144 offset:3072
	s_add_u32 s36, vcc_lo, 0x80000
	s_addc_u32 s37, vcc_hi, 0
	s_mov_b32 m0, s58
	ds_read_b128 v[198:201], v175 offset:32768
	ds_read_b128 v[202:205], v175 offset:33792
	ds_read_b128 v[206:209], v175 offset:34816
	ds_read_b128 v[210:213], v175 offset:35840
	ds_read_b128 v[214:217], v175 offset:36864
	ds_read_b128 v[218:221], v175 offset:37888
	ds_read_b128 v[222:225], v175 offset:38912
	ds_read_b128 v[230:233], v175 offset:39936
	global_load_lds_dwordx4 v136, s[36:37]
	s_mov_b32 m0, s59
	s_nop 0
	global_load_lds_dwordx4 v140, s[36:37]
	s_waitcnt vmcnt(8)
	s_waitcnt lgkmcnt(0)
	s_barrier
	s_setprio 1
	s_waitcnt lgkmcnt(0)
	v_mfma_f32_16x16x32_bf16 v[124:127], v[128:131], v[198:201], v[124:127]
	v_mfma_f32_16x16x32_bf16 v[120:123], v[158:161], v[198:201], v[120:123]
	v_mfma_f32_16x16x32_bf16 v[108:111], v[128:131], v[206:209], v[108:111]
	v_mfma_f32_16x16x32_bf16 v[104:107], v[158:161], v[206:209], v[104:107]
	v_mfma_f32_16x16x32_bf16 v[92:95], v[128:131], v[214:217], v[92:95]
	v_mfma_f32_16x16x32_bf16 v[88:91], v[158:161], v[214:217], v[88:91]
	v_mfma_f32_16x16x32_bf16 v[76:79], v[128:131], v[222:225], v[76:79]
	v_mfma_f32_16x16x32_bf16 v[72:75], v[158:161], v[222:225], v[72:75]
	v_mfma_f32_16x16x32_bf16 v[124:127], v[132:135], v[202:205], v[124:127]
	v_mfma_f32_16x16x32_bf16 v[120:123], v[178:181], v[202:205], v[120:123]
	v_mfma_f32_16x16x32_bf16 v[108:111], v[132:135], v[210:213], v[108:111]
	v_mfma_f32_16x16x32_bf16 v[104:107], v[178:181], v[210:213], v[104:107]
	v_mfma_f32_16x16x32_bf16 v[92:95], v[132:135], v[218:221], v[92:95]
	v_mfma_f32_16x16x32_bf16 v[88:91], v[178:181], v[218:221], v[88:91]
	v_mfma_f32_16x16x32_bf16 v[76:79], v[132:135], v[230:233], v[76:79]
	v_mfma_f32_16x16x32_bf16 v[72:75], v[178:181], v[230:233], v[72:75]
	v_mfma_f32_16x16x32_bf16 v[116:119], v[182:185], v[198:201], v[116:119]
	v_mfma_f32_16x16x32_bf16 v[112:115], v[190:193], v[198:201], v[112:115]
	v_mfma_f32_16x16x32_bf16 v[100:103], v[182:185], v[206:209], v[100:103]
	v_mfma_f32_16x16x32_bf16 v[96:99], v[190:193], v[206:209], v[96:99]
	v_mfma_f32_16x16x32_bf16 v[84:87], v[182:185], v[214:217], v[84:87]
	v_mfma_f32_16x16x32_bf16 v[80:83], v[190:193], v[214:217], v[80:83]
	v_mfma_f32_16x16x32_bf16 v[68:71], v[182:185], v[222:225], v[68:71]
	v_mfma_f32_16x16x32_bf16 v[64:67], v[190:193], v[222:225], v[64:67]
	v_mfma_f32_16x16x32_bf16 v[116:119], v[186:189], v[202:205], v[116:119]
	v_mfma_f32_16x16x32_bf16 v[112:115], v[194:197], v[202:205], v[112:115]
	v_mfma_f32_16x16x32_bf16 v[100:103], v[186:189], v[210:213], v[100:103]
	v_mfma_f32_16x16x32_bf16 v[96:99], v[194:197], v[210:213], v[96:99]
	v_mfma_f32_16x16x32_bf16 v[84:87], v[186:189], v[218:221], v[84:87]
	v_mfma_f32_16x16x32_bf16 v[80:83], v[194:197], v[218:221], v[80:83]
	v_mfma_f32_16x16x32_bf16 v[68:71], v[186:189], v[230:233], v[68:71]
	v_mfma_f32_16x16x32_bf16 v[64:67], v[194:197], v[230:233], v[64:67]
	s_setprio 0
	s_barrier
	s_add_i32 s3, s3, s25
	s_add_u32 s36, s80, 0x80
	s_addc_u32 s37, s81, 0
	s_mov_b32 m0, s3
	ds_read_b128 v[198:201], v175 offset:49152
	ds_read_b128 v[202:205], v175 offset:50176
	ds_read_b128 v[206:209], v175 offset:51200
	ds_read_b128 v[210:213], v175 offset:52224
	ds_read_b128 v[214:217], v175 offset:53248
	ds_read_b128 v[218:221], v175 offset:54272
	ds_read_b128 v[222:225], v175 offset:55296
	ds_read_b128 v[230:233], v175 offset:56320
	global_load_lds_dwordx4 v138, s[36:37]
	s_add_i32 m0, s3, 0x2000
	s_add_i32 s3, s27, s25
	global_load_lds_dwordx4 v142, s[36:37]
	s_add_u32 s36, s36, 0x80000
	s_addc_u32 s37, s37, 0
	s_mov_b32 m0, s3
	s_nop 0
	global_load_lds_dwordx4 v138, s[36:37]
	s_add_i32 m0, s3, 0x2000
	s_nop 0
	global_load_lds_dwordx4 v142, s[36:37]
	s_add_u32 vcc_lo, vcc_lo, 0x80
	s_addc_u32 vcc_hi, vcc_hi, 0
	s_mov_b32 m0, s78
	s_nop 0
	global_load_lds_dwordx4 v136, vcc
	s_mov_b32 m0, s56
	s_nop 0
	global_load_lds_dwordx4 v140, vcc
	s_waitcnt vmcnt(8)
	s_waitcnt lgkmcnt(0)
	s_barrier
	s_setprio 1
	s_waitcnt lgkmcnt(0)
	v_mfma_f32_16x16x32_bf16 v[60:63], v[128:131], v[198:201], v[60:63]
	v_mfma_f32_16x16x32_bf16 v[56:59], v[158:161], v[198:201], v[56:59]
	v_mfma_f32_16x16x32_bf16 v[44:47], v[128:131], v[206:209], v[44:47]
	v_mfma_f32_16x16x32_bf16 v[40:43], v[158:161], v[206:209], v[40:43]
	v_mfma_f32_16x16x32_bf16 v[28:31], v[128:131], v[214:217], v[28:31]
	v_mfma_f32_16x16x32_bf16 v[24:27], v[158:161], v[214:217], v[24:27]
	v_mfma_f32_16x16x32_bf16 v[12:15], v[128:131], v[222:225], v[12:15]
	v_mfma_f32_16x16x32_bf16 v[8:11], v[158:161], v[222:225], v[8:11]
	v_mfma_f32_16x16x32_bf16 v[60:63], v[132:135], v[202:205], v[60:63]
	v_mfma_f32_16x16x32_bf16 v[56:59], v[178:181], v[202:205], v[56:59]
	v_mfma_f32_16x16x32_bf16 v[44:47], v[132:135], v[210:213], v[44:47]
	v_mfma_f32_16x16x32_bf16 v[40:43], v[178:181], v[210:213], v[40:43]
	v_mfma_f32_16x16x32_bf16 v[28:31], v[132:135], v[218:221], v[28:31]
	v_mfma_f32_16x16x32_bf16 v[24:27], v[178:181], v[218:221], v[24:27]
	v_mfma_f32_16x16x32_bf16 v[12:15], v[132:135], v[230:233], v[12:15]
	v_mfma_f32_16x16x32_bf16 v[8:11], v[178:181], v[230:233], v[8:11]
	v_mfma_f32_16x16x32_bf16 v[52:55], v[182:185], v[198:201], v[52:55]
	v_mfma_f32_16x16x32_bf16 v[48:51], v[190:193], v[198:201], v[48:51]
	v_mfma_f32_16x16x32_bf16 v[36:39], v[182:185], v[206:209], v[36:39]
	v_mfma_f32_16x16x32_bf16 v[32:35], v[190:193], v[206:209], v[32:35]
	v_mfma_f32_16x16x32_bf16 v[20:23], v[182:185], v[214:217], v[20:23]
	v_mfma_f32_16x16x32_bf16 v[16:19], v[190:193], v[214:217], v[16:19]
	v_mfma_f32_16x16x32_bf16 v[4:7], v[182:185], v[222:225], v[4:7]
	v_mfma_f32_16x16x32_bf16 v[0:3], v[190:193], v[222:225], v[0:3]
	v_mfma_f32_16x16x32_bf16 v[52:55], v[186:189], v[202:205], v[52:55]
	v_mfma_f32_16x16x32_bf16 v[48:51], v[194:197], v[202:205], v[48:51]
	v_mfma_f32_16x16x32_bf16 v[36:39], v[186:189], v[210:213], v[36:39]
	v_mfma_f32_16x16x32_bf16 v[32:35], v[194:197], v[210:213], v[32:35]
	v_mfma_f32_16x16x32_bf16 v[20:23], v[186:189], v[218:221], v[20:23]
	v_mfma_f32_16x16x32_bf16 v[16:19], v[194:197], v[218:221], v[16:19]
	v_mfma_f32_16x16x32_bf16 v[4:7], v[186:189], v[230:233], v[4:7]
	v_mfma_f32_16x16x32_bf16 v[0:3], v[194:197], v[230:233], v[0:3]
	s_setprio 0
	s_add_i32 s24, s24, 2
	s_add_u32 s34, s34, 0x100
	s_addc_u32 s35, s35, 0
	s_add_u32 s18, s18, 0x100
	s_addc_u32 s19, s19, 0
	s_cmp_gt_u32 s24, 29
	s_barrier
	s_cbranch_scc0 .LBB0_919
	s_and_b64 vcc, exec, s[86:87]
	s_cbranch_vccz .LBB0_922
	s_barrier

.LBB0_1393:
	ds_read_b128 v[144:147], v153
	ds_read_b128 v[156:159], v153 offset:1024
	ds_read_b128 v[160:163], v153 offset:2048
	ds_read_b128 v[164:167], v153 offset:3072
	ds_read_b128 v[168:171], v154
	ds_read_b128 v[172:175], v154 offset:1024
	ds_read_b128 v[176:179], v154 offset:2048
	ds_read_b128 v[180:183], v154 offset:3072
	s_add_u32 s3, s88, 0xfffc0080
	s_addc_u32 s37, s89, -1
	s_cmp_eq_u32 s36, 12
	s_cselect_b32 s91, s0, s37
	s_cselect_b32 s90, s1, s3
	s_cselect_b32 s81, s17, s35
	s_cselect_b32 s80, s27, s33
	s_add_i32 m0, s19, 0xc000
	ds_read_b128 v[184:187], v155
	ds_read_b128 v[188:191], v155 offset:1024
	ds_read_b128 v[192:195], v155 offset:2048
	ds_read_b128 v[196:199], v155 offset:3072
	ds_read_b128 v[200:203], v155 offset:4096
	ds_read_b128 v[204:207], v155 offset:5120
	ds_read_b128 v[208:211], v155 offset:6144
	ds_read_b128 v[212:215], v155 offset:7168
	global_load_lds_dwordx4 v136, s[88:89]
	s_add_i32 m0, s19, 0xe000
	s_nop 0
	global_load_lds_dwordx4 v138, s[88:89]
	s_waitcnt vmcnt(8)
	s_waitcnt lgkmcnt(0)
	s_barrier
	s_setprio 1
	s_waitcnt lgkmcnt(0)
	v_mfma_f32_16x16x32_bf16 v[124:127], v[144:147], v[184:187], v[124:127]
	v_mfma_f32_16x16x32_bf16 v[120:123], v[160:163], v[184:187], v[120:123]
	v_mfma_f32_16x16x32_bf16 v[108:111], v[144:147], v[192:195], v[108:111]
	v_mfma_f32_16x16x32_bf16 v[104:107], v[160:163], v[192:195], v[104:107]
	v_mfma_f32_16x16x32_bf16 v[92:95], v[144:147], v[200:203], v[92:95]
	v_mfma_f32_16x16x32_bf16 v[88:91], v[160:163], v[200:203], v[88:91]
	v_mfma_f32_16x16x32_bf16 v[76:79], v[144:147], v[208:211], v[76:79]
	v_mfma_f32_16x16x32_bf16 v[72:75], v[160:163], v[208:211], v[72:75]
	v_mfma_f32_16x16x32_bf16 v[124:127], v[156:159], v[188:191], v[124:127]
	v_mfma_f32_16x16x32_bf16 v[120:123], v[164:167], v[188:191], v[120:123]
	v_mfma_f32_16x16x32_bf16 v[108:111], v[156:159], v[196:199], v[108:111]
	v_mfma_f32_16x16x32_bf16 v[104:107], v[164:167], v[196:199], v[104:107]
	v_mfma_f32_16x16x32_bf16 v[92:95], v[156:159], v[204:207], v[92:95]
	v_mfma_f32_16x16x32_bf16 v[88:91], v[164:167], v[204:207], v[88:91]
	v_mfma_f32_16x16x32_bf16 v[76:79], v[156:159], v[212:215], v[76:79]
	v_mfma_f32_16x16x32_bf16 v[72:75], v[164:167], v[212:215], v[72:75]
	v_mfma_f32_16x16x32_bf16 v[116:119], v[168:171], v[184:187], v[116:119]
	v_mfma_f32_16x16x32_bf16 v[112:115], v[176:179], v[184:187], v[112:115]
	v_mfma_f32_16x16x32_bf16 v[100:103], v[168:171], v[192:195], v[100:103]
	v_mfma_f32_16x16x32_bf16 v[96:99], v[176:179], v[192:195], v[96:99]
	v_mfma_f32_16x16x32_bf16 v[84:87], v[168:171], v[200:203], v[84:87]
	v_mfma_f32_16x16x32_bf16 v[80:83], v[176:179], v[200:203], v[80:83]
	v_mfma_f32_16x16x32_bf16 v[68:71], v[168:171], v[208:211], v[68:71]
	v_mfma_f32_16x16x32_bf16 v[64:67], v[176:179], v[208:211], v[64:67]
	v_mfma_f32_16x16x32_bf16 v[116:119], v[172:175], v[188:191], v[116:119]
	v_mfma_f32_16x16x32_bf16 v[112:115], v[180:183], v[188:191], v[112:115]
	v_mfma_f32_16x16x32_bf16 v[100:103], v[172:175], v[196:199], v[100:103]
	v_mfma_f32_16x16x32_bf16 v[96:99], v[180:183], v[196:199], v[96:99]
	v_mfma_f32_16x16x32_bf16 v[84:87], v[172:175], v[204:207], v[84:87]
	v_mfma_f32_16x16x32_bf16 v[80:83], v[180:183], v[204:207], v[80:83]
	v_mfma_f32_16x16x32_bf16 v[68:71], v[172:175], v[212:215], v[68:71]
	v_mfma_f32_16x16x32_bf16 v[64:67], v[180:183], v[212:215], v[64:67]
	s_setprio 0
	s_barrier
	s_add_i32 s3, s57, s18
	s_mov_b32 m0, s3
	ds_read_b128 v[184:187], v155 offset:16384
	ds_read_b128 v[188:191], v155 offset:17408
	ds_read_b128 v[192:195], v155 offset:18432
	ds_read_b128 v[196:199], v155 offset:19456
	ds_read_b128 v[200:203], v155 offset:20480
	ds_read_b128 v[204:207], v155 offset:21504
	ds_read_b128 v[208:211], v155 offset:22528
	ds_read_b128 v[212:215], v155 offset:23552
	global_load_lds_dwordx4 v130, s[80:81]
	s_add_i32 m0, s3, 0x2000
	s_add_u32 s42, s80, 0x40000
	s_addc_u32 s43, s81, 0
	s_add_i32 s3, s58, s18
	global_load_lds_dwordx4 v134, s[80:81]
	s_mov_b32 m0, s3
	s_nop 0
	global_load_lds_dwordx4 v130, s[42:43]
	s_add_i32 m0, s3, 0x2000
	s_nop 0
	global_load_lds_dwordx4 v134, s[42:43]
	s_mov_b32 m0, s19
	s_nop 0
	global_load_lds_dwordx4 v128, s[90:91]
	s_mov_b32 m0, s25
	s_nop 0
	global_load_lds_dwordx4 v132, s[90:91]
	s_waitcnt vmcnt(8)
	s_waitcnt lgkmcnt(0)
	s_barrier
	s_setprio 1
	s_waitcnt lgkmcnt(0)
	v_mfma_f32_16x16x32_bf16 v[60:63], v[144:147], v[184:187], v[60:63]
	v_mfma_f32_16x16x32_bf16 v[56:59], v[160:163], v[184:187], v[56:59]
	v_mfma_f32_16x16x32_bf16 v[44:47], v[144:147], v[192:195], v[44:47]
	v_mfma_f32_16x16x32_bf16 v[40:43], v[160:163], v[192:195], v[40:43]
	v_mfma_f32_16x16x32_bf16 v[28:31], v[144:147], v[200:203], v[28:31]
	v_mfma_f32_16x16x32_bf16 v[24:27], v[160:163], v[200:203], v[24:27]
	v_mfma_f32_16x16x32_bf16 v[12:15], v[144:147], v[208:211], v[12:15]
	v_mfma_f32_16x16x32_bf16 v[8:11], v[160:163], v[208:211], v[8:11]
	v_mfma_f32_16x16x32_bf16 v[60:63], v[156:159], v[188:191], v[60:63]
	v_mfma_f32_16x16x32_bf16 v[56:59], v[164:167], v[188:191], v[56:59]
	v_mfma_f32_16x16x32_bf16 v[44:47], v[156:159], v[196:199], v[44:47]
	v_mfma_f32_16x16x32_bf16 v[40:43], v[164:167], v[196:199], v[40:43]
	v_mfma_f32_16x16x32_bf16 v[28:31], v[156:159], v[204:207], v[28:31]
	v_mfma_f32_16x16x32_bf16 v[24:27], v[164:167], v[204:207], v[24:27]
	v_mfma_f32_16x16x32_bf16 v[12:15], v[156:159], v[212:215], v[12:15]
	v_mfma_f32_16x16x32_bf16 v[8:11], v[164:167], v[212:215], v[8:11]
	v_mfma_f32_16x16x32_bf16 v[52:55], v[168:171], v[184:187], v[52:55]
	v_mfma_f32_16x16x32_bf16 v[48:51], v[176:179], v[184:187], v[48:51]
	v_mfma_f32_16x16x32_bf16 v[36:39], v[168:171], v[192:195], v[36:39]
	v_mfma_f32_16x16x32_bf16 v[32:35], v[176:179], v[192:195], v[32:35]
	v_mfma_f32_16x16x32_bf16 v[20:23], v[168:171], v[200:203], v[20:23]
	v_mfma_f32_16x16x32_bf16 v[16:19], v[176:179], v[200:203], v[16:19]
	v_mfma_f32_16x16x32_bf16 v[4:7], v[168:171], v[208:211], v[4:7]
	v_mfma_f32_16x16x32_bf16 v[0:3], v[176:179], v[208:211], v[0:3]
	v_mfma_f32_16x16x32_bf16 v[52:55], v[172:175], v[188:191], v[52:55]
	v_mfma_f32_16x16x32_bf16 v[48:51], v[180:183], v[188:191], v[48:51]
	v_mfma_f32_16x16x32_bf16 v[36:39], v[172:175], v[196:199], v[36:39]
	v_mfma_f32_16x16x32_bf16 v[32:35], v[180:183], v[196:199], v[32:35]
	v_mfma_f32_16x16x32_bf16 v[20:23], v[172:175], v[204:207], v[20:23]
	v_mfma_f32_16x16x32_bf16 v[16:19], v[180:183], v[204:207], v[16:19]
	v_mfma_f32_16x16x32_bf16 v[4:7], v[172:175], v[212:215], v[4:7]
	v_mfma_f32_16x16x32_bf16 v[0:3], v[180:183], v[212:215], v[0:3]
	s_setprio 0
	s_barrier
	s_add_i32 s3, 0, 0x18000
	s_add_i32 s37, 0, 0x1c000
	v_add_u32_e32 v164, s3, v151
	v_add_u32_e32 v180, s37, v151
	ds_read_b128 v[144:147], v164
	ds_read_b128 v[156:159], v164 offset:1024
	ds_read_b128 v[160:163], v164 offset:2048
	ds_read_b128 v[164:167], v164 offset:3072
	ds_read_b128 v[168:171], v180
	ds_read_b128 v[172:175], v180 offset:1024
	ds_read_b128 v[176:179], v180 offset:2048
	ds_read_b128 v[180:183], v180 offset:3072
	s_add_u32 s42, s90, 0x40000
	s_addc_u32 s43, s91, 0
	s_mov_b32 m0, s30
	ds_read_b128 v[184:187], v155 offset:32768
	ds_read_b128 v[188:191], v155 offset:33792
	ds_read_b128 v[192:195], v155 offset:34816
	ds_read_b128 v[196:199], v155 offset:35840
	ds_read_b128 v[200:203], v155 offset:36864
	ds_read_b128 v[204:207], v155 offset:37888
	ds_read_b128 v[208:211], v155 offset:38912
	ds_read_b128 v[212:215], v155 offset:39936
	global_load_lds_dwordx4 v128, s[42:43]
	v_lshl_add_u64 v[222:223], s[42:43], 0, v[132:133]
	s_mov_b32 m0, s31
	s_nop 0
	global_load_lds_dwordx4 v[222:223], off
	s_waitcnt vmcnt(8)
	s_waitcnt lgkmcnt(0)
	s_barrier
	s_setprio 1
	s_waitcnt lgkmcnt(0)
	v_mfma_f32_16x16x32_bf16 v[124:127], v[144:147], v[184:187], v[124:127]
	v_mfma_f32_16x16x32_bf16 v[120:123], v[160:163], v[184:187], v[120:123]
	v_mfma_f32_16x16x32_bf16 v[108:111], v[144:147], v[192:195], v[108:111]
	v_mfma_f32_16x16x32_bf16 v[104:107], v[160:163], v[192:195], v[104:107]
	v_mfma_f32_16x16x32_bf16 v[92:95], v[144:147], v[200:203], v[92:95]
	v_mfma_f32_16x16x32_bf16 v[88:91], v[160:163], v[200:203], v[88:91]
	v_mfma_f32_16x16x32_bf16 v[76:79], v[144:147], v[208:211], v[76:79]
	v_mfma_f32_16x16x32_bf16 v[72:75], v[160:163], v[208:211], v[72:75]
	v_mfma_f32_16x16x32_bf16 v[124:127], v[156:159], v[188:191], v[124:127]
	v_mfma_f32_16x16x32_bf16 v[120:123], v[164:167], v[188:191], v[120:123]
	v_mfma_f32_16x16x32_bf16 v[108:111], v[156:159], v[196:199], v[108:111]
	v_mfma_f32_16x16x32_bf16 v[104:107], v[164:167], v[196:199], v[104:107]
	v_mfma_f32_16x16x32_bf16 v[92:95], v[156:159], v[204:207], v[92:95]
	v_mfma_f32_16x16x32_bf16 v[88:91], v[164:167], v[204:207], v[88:91]
	v_mfma_f32_16x16x32_bf16 v[76:79], v[156:159], v[212:215], v[76:79]
	v_mfma_f32_16x16x32_bf16 v[72:75], v[164:167], v[212:215], v[72:75]
	v_mfma_f32_16x16x32_bf16 v[116:119], v[168:171], v[184:187], v[116:119]
	v_mfma_f32_16x16x32_bf16 v[112:115], v[176:179], v[184:187], v[112:115]
	v_mfma_f32_16x16x32_bf16 v[100:103], v[168:171], v[192:195], v[100:103]
	v_mfma_f32_16x16x32_bf16 v[96:99], v[176:179], v[192:195], v[96:99]
	v_mfma_f32_16x16x32_bf16 v[84:87], v[168:171], v[200:203], v[84:87]
	v_mfma_f32_16x16x32_bf16 v[80:83], v[176:179], v[200:203], v[80:83]
	v_mfma_f32_16x16x32_bf16 v[68:71], v[168:171], v[208:211], v[68:71]
	v_mfma_f32_16x16x32_bf16 v[64:67], v[176:179], v[208:211], v[64:67]
	v_mfma_f32_16x16x32_bf16 v[116:119], v[172:175], v[188:191], v[116:119]
	v_mfma_f32_16x16x32_bf16 v[112:115], v[180:183], v[188:191], v[112:115]
	v_mfma_f32_16x16x32_bf16 v[100:103], v[172:175], v[196:199], v[100:103]
	v_mfma_f32_16x16x32_bf16 v[96:99], v[180:183], v[196:199], v[96:99]
	v_mfma_f32_16x16x32_bf16 v[84:87], v[172:175], v[204:207], v[84:87]
	v_mfma_f32_16x16x32_bf16 v[80:83], v[180:183], v[204:207], v[80:83]
	v_mfma_f32_16x16x32_bf16 v[68:71], v[172:175], v[212:215], v[68:71]
	v_mfma_f32_16x16x32_bf16 v[64:67], v[180:183], v[212:215], v[64:67]
	s_setprio 0
	s_barrier
	s_add_i32 s3, s3, s18
	s_add_u32 s42, s80, 0x80
	s_addc_u32 s43, s81, 0
	s_mov_b32 m0, s3
	ds_read_b128 v[184:187], v155 offset:49152
	ds_read_b128 v[188:191], v155 offset:50176
	ds_read_b128 v[192:195], v155 offset:51200
	ds_read_b128 v[196:199], v155 offset:52224
	ds_read_b128 v[200:203], v155 offset:53248
	ds_read_b128 v[204:207], v155 offset:54272
	ds_read_b128 v[208:211], v155 offset:55296
	ds_read_b128 v[212:215], v155 offset:56320
	global_load_lds_dwordx4 v130, s[42:43]
	s_add_i32 m0, s3, 0x2000
	s_add_i32 s3, s37, s18
	global_load_lds_dwordx4 v134, s[42:43]
	s_add_u32 s42, s42, 0x40000
	s_addc_u32 s43, s43, 0
	s_mov_b32 m0, s3
	s_nop 0
	global_load_lds_dwordx4 v130, s[42:43]
	s_add_i32 m0, s3, 0x2000
	s_nop 0
	global_load_lds_dwordx4 v134, s[42:43]
	s_add_u32 s90, s90, 0x80
	s_addc_u32 s91, s91, 0
	s_mov_b32 m0, s53
	s_nop 0
	global_load_lds_dwordx4 v128, s[90:91]
	s_mov_b32 m0, s56
	s_nop 0
	global_load_lds_dwordx4 v132, s[90:91]
	s_waitcnt vmcnt(8)
	s_waitcnt lgkmcnt(0)
	s_barrier
	s_setprio 1
	s_waitcnt lgkmcnt(0)
	v_mfma_f32_16x16x32_bf16 v[60:63], v[144:147], v[184:187], v[60:63]
	v_mfma_f32_16x16x32_bf16 v[56:59], v[160:163], v[184:187], v[56:59]
	v_mfma_f32_16x16x32_bf16 v[44:47], v[144:147], v[192:195], v[44:47]
	v_mfma_f32_16x16x32_bf16 v[40:43], v[160:163], v[192:195], v[40:43]
	v_mfma_f32_16x16x32_bf16 v[28:31], v[144:147], v[200:203], v[28:31]
	v_mfma_f32_16x16x32_bf16 v[24:27], v[160:163], v[200:203], v[24:27]
	v_mfma_f32_16x16x32_bf16 v[12:15], v[144:147], v[208:211], v[12:15]
	v_mfma_f32_16x16x32_bf16 v[8:11], v[160:163], v[208:211], v[8:11]
	v_mfma_f32_16x16x32_bf16 v[60:63], v[156:159], v[188:191], v[60:63]
	v_mfma_f32_16x16x32_bf16 v[56:59], v[164:167], v[188:191], v[56:59]
	v_mfma_f32_16x16x32_bf16 v[44:47], v[156:159], v[196:199], v[44:47]
	v_mfma_f32_16x16x32_bf16 v[40:43], v[164:167], v[196:199], v[40:43]
	v_mfma_f32_16x16x32_bf16 v[28:31], v[156:159], v[204:207], v[28:31]
	v_mfma_f32_16x16x32_bf16 v[24:27], v[164:167], v[204:207], v[24:27]
	v_mfma_f32_16x16x32_bf16 v[12:15], v[156:159], v[212:215], v[12:15]
	v_mfma_f32_16x16x32_bf16 v[8:11], v[164:167], v[212:215], v[8:11]
	v_mfma_f32_16x16x32_bf16 v[52:55], v[168:171], v[184:187], v[52:55]
	v_mfma_f32_16x16x32_bf16 v[48:51], v[176:179], v[184:187], v[48:51]
	v_mfma_f32_16x16x32_bf16 v[36:39], v[168:171], v[192:195], v[36:39]
	v_mfma_f32_16x16x32_bf16 v[32:35], v[176:179], v[192:195], v[32:35]
	v_mfma_f32_16x16x32_bf16 v[20:23], v[168:171], v[200:203], v[20:23]
	v_mfma_f32_16x16x32_bf16 v[16:19], v[176:179], v[200:203], v[16:19]
	v_mfma_f32_16x16x32_bf16 v[4:7], v[168:171], v[208:211], v[4:7]
	v_mfma_f32_16x16x32_bf16 v[0:3], v[176:179], v[208:211], v[0:3]
	v_mfma_f32_16x16x32_bf16 v[52:55], v[172:175], v[188:191], v[52:55]
	v_mfma_f32_16x16x32_bf16 v[48:51], v[180:183], v[188:191], v[48:51]
	v_mfma_f32_16x16x32_bf16 v[36:39], v[172:175], v[196:199], v[36:39]
	v_mfma_f32_16x16x32_bf16 v[32:35], v[180:183], v[196:199], v[32:35]
	v_mfma_f32_16x16x32_bf16 v[20:23], v[172:175], v[204:207], v[20:23]
	v_mfma_f32_16x16x32_bf16 v[16:19], v[180:183], v[204:207], v[16:19]
	v_mfma_f32_16x16x32_bf16 v[4:7], v[172:175], v[212:215], v[4:7]
	v_mfma_f32_16x16x32_bf16 v[0:3], v[180:183], v[212:215], v[0:3]
	s_setprio 0
	s_add_i32 s36, s36, 2
	s_add_u32 s88, s88, 0x100
	s_addc_u32 s89, s89, 0
	s_add_u32 s33, s33, 0x100
	s_addc_u32 s35, s35, 0
	s_cmp_gt_u32 s36, 13
	s_barrier
	s_cbranch_scc0 .LBB0_1393
	s_and_b64 vcc, exec, s[12:13]
	s_cbranch_vccz .LBB0_1396
	s_barrier

.LBB0_1417:
	ds_read_b128 v[144:147], v157
	ds_read_b128 v[148:151], v157 offset:1024
	ds_read_b128 v[160:163], v157 offset:2048
	ds_read_b128 v[164:167], v157 offset:3072
	ds_read_b128 v[168:171], v158
	ds_read_b128 v[172:175], v158 offset:1024
	ds_read_b128 v[176:179], v158 offset:2048
	ds_read_b128 v[180:183], v158 offset:3072
	s_add_u32 s3, s34, 0xfffe0080
	s_addc_u32 s42, s35, -1
	s_cmp_eq_u32 s37, 4
	s_cselect_b32 s91, s0, s42
	s_cselect_b32 s90, s1, s3
	s_cselect_b32 s81, s24, s36
	s_cselect_b32 s80, s27, s33
	s_add_i32 m0, s19, 0xc000
	ds_read_b128 v[184:187], v159
	ds_read_b128 v[188:191], v159 offset:1024
	ds_read_b128 v[192:195], v159 offset:2048
	ds_read_b128 v[196:199], v159 offset:3072
	ds_read_b128 v[200:203], v159 offset:4096
	ds_read_b128 v[204:207], v159 offset:5120
	ds_read_b128 v[208:211], v159 offset:6144
	ds_read_b128 v[212:215], v159 offset:7168
	global_load_lds_dwordx4 v136, s[34:35]
	s_add_i32 m0, s19, 0xe000
	s_nop 0
	global_load_lds_dwordx4 v138, s[34:35]
	s_waitcnt vmcnt(8)
	s_waitcnt lgkmcnt(0)
	s_barrier
	s_setprio 1
	s_waitcnt lgkmcnt(0)
	v_mfma_f32_16x16x32_bf16 v[124:127], v[144:147], v[184:187], v[124:127]
	v_mfma_f32_16x16x32_bf16 v[120:123], v[160:163], v[184:187], v[120:123]
	v_mfma_f32_16x16x32_bf16 v[108:111], v[144:147], v[192:195], v[108:111]
	v_mfma_f32_16x16x32_bf16 v[104:107], v[160:163], v[192:195], v[104:107]
	v_mfma_f32_16x16x32_bf16 v[92:95], v[144:147], v[200:203], v[92:95]
	v_mfma_f32_16x16x32_bf16 v[88:91], v[160:163], v[200:203], v[88:91]
	v_mfma_f32_16x16x32_bf16 v[76:79], v[144:147], v[208:211], v[76:79]
	v_mfma_f32_16x16x32_bf16 v[72:75], v[160:163], v[208:211], v[72:75]
	v_mfma_f32_16x16x32_bf16 v[124:127], v[148:151], v[188:191], v[124:127]
	v_mfma_f32_16x16x32_bf16 v[120:123], v[164:167], v[188:191], v[120:123]
	v_mfma_f32_16x16x32_bf16 v[108:111], v[148:151], v[196:199], v[108:111]
	v_mfma_f32_16x16x32_bf16 v[104:107], v[164:167], v[196:199], v[104:107]
	v_mfma_f32_16x16x32_bf16 v[92:95], v[148:151], v[204:207], v[92:95]
	v_mfma_f32_16x16x32_bf16 v[88:91], v[164:167], v[204:207], v[88:91]
	v_mfma_f32_16x16x32_bf16 v[76:79], v[148:151], v[212:215], v[76:79]
	v_mfma_f32_16x16x32_bf16 v[72:75], v[164:167], v[212:215], v[72:75]
	v_mfma_f32_16x16x32_bf16 v[116:119], v[168:171], v[184:187], v[116:119]
	v_mfma_f32_16x16x32_bf16 v[112:115], v[176:179], v[184:187], v[112:115]
	v_mfma_f32_16x16x32_bf16 v[100:103], v[168:171], v[192:195], v[100:103]
	v_mfma_f32_16x16x32_bf16 v[96:99], v[176:179], v[192:195], v[96:99]
	v_mfma_f32_16x16x32_bf16 v[84:87], v[168:171], v[200:203], v[84:87]
	v_mfma_f32_16x16x32_bf16 v[80:83], v[176:179], v[200:203], v[80:83]
	v_mfma_f32_16x16x32_bf16 v[68:71], v[168:171], v[208:211], v[68:71]
	v_mfma_f32_16x16x32_bf16 v[64:67], v[176:179], v[208:211], v[64:67]
	v_mfma_f32_16x16x32_bf16 v[116:119], v[172:175], v[188:191], v[116:119]
	v_mfma_f32_16x16x32_bf16 v[112:115], v[180:183], v[188:191], v[112:115]
	v_mfma_f32_16x16x32_bf16 v[100:103], v[172:175], v[196:199], v[100:103]
	v_mfma_f32_16x16x32_bf16 v[96:99], v[180:183], v[196:199], v[96:99]
	v_mfma_f32_16x16x32_bf16 v[84:87], v[172:175], v[204:207], v[84:87]
	v_mfma_f32_16x16x32_bf16 v[80:83], v[180:183], v[204:207], v[80:83]
	v_mfma_f32_16x16x32_bf16 v[68:71], v[172:175], v[212:215], v[68:71]
	v_mfma_f32_16x16x32_bf16 v[64:67], v[180:183], v[212:215], v[64:67]
	s_setprio 0
	s_barrier
	s_add_i32 s3, s78, s18
	s_mov_b32 m0, s3
	ds_read_b128 v[184:187], v159 offset:16384
	ds_read_b128 v[188:191], v159 offset:17408
	ds_read_b128 v[192:195], v159 offset:18432
	ds_read_b128 v[196:199], v159 offset:19456
	ds_read_b128 v[200:203], v159 offset:20480
	ds_read_b128 v[204:207], v159 offset:21504
	ds_read_b128 v[208:211], v159 offset:22528
	ds_read_b128 v[212:215], v159 offset:23552
	global_load_lds_dwordx4 v130, s[80:81]
	s_add_i32 m0, s3, 0x2000
	s_add_u32 s42, s80, 0x20000
	s_addc_u32 s43, s81, 0
	s_add_i32 s3, s79, s18
	global_load_lds_dwordx4 v134, s[80:81]
	s_mov_b32 m0, s3
	s_nop 0
	global_load_lds_dwordx4 v130, s[42:43]
	s_add_i32 m0, s3, 0x2000
	s_nop 0
	global_load_lds_dwordx4 v134, s[42:43]
	s_mov_b32 m0, s19
	s_nop 0
	global_load_lds_dwordx4 v128, s[90:91]
	s_mov_b32 m0, s25
	s_nop 0
	global_load_lds_dwordx4 v132, s[90:91]
	s_waitcnt vmcnt(8)
	s_waitcnt lgkmcnt(0)
	s_barrier
	s_setprio 1
	s_waitcnt lgkmcnt(0)
	v_mfma_f32_16x16x32_bf16 v[60:63], v[144:147], v[184:187], v[60:63]
	v_mfma_f32_16x16x32_bf16 v[56:59], v[160:163], v[184:187], v[56:59]
	v_mfma_f32_16x16x32_bf16 v[44:47], v[144:147], v[192:195], v[44:47]
	v_mfma_f32_16x16x32_bf16 v[40:43], v[160:163], v[192:195], v[40:43]
	v_mfma_f32_16x16x32_bf16 v[28:31], v[144:147], v[200:203], v[28:31]
	v_mfma_f32_16x16x32_bf16 v[24:27], v[160:163], v[200:203], v[24:27]
	v_mfma_f32_16x16x32_bf16 v[12:15], v[144:147], v[208:211], v[12:15]
	v_mfma_f32_16x16x32_bf16 v[8:11], v[160:163], v[208:211], v[8:11]
	v_mfma_f32_16x16x32_bf16 v[60:63], v[148:151], v[188:191], v[60:63]
	v_mfma_f32_16x16x32_bf16 v[56:59], v[164:167], v[188:191], v[56:59]
	v_mfma_f32_16x16x32_bf16 v[44:47], v[148:151], v[196:199], v[44:47]
	v_mfma_f32_16x16x32_bf16 v[40:43], v[164:167], v[196:199], v[40:43]
	v_mfma_f32_16x16x32_bf16 v[28:31], v[148:151], v[204:207], v[28:31]
	v_mfma_f32_16x16x32_bf16 v[24:27], v[164:167], v[204:207], v[24:27]
	v_mfma_f32_16x16x32_bf16 v[12:15], v[148:151], v[212:215], v[12:15]
	v_mfma_f32_16x16x32_bf16 v[8:11], v[164:167], v[212:215], v[8:11]
	v_mfma_f32_16x16x32_bf16 v[52:55], v[168:171], v[184:187], v[52:55]
	v_mfma_f32_16x16x32_bf16 v[48:51], v[176:179], v[184:187], v[48:51]
	v_mfma_f32_16x16x32_bf16 v[36:39], v[168:171], v[192:195], v[36:39]
	v_mfma_f32_16x16x32_bf16 v[32:35], v[176:179], v[192:195], v[32:35]
	v_mfma_f32_16x16x32_bf16 v[20:23], v[168:171], v[200:203], v[20:23]
	v_mfma_f32_16x16x32_bf16 v[16:19], v[176:179], v[200:203], v[16:19]
	v_mfma_f32_16x16x32_bf16 v[4:7], v[168:171], v[208:211], v[4:7]
	v_mfma_f32_16x16x32_bf16 v[0:3], v[176:179], v[208:211], v[0:3]
	v_mfma_f32_16x16x32_bf16 v[52:55], v[172:175], v[188:191], v[52:55]
	v_mfma_f32_16x16x32_bf16 v[48:51], v[180:183], v[188:191], v[48:51]
	v_mfma_f32_16x16x32_bf16 v[36:39], v[172:175], v[196:199], v[36:39]
	v_mfma_f32_16x16x32_bf16 v[32:35], v[180:183], v[196:199], v[32:35]
	v_mfma_f32_16x16x32_bf16 v[20:23], v[172:175], v[204:207], v[20:23]
	v_mfma_f32_16x16x32_bf16 v[16:19], v[180:183], v[204:207], v[16:19]
	v_mfma_f32_16x16x32_bf16 v[4:7], v[172:175], v[212:215], v[4:7]
	v_mfma_f32_16x16x32_bf16 v[0:3], v[180:183], v[212:215], v[0:3]
	s_setprio 0
	s_barrier
	s_add_i32 s3, 0, 0x18000
	s_add_i32 s44, 0, 0x1c000
	v_add_u32_e32 v164, s3, v155
	v_add_u32_e32 v180, s44, v155
	ds_read_b128 v[144:147], v164
	ds_read_b128 v[148:151], v164 offset:1024
	ds_read_b128 v[160:163], v164 offset:2048
	ds_read_b128 v[164:167], v164 offset:3072
	ds_read_b128 v[168:171], v180
	ds_read_b128 v[172:175], v180 offset:1024
	ds_read_b128 v[176:179], v180 offset:2048
	ds_read_b128 v[180:183], v180 offset:3072
	s_add_u32 s42, s90, 0x20000
	s_addc_u32 s43, s91, 0
	s_mov_b32 m0, s30
	ds_read_b128 v[184:187], v159 offset:32768
	ds_read_b128 v[188:191], v159 offset:33792
	ds_read_b128 v[192:195], v159 offset:34816
	ds_read_b128 v[196:199], v159 offset:35840
	ds_read_b128 v[200:203], v159 offset:36864
	ds_read_b128 v[204:207], v159 offset:37888
	ds_read_b128 v[208:211], v159 offset:38912
	ds_read_b128 v[212:215], v159 offset:39936
	global_load_lds_dwordx4 v128, s[42:43]
	v_lshl_add_u64 v[222:223], s[42:43], 0, v[132:133]
	s_mov_b32 m0, s31
	s_nop 0
	global_load_lds_dwordx4 v[222:223], off
	s_waitcnt vmcnt(8)
	s_waitcnt lgkmcnt(0)
	s_barrier
	s_setprio 1
	s_waitcnt lgkmcnt(0)
	v_mfma_f32_16x16x32_bf16 v[124:127], v[144:147], v[184:187], v[124:127]
	v_mfma_f32_16x16x32_bf16 v[120:123], v[160:163], v[184:187], v[120:123]
	v_mfma_f32_16x16x32_bf16 v[108:111], v[144:147], v[192:195], v[108:111]
	v_mfma_f32_16x16x32_bf16 v[104:107], v[160:163], v[192:195], v[104:107]
	v_mfma_f32_16x16x32_bf16 v[92:95], v[144:147], v[200:203], v[92:95]
	v_mfma_f32_16x16x32_bf16 v[88:91], v[160:163], v[200:203], v[88:91]
	v_mfma_f32_16x16x32_bf16 v[76:79], v[144:147], v[208:211], v[76:79]
	v_mfma_f32_16x16x32_bf16 v[72:75], v[160:163], v[208:211], v[72:75]
	v_mfma_f32_16x16x32_bf16 v[124:127], v[148:151], v[188:191], v[124:127]
	v_mfma_f32_16x16x32_bf16 v[120:123], v[164:167], v[188:191], v[120:123]
	v_mfma_f32_16x16x32_bf16 v[108:111], v[148:151], v[196:199], v[108:111]
	v_mfma_f32_16x16x32_bf16 v[104:107], v[164:167], v[196:199], v[104:107]
	v_mfma_f32_16x16x32_bf16 v[92:95], v[148:151], v[204:207], v[92:95]
	v_mfma_f32_16x16x32_bf16 v[88:91], v[164:167], v[204:207], v[88:91]
	v_mfma_f32_16x16x32_bf16 v[76:79], v[148:151], v[212:215], v[76:79]
	v_mfma_f32_16x16x32_bf16 v[72:75], v[164:167], v[212:215], v[72:75]
	v_mfma_f32_16x16x32_bf16 v[116:119], v[168:171], v[184:187], v[116:119]
	v_mfma_f32_16x16x32_bf16 v[112:115], v[176:179], v[184:187], v[112:115]
	v_mfma_f32_16x16x32_bf16 v[100:103], v[168:171], v[192:195], v[100:103]
	v_mfma_f32_16x16x32_bf16 v[96:99], v[176:179], v[192:195], v[96:99]
	v_mfma_f32_16x16x32_bf16 v[84:87], v[168:171], v[200:203], v[84:87]
	v_mfma_f32_16x16x32_bf16 v[80:83], v[176:179], v[200:203], v[80:83]
	v_mfma_f32_16x16x32_bf16 v[68:71], v[168:171], v[208:211], v[68:71]
	v_mfma_f32_16x16x32_bf16 v[64:67], v[176:179], v[208:211], v[64:67]
	v_mfma_f32_16x16x32_bf16 v[116:119], v[172:175], v[188:191], v[116:119]
	v_mfma_f32_16x16x32_bf16 v[112:115], v[180:183], v[188:191], v[112:115]
	v_mfma_f32_16x16x32_bf16 v[100:103], v[172:175], v[196:199], v[100:103]
	v_mfma_f32_16x16x32_bf16 v[96:99], v[180:183], v[196:199], v[96:99]
	v_mfma_f32_16x16x32_bf16 v[84:87], v[172:175], v[204:207], v[84:87]
	v_mfma_f32_16x16x32_bf16 v[80:83], v[180:183], v[204:207], v[80:83]
	v_mfma_f32_16x16x32_bf16 v[68:71], v[172:175], v[212:215], v[68:71]
	v_mfma_f32_16x16x32_bf16 v[64:67], v[180:183], v[212:215], v[64:67]
	s_setprio 0
	s_barrier
	s_add_i32 s3, s3, s18
	s_add_u32 s42, s80, 0x80
	s_addc_u32 s43, s81, 0
	s_mov_b32 m0, s3
	ds_read_b128 v[184:187], v159 offset:49152
	ds_read_b128 v[188:191], v159 offset:50176
	ds_read_b128 v[192:195], v159 offset:51200
	ds_read_b128 v[196:199], v159 offset:52224
	ds_read_b128 v[200:203], v159 offset:53248
	ds_read_b128 v[204:207], v159 offset:54272
	ds_read_b128 v[208:211], v159 offset:55296
	ds_read_b128 v[212:215], v159 offset:56320
	global_load_lds_dwordx4 v130, s[42:43]
	s_add_i32 m0, s3, 0x2000
	s_add_i32 s3, s44, s18
	global_load_lds_dwordx4 v134, s[42:43]
	s_add_u32 s42, s42, 0x20000
	s_addc_u32 s43, s43, 0
	s_mov_b32 m0, s3
	s_nop 0
	global_load_lds_dwordx4 v130, s[42:43]
	s_add_i32 m0, s3, 0x2000
	s_nop 0
	global_load_lds_dwordx4 v134, s[42:43]
	s_add_u32 s90, s90, 0x80
	s_addc_u32 s91, s91, 0
	s_mov_b32 m0, s58
	s_nop 0
	global_load_lds_dwordx4 v128, s[90:91]
	s_mov_b32 m0, s59
	s_nop 0
	global_load_lds_dwordx4 v132, s[90:91]
	s_waitcnt vmcnt(8)
	s_waitcnt lgkmcnt(0)
	s_barrier
	s_setprio 1
	s_waitcnt lgkmcnt(0)
	v_mfma_f32_16x16x32_bf16 v[60:63], v[144:147], v[184:187], v[60:63]
	v_mfma_f32_16x16x32_bf16 v[56:59], v[160:163], v[184:187], v[56:59]
	v_mfma_f32_16x16x32_bf16 v[44:47], v[144:147], v[192:195], v[44:47]
	v_mfma_f32_16x16x32_bf16 v[40:43], v[160:163], v[192:195], v[40:43]
	v_mfma_f32_16x16x32_bf16 v[28:31], v[144:147], v[200:203], v[28:31]
	v_mfma_f32_16x16x32_bf16 v[24:27], v[160:163], v[200:203], v[24:27]
	v_mfma_f32_16x16x32_bf16 v[12:15], v[144:147], v[208:211], v[12:15]
	v_mfma_f32_16x16x32_bf16 v[8:11], v[160:163], v[208:211], v[8:11]
	v_mfma_f32_16x16x32_bf16 v[60:63], v[148:151], v[188:191], v[60:63]
	v_mfma_f32_16x16x32_bf16 v[56:59], v[164:167], v[188:191], v[56:59]
	v_mfma_f32_16x16x32_bf16 v[44:47], v[148:151], v[196:199], v[44:47]
	v_mfma_f32_16x16x32_bf16 v[40:43], v[164:167], v[196:199], v[40:43]
	v_mfma_f32_16x16x32_bf16 v[28:31], v[148:151], v[204:207], v[28:31]
	v_mfma_f32_16x16x32_bf16 v[24:27], v[164:167], v[204:207], v[24:27]
	v_mfma_f32_16x16x32_bf16 v[12:15], v[148:151], v[212:215], v[12:15]
	v_mfma_f32_16x16x32_bf16 v[8:11], v[164:167], v[212:215], v[8:11]
	v_mfma_f32_16x16x32_bf16 v[52:55], v[168:171], v[184:187], v[52:55]
	v_mfma_f32_16x16x32_bf16 v[48:51], v[176:179], v[184:187], v[48:51]
	v_mfma_f32_16x16x32_bf16 v[36:39], v[168:171], v[192:195], v[36:39]
	v_mfma_f32_16x16x32_bf16 v[32:35], v[176:179], v[192:195], v[32:35]
	v_mfma_f32_16x16x32_bf16 v[20:23], v[168:171], v[200:203], v[20:23]
	v_mfma_f32_16x16x32_bf16 v[16:19], v[176:179], v[200:203], v[16:19]
	v_mfma_f32_16x16x32_bf16 v[4:7], v[168:171], v[208:211], v[4:7]
	v_mfma_f32_16x16x32_bf16 v[0:3], v[176:179], v[208:211], v[0:3]
	v_mfma_f32_16x16x32_bf16 v[52:55], v[172:175], v[188:191], v[52:55]
	v_mfma_f32_16x16x32_bf16 v[48:51], v[180:183], v[188:191], v[48:51]
	v_mfma_f32_16x16x32_bf16 v[36:39], v[172:175], v[196:199], v[36:39]
	v_mfma_f32_16x16x32_bf16 v[32:35], v[180:183], v[196:199], v[32:35]
	v_mfma_f32_16x16x32_bf16 v[20:23], v[172:175], v[204:207], v[20:23]
	v_mfma_f32_16x16x32_bf16 v[16:19], v[180:183], v[204:207], v[16:19]
	v_mfma_f32_16x16x32_bf16 v[4:7], v[172:175], v[212:215], v[4:7]
	v_mfma_f32_16x16x32_bf16 v[0:3], v[180:183], v[212:215], v[0:3]
	s_setprio 0
	s_add_i32 s37, s37, 2
	s_add_u32 s34, s34, 0x100
	s_addc_u32 s35, s35, 0
	s_add_u32 s33, s33, 0x100
	s_addc_u32 s36, s36, 0
	s_cmp_gt_u32 s37, 5
	s_barrier
	s_cbranch_scc0 .LBB0_1417
	s_and_b64 vcc, exec, s[14:15]
	s_cbranch_vccz .LBB0_1420
	s_barrier

.LBB0_1493:
	ds_read_b128 v[140:143], v149
	ds_read_b128 v[152:155], v149 offset:1024
	ds_read_b128 v[156:159], v149 offset:2048
	ds_read_b128 v[160:163], v149 offset:3072
	ds_read_b128 v[164:167], v150
	ds_read_b128 v[168:171], v150 offset:1024
	ds_read_b128 v[172:175], v150 offset:2048
	ds_read_b128 v[176:179], v150 offset:3072
	s_add_u32 s3, s86, 0xfff80080
	s_addc_u32 s33, s87, -1
	s_cmp_eq_u32 s27, 28
	s_cselect_b32 s89, s0, s33
	s_cselect_b32 s88, s1, s3
	s_cselect_b32 s81, s15, s24
	s_cselect_b32 s80, s17, s19
	s_add_i32 m0, s30, 0xc000
	ds_read_b128 v[180:183], v151
	ds_read_b128 v[184:187], v151 offset:1024
	ds_read_b128 v[188:191], v151 offset:2048
	ds_read_b128 v[192:195], v151 offset:3072
	ds_read_b128 v[196:199], v151 offset:4096
	ds_read_b128 v[200:203], v151 offset:5120
	ds_read_b128 v[204:207], v151 offset:6144
	ds_read_b128 v[208:211], v151 offset:7168
	global_load_lds_dwordx4 v132, s[86:87]
	s_add_i32 m0, s30, 0xe000
	s_nop 0
	global_load_lds_dwordx4 v134, s[86:87]
	s_waitcnt vmcnt(8)
	s_waitcnt lgkmcnt(0)
	s_barrier
	s_setprio 1
	s_waitcnt lgkmcnt(0)
	v_mfma_f32_16x16x32_bf16 v[124:127], v[140:143], v[180:183], v[124:127]
	v_mfma_f32_16x16x32_bf16 v[120:123], v[156:159], v[180:183], v[120:123]
	v_mfma_f32_16x16x32_bf16 v[108:111], v[140:143], v[188:191], v[108:111]
	v_mfma_f32_16x16x32_bf16 v[104:107], v[156:159], v[188:191], v[104:107]
	v_mfma_f32_16x16x32_bf16 v[92:95], v[140:143], v[196:199], v[92:95]
	v_mfma_f32_16x16x32_bf16 v[88:91], v[156:159], v[196:199], v[88:91]
	v_mfma_f32_16x16x32_bf16 v[76:79], v[140:143], v[204:207], v[76:79]
	v_mfma_f32_16x16x32_bf16 v[72:75], v[156:159], v[204:207], v[72:75]
	v_mfma_f32_16x16x32_bf16 v[124:127], v[152:155], v[184:187], v[124:127]
	v_mfma_f32_16x16x32_bf16 v[120:123], v[160:163], v[184:187], v[120:123]
	v_mfma_f32_16x16x32_bf16 v[108:111], v[152:155], v[192:195], v[108:111]
	v_mfma_f32_16x16x32_bf16 v[104:107], v[160:163], v[192:195], v[104:107]
	v_mfma_f32_16x16x32_bf16 v[92:95], v[152:155], v[200:203], v[92:95]
	v_mfma_f32_16x16x32_bf16 v[88:91], v[160:163], v[200:203], v[88:91]
	v_mfma_f32_16x16x32_bf16 v[76:79], v[152:155], v[208:211], v[76:79]
	v_mfma_f32_16x16x32_bf16 v[72:75], v[160:163], v[208:211], v[72:75]
	v_mfma_f32_16x16x32_bf16 v[116:119], v[164:167], v[180:183], v[116:119]
	v_mfma_f32_16x16x32_bf16 v[112:115], v[172:175], v[180:183], v[112:115]
	v_mfma_f32_16x16x32_bf16 v[100:103], v[164:167], v[188:191], v[100:103]
	v_mfma_f32_16x16x32_bf16 v[96:99], v[172:175], v[188:191], v[96:99]
	v_mfma_f32_16x16x32_bf16 v[84:87], v[164:167], v[196:199], v[84:87]
	v_mfma_f32_16x16x32_bf16 v[80:83], v[172:175], v[196:199], v[80:83]
	v_mfma_f32_16x16x32_bf16 v[68:71], v[164:167], v[204:207], v[68:71]
	v_mfma_f32_16x16x32_bf16 v[64:67], v[172:175], v[204:207], v[64:67]
	v_mfma_f32_16x16x32_bf16 v[116:119], v[168:171], v[184:187], v[116:119]
	v_mfma_f32_16x16x32_bf16 v[112:115], v[176:179], v[184:187], v[112:115]
	v_mfma_f32_16x16x32_bf16 v[100:103], v[168:171], v[192:195], v[100:103]
	v_mfma_f32_16x16x32_bf16 v[96:99], v[176:179], v[192:195], v[96:99]
	v_mfma_f32_16x16x32_bf16 v[84:87], v[168:171], v[200:203], v[84:87]
	v_mfma_f32_16x16x32_bf16 v[80:83], v[176:179], v[200:203], v[80:83]
	v_mfma_f32_16x16x32_bf16 v[68:71], v[168:171], v[208:211], v[68:71]
	v_mfma_f32_16x16x32_bf16 v[64:67], v[176:179], v[208:211], v[64:67]
	s_setprio 0
	s_barrier
	s_add_i32 s3, s59, s25
	s_mov_b32 m0, s3
	ds_read_b128 v[180:183], v151 offset:16384
	ds_read_b128 v[184:187], v151 offset:17408
	ds_read_b128 v[188:191], v151 offset:18432
	ds_read_b128 v[192:195], v151 offset:19456
	ds_read_b128 v[196:199], v151 offset:20480
	ds_read_b128 v[200:203], v151 offset:21504
	ds_read_b128 v[204:207], v151 offset:22528
	ds_read_b128 v[208:211], v151 offset:23552
	global_load_lds_dwordx4 v128, s[80:81]
	s_add_i32 m0, s3, 0x2000
	s_add_u32 s36, s80, 0x80000
	s_addc_u32 s37, s81, 0
	s_add_i32 s3, s68, s25
	global_load_lds_dwordx4 v130, s[80:81]
	s_mov_b32 m0, s3
	s_nop 0
	global_load_lds_dwordx4 v128, s[36:37]
	s_add_i32 m0, s3, 0x2000
	s_nop 0
	global_load_lds_dwordx4 v130, s[36:37]
	s_mov_b32 m0, s30
	s_nop 0
	global_load_lds_dwordx4 v128, s[88:89]
	s_mov_b32 m0, s31
	s_nop 0
	global_load_lds_dwordx4 v130, s[88:89]
	s_waitcnt vmcnt(8)
	s_waitcnt lgkmcnt(0)
	s_barrier
	s_setprio 1
	s_waitcnt lgkmcnt(0)
	v_mfma_f32_16x16x32_bf16 v[60:63], v[140:143], v[180:183], v[60:63]
	v_mfma_f32_16x16x32_bf16 v[56:59], v[156:159], v[180:183], v[56:59]
	v_mfma_f32_16x16x32_bf16 v[44:47], v[140:143], v[188:191], v[44:47]
	v_mfma_f32_16x16x32_bf16 v[40:43], v[156:159], v[188:191], v[40:43]
	v_mfma_f32_16x16x32_bf16 v[28:31], v[140:143], v[196:199], v[28:31]
	v_mfma_f32_16x16x32_bf16 v[24:27], v[156:159], v[196:199], v[24:27]
	v_mfma_f32_16x16x32_bf16 v[12:15], v[140:143], v[204:207], v[12:15]
	v_mfma_f32_16x16x32_bf16 v[8:11], v[156:159], v[204:207], v[8:11]
	v_mfma_f32_16x16x32_bf16 v[60:63], v[152:155], v[184:187], v[60:63]
	v_mfma_f32_16x16x32_bf16 v[56:59], v[160:163], v[184:187], v[56:59]
	v_mfma_f32_16x16x32_bf16 v[44:47], v[152:155], v[192:195], v[44:47]
	v_mfma_f32_16x16x32_bf16 v[40:43], v[160:163], v[192:195], v[40:43]
	v_mfma_f32_16x16x32_bf16 v[28:31], v[152:155], v[200:203], v[28:31]
	v_mfma_f32_16x16x32_bf16 v[24:27], v[160:163], v[200:203], v[24:27]
	v_mfma_f32_16x16x32_bf16 v[12:15], v[152:155], v[208:211], v[12:15]
	v_mfma_f32_16x16x32_bf16 v[8:11], v[160:163], v[208:211], v[8:11]
	v_mfma_f32_16x16x32_bf16 v[52:55], v[164:167], v[180:183], v[52:55]
	v_mfma_f32_16x16x32_bf16 v[48:51], v[172:175], v[180:183], v[48:51]
	v_mfma_f32_16x16x32_bf16 v[36:39], v[164:167], v[188:191], v[36:39]
	v_mfma_f32_16x16x32_bf16 v[32:35], v[172:175], v[188:191], v[32:35]
	v_mfma_f32_16x16x32_bf16 v[20:23], v[164:167], v[196:199], v[20:23]
	v_mfma_f32_16x16x32_bf16 v[16:19], v[172:175], v[196:199], v[16:19]
	v_mfma_f32_16x16x32_bf16 v[4:7], v[164:167], v[204:207], v[4:7]
	v_mfma_f32_16x16x32_bf16 v[0:3], v[172:175], v[204:207], v[0:3]
	v_mfma_f32_16x16x32_bf16 v[52:55], v[168:171], v[184:187], v[52:55]
	v_mfma_f32_16x16x32_bf16 v[48:51], v[176:179], v[184:187], v[48:51]
	v_mfma_f32_16x16x32_bf16 v[36:39], v[168:171], v[192:195], v[36:39]
	v_mfma_f32_16x16x32_bf16 v[32:35], v[176:179], v[192:195], v[32:35]
	v_mfma_f32_16x16x32_bf16 v[20:23], v[168:171], v[200:203], v[20:23]
	v_mfma_f32_16x16x32_bf16 v[16:19], v[176:179], v[200:203], v[16:19]
	v_mfma_f32_16x16x32_bf16 v[4:7], v[168:171], v[208:211], v[4:7]
	v_mfma_f32_16x16x32_bf16 v[0:3], v[176:179], v[208:211], v[0:3]
	s_setprio 0
	s_barrier
	s_add_i32 s3, 0, 0x18000
	s_add_i32 s33, 0, 0x1c000
	v_add_u32_e32 v160, s3, v147
	v_add_u32_e32 v176, s33, v147
	ds_read_b128 v[140:143], v160
	ds_read_b128 v[152:155], v160 offset:1024
	ds_read_b128 v[156:159], v160 offset:2048
	ds_read_b128 v[160:163], v160 offset:3072
	ds_read_b128 v[164:167], v176
	ds_read_b128 v[168:171], v176 offset:1024
	ds_read_b128 v[172:175], v176 offset:2048
	ds_read_b128 v[176:179], v176 offset:3072
	s_add_u32 s36, s88, 0x80000
	s_addc_u32 s37, s89, 0
	s_mov_b32 m0, s52
	ds_read_b128 v[180:183], v151 offset:32768
	ds_read_b128 v[184:187], v151 offset:33792
	ds_read_b128 v[188:191], v151 offset:34816
	ds_read_b128 v[192:195], v151 offset:35840
	ds_read_b128 v[196:199], v151 offset:36864
	ds_read_b128 v[200:203], v151 offset:37888
	ds_read_b128 v[204:207], v151 offset:38912
	ds_read_b128 v[208:211], v151 offset:39936
	global_load_lds_dwordx4 v128, s[36:37]
	v_lshl_add_u64 v[218:219], s[36:37], 0, v[130:131]
	s_mov_b32 m0, s53
	s_nop 0
	global_load_lds_dwordx4 v[218:219], off
	s_waitcnt vmcnt(8)
	s_waitcnt lgkmcnt(0)
	s_barrier
	s_setprio 1
	s_waitcnt lgkmcnt(0)
	v_mfma_f32_16x16x32_bf16 v[124:127], v[140:143], v[180:183], v[124:127]
	v_mfma_f32_16x16x32_bf16 v[120:123], v[156:159], v[180:183], v[120:123]
	v_mfma_f32_16x16x32_bf16 v[108:111], v[140:143], v[188:191], v[108:111]
	v_mfma_f32_16x16x32_bf16 v[104:107], v[156:159], v[188:191], v[104:107]
	v_mfma_f32_16x16x32_bf16 v[92:95], v[140:143], v[196:199], v[92:95]
	v_mfma_f32_16x16x32_bf16 v[88:91], v[156:159], v[196:199], v[88:91]
	v_mfma_f32_16x16x32_bf16 v[76:79], v[140:143], v[204:207], v[76:79]
	v_mfma_f32_16x16x32_bf16 v[72:75], v[156:159], v[204:207], v[72:75]
	v_mfma_f32_16x16x32_bf16 v[124:127], v[152:155], v[184:187], v[124:127]
	v_mfma_f32_16x16x32_bf16 v[120:123], v[160:163], v[184:187], v[120:123]
	v_mfma_f32_16x16x32_bf16 v[108:111], v[152:155], v[192:195], v[108:111]
	v_mfma_f32_16x16x32_bf16 v[104:107], v[160:163], v[192:195], v[104:107]
	v_mfma_f32_16x16x32_bf16 v[92:95], v[152:155], v[200:203], v[92:95]
	v_mfma_f32_16x16x32_bf16 v[88:91], v[160:163], v[200:203], v[88:91]
	v_mfma_f32_16x16x32_bf16 v[76:79], v[152:155], v[208:211], v[76:79]
	v_mfma_f32_16x16x32_bf16 v[72:75], v[160:163], v[208:211], v[72:75]
	v_mfma_f32_16x16x32_bf16 v[116:119], v[164:167], v[180:183], v[116:119]
	v_mfma_f32_16x16x32_bf16 v[112:115], v[172:175], v[180:183], v[112:115]
	v_mfma_f32_16x16x32_bf16 v[100:103], v[164:167], v[188:191], v[100:103]
	v_mfma_f32_16x16x32_bf16 v[96:99], v[172:175], v[188:191], v[96:99]
	v_mfma_f32_16x16x32_bf16 v[84:87], v[164:167], v[196:199], v[84:87]
	v_mfma_f32_16x16x32_bf16 v[80:83], v[172:175], v[196:199], v[80:83]
	v_mfma_f32_16x16x32_bf16 v[68:71], v[164:167], v[204:207], v[68:71]
	v_mfma_f32_16x16x32_bf16 v[64:67], v[172:175], v[204:207], v[64:67]
	v_mfma_f32_16x16x32_bf16 v[116:119], v[168:171], v[184:187], v[116:119]
	v_mfma_f32_16x16x32_bf16 v[112:115], v[176:179], v[184:187], v[112:115]
	v_mfma_f32_16x16x32_bf16 v[100:103], v[168:171], v[192:195], v[100:103]
	v_mfma_f32_16x16x32_bf16 v[96:99], v[176:179], v[192:195], v[96:99]
	v_mfma_f32_16x16x32_bf16 v[84:87], v[168:171], v[200:203], v[84:87]
	v_mfma_f32_16x16x32_bf16 v[80:83], v[176:179], v[200:203], v[80:83]
	v_mfma_f32_16x16x32_bf16 v[68:71], v[168:171], v[208:211], v[68:71]
	v_mfma_f32_16x16x32_bf16 v[64:67], v[176:179], v[208:211], v[64:67]
	s_setprio 0
	s_barrier
	s_add_i32 s3, s3, s25
	s_add_u32 s36, s80, 0x80
	s_addc_u32 s37, s81, 0
	s_mov_b32 m0, s3
	ds_read_b128 v[180:183], v151 offset:49152
	ds_read_b128 v[184:187], v151 offset:50176
	ds_read_b128 v[188:191], v151 offset:51200
	ds_read_b128 v[192:195], v151 offset:52224
	ds_read_b128 v[196:199], v151 offset:53248
	ds_read_b128 v[200:203], v151 offset:54272
	ds_read_b128 v[204:207], v151 offset:55296
	ds_read_b128 v[208:211], v151 offset:56320
	global_load_lds_dwordx4 v128, s[36:37]
	s_add_i32 m0, s3, 0x2000
	s_add_i32 s3, s33, s25
	global_load_lds_dwordx4 v130, s[36:37]
	s_add_u32 s36, s36, 0x80000
	s_addc_u32 s37, s37, 0
	s_mov_b32 m0, s3
	s_nop 0
	global_load_lds_dwordx4 v128, s[36:37]
	s_add_i32 m0, s3, 0x2000
	s_nop 0
	global_load_lds_dwordx4 v130, s[36:37]
	s_add_u32 s88, s88, 0x80
	s_addc_u32 s89, s89, 0
	s_mov_b32 m0, s57
	s_nop 0
	global_load_lds_dwordx4 v128, s[88:89]
	s_mov_b32 m0, s58
	s_nop 0
	global_load_lds_dwordx4 v130, s[88:89]
	s_waitcnt vmcnt(8)
	s_waitcnt lgkmcnt(0)
	s_barrier
	s_setprio 1
	s_waitcnt lgkmcnt(0)
	v_mfma_f32_16x16x32_bf16 v[60:63], v[140:143], v[180:183], v[60:63]
	v_mfma_f32_16x16x32_bf16 v[56:59], v[156:159], v[180:183], v[56:59]
	v_mfma_f32_16x16x32_bf16 v[44:47], v[140:143], v[188:191], v[44:47]
	v_mfma_f32_16x16x32_bf16 v[40:43], v[156:159], v[188:191], v[40:43]
	v_mfma_f32_16x16x32_bf16 v[28:31], v[140:143], v[196:199], v[28:31]
	v_mfma_f32_16x16x32_bf16 v[24:27], v[156:159], v[196:199], v[24:27]
	v_mfma_f32_16x16x32_bf16 v[12:15], v[140:143], v[204:207], v[12:15]
	v_mfma_f32_16x16x32_bf16 v[8:11], v[156:159], v[204:207], v[8:11]
	v_mfma_f32_16x16x32_bf16 v[60:63], v[152:155], v[184:187], v[60:63]
	v_mfma_f32_16x16x32_bf16 v[56:59], v[160:163], v[184:187], v[56:59]
	v_mfma_f32_16x16x32_bf16 v[44:47], v[152:155], v[192:195], v[44:47]
	v_mfma_f32_16x16x32_bf16 v[40:43], v[160:163], v[192:195], v[40:43]
	v_mfma_f32_16x16x32_bf16 v[28:31], v[152:155], v[200:203], v[28:31]
	v_mfma_f32_16x16x32_bf16 v[24:27], v[160:163], v[200:203], v[24:27]
	v_mfma_f32_16x16x32_bf16 v[12:15], v[152:155], v[208:211], v[12:15]
	v_mfma_f32_16x16x32_bf16 v[8:11], v[160:163], v[208:211], v[8:11]
	v_mfma_f32_16x16x32_bf16 v[52:55], v[164:167], v[180:183], v[52:55]
	v_mfma_f32_16x16x32_bf16 v[48:51], v[172:175], v[180:183], v[48:51]
	v_mfma_f32_16x16x32_bf16 v[36:39], v[164:167], v[188:191], v[36:39]
	v_mfma_f32_16x16x32_bf16 v[32:35], v[172:175], v[188:191], v[32:35]
	v_mfma_f32_16x16x32_bf16 v[20:23], v[164:167], v[196:199], v[20:23]
	v_mfma_f32_16x16x32_bf16 v[16:19], v[172:175], v[196:199], v[16:19]
	v_mfma_f32_16x16x32_bf16 v[4:7], v[164:167], v[204:207], v[4:7]
	v_mfma_f32_16x16x32_bf16 v[0:3], v[172:175], v[204:207], v[0:3]
	v_mfma_f32_16x16x32_bf16 v[52:55], v[168:171], v[184:187], v[52:55]
	v_mfma_f32_16x16x32_bf16 v[48:51], v[176:179], v[184:187], v[48:51]
	v_mfma_f32_16x16x32_bf16 v[36:39], v[168:171], v[192:195], v[36:39]
	v_mfma_f32_16x16x32_bf16 v[32:35], v[176:179], v[192:195], v[32:35]
	v_mfma_f32_16x16x32_bf16 v[20:23], v[168:171], v[200:203], v[20:23]
	v_mfma_f32_16x16x32_bf16 v[16:19], v[176:179], v[200:203], v[16:19]
	v_mfma_f32_16x16x32_bf16 v[4:7], v[168:171], v[208:211], v[4:7]
	v_mfma_f32_16x16x32_bf16 v[0:3], v[176:179], v[208:211], v[0:3]
	s_setprio 0
	s_add_i32 s27, s27, 2
	s_add_u32 s86, s86, 0x100
	s_addc_u32 s87, s87, 0
	s_add_u32 s19, s19, 0x100
	s_addc_u32 s24, s24, 0
	s_cmp_gt_u32 s27, 29
	s_barrier
	s_cbranch_scc0 .LBB0_1493
	s_and_b64 vcc, exec, s[12:13]
	s_cbranch_vccz .LBB0_1496
	s_barrier

.LBB0_1624:
	ds_read_b128 v[154:157], v150
	ds_read_b128 v[158:161], v150 offset:1024
	ds_read_b128 v[162:165], v150 offset:2048
	ds_read_b128 v[166:169], v150 offset:3072
	ds_read_b128 v[170:173], v151
	ds_read_b128 v[174:177], v151 offset:1024
	ds_read_b128 v[178:181], v151 offset:2048
	ds_read_b128 v[182:185], v151 offset:3072
	s_add_u32 s3, s88, 0xfff80080
	s_addc_u32 s42, s89, -1
	s_cmp_eq_u32 s37, 28
	s_cselect_b32 s93, s0, s42
	s_cselect_b32 s92, s1, s3
	s_cselect_b32 s91, s27, s36
	s_cselect_b32 s90, s33, s35
	s_add_i32 m0, s9, 0xc000
	ds_read_b128 v[186:189], v152
	ds_read_b128 v[190:193], v152 offset:1024
	ds_read_b128 v[194:197], v152 offset:2048
	ds_read_b128 v[198:201], v152 offset:3072
	ds_read_b128 v[202:205], v152 offset:4096
	ds_read_b128 v[206:209], v152 offset:5120
	ds_read_b128 v[210:213], v152 offset:6144
	ds_read_b128 v[214:217], v152 offset:7168
	global_load_lds_dwordx4 v138, s[88:89]
	s_add_i32 m0, s9, 0xe000
	s_nop 0
	global_load_lds_dwordx4 v140, s[88:89]
	s_waitcnt vmcnt(8)
	s_waitcnt lgkmcnt(0)
	s_barrier
	s_setprio 1
	s_waitcnt lgkmcnt(0)
	v_mfma_f32_16x16x32_bf16 v[124:127], v[154:157], v[186:189], v[124:127]
	v_mfma_f32_16x16x32_bf16 v[120:123], v[162:165], v[186:189], v[120:123]
	v_mfma_f32_16x16x32_bf16 v[108:111], v[154:157], v[194:197], v[108:111]
	v_mfma_f32_16x16x32_bf16 v[104:107], v[162:165], v[194:197], v[104:107]
	v_mfma_f32_16x16x32_bf16 v[92:95], v[154:157], v[202:205], v[92:95]
	v_mfma_f32_16x16x32_bf16 v[88:91], v[162:165], v[202:205], v[88:91]
	v_mfma_f32_16x16x32_bf16 v[76:79], v[154:157], v[210:213], v[76:79]
	v_mfma_f32_16x16x32_bf16 v[72:75], v[162:165], v[210:213], v[72:75]
	v_mfma_f32_16x16x32_bf16 v[124:127], v[158:161], v[190:193], v[124:127]
	v_mfma_f32_16x16x32_bf16 v[120:123], v[166:169], v[190:193], v[120:123]
	v_mfma_f32_16x16x32_bf16 v[108:111], v[158:161], v[198:201], v[108:111]
	v_mfma_f32_16x16x32_bf16 v[104:107], v[166:169], v[198:201], v[104:107]
	v_mfma_f32_16x16x32_bf16 v[92:95], v[158:161], v[206:209], v[92:95]
	v_mfma_f32_16x16x32_bf16 v[88:91], v[166:169], v[206:209], v[88:91]
	v_mfma_f32_16x16x32_bf16 v[76:79], v[158:161], v[214:217], v[76:79]
	v_mfma_f32_16x16x32_bf16 v[72:75], v[166:169], v[214:217], v[72:75]
	v_mfma_f32_16x16x32_bf16 v[116:119], v[170:173], v[186:189], v[116:119]
	v_mfma_f32_16x16x32_bf16 v[112:115], v[178:181], v[186:189], v[112:115]
	v_mfma_f32_16x16x32_bf16 v[100:103], v[170:173], v[194:197], v[100:103]
	v_mfma_f32_16x16x32_bf16 v[96:99], v[178:181], v[194:197], v[96:99]
	v_mfma_f32_16x16x32_bf16 v[84:87], v[170:173], v[202:205], v[84:87]
	v_mfma_f32_16x16x32_bf16 v[80:83], v[178:181], v[202:205], v[80:83]
	v_mfma_f32_16x16x32_bf16 v[68:71], v[170:173], v[210:213], v[68:71]
	v_mfma_f32_16x16x32_bf16 v[64:67], v[178:181], v[210:213], v[64:67]
	v_mfma_f32_16x16x32_bf16 v[116:119], v[174:177], v[190:193], v[116:119]
	v_mfma_f32_16x16x32_bf16 v[112:115], v[182:185], v[190:193], v[112:115]
	v_mfma_f32_16x16x32_bf16 v[100:103], v[174:177], v[198:201], v[100:103]
	v_mfma_f32_16x16x32_bf16 v[96:99], v[182:185], v[198:201], v[96:99]
	v_mfma_f32_16x16x32_bf16 v[84:87], v[174:177], v[206:209], v[84:87]
	v_mfma_f32_16x16x32_bf16 v[80:83], v[182:185], v[206:209], v[80:83]
	v_mfma_f32_16x16x32_bf16 v[68:71], v[174:177], v[214:217], v[68:71]
	v_mfma_f32_16x16x32_bf16 v[64:67], v[182:185], v[214:217], v[64:67]
	s_setprio 0
	s_barrier
	s_add_i32 s3, s48, s8
	s_mov_b32 m0, s3
	ds_read_b128 v[186:189], v152 offset:16384
	ds_read_b128 v[190:193], v152 offset:17408
	ds_read_b128 v[194:197], v152 offset:18432
	ds_read_b128 v[198:201], v152 offset:19456
	ds_read_b128 v[202:205], v152 offset:20480
	ds_read_b128 v[206:209], v152 offset:21504
	ds_read_b128 v[210:213], v152 offset:22528
	ds_read_b128 v[214:217], v152 offset:23552
	global_load_lds_dwordx4 v130, s[90:91]
	s_add_i32 m0, s3, 0x2000
	s_add_u32 s42, s90, 0x80000
	s_addc_u32 s43, s91, 0
	s_add_i32 s3, s49, s8
	global_load_lds_dwordx4 v134, s[90:91]
	s_mov_b32 m0, s3
	s_nop 0
	global_load_lds_dwordx4 v130, s[42:43]
	s_add_i32 m0, s3, 0x2000
	s_nop 0
	global_load_lds_dwordx4 v134, s[42:43]
	s_mov_b32 m0, s9
	s_nop 0
	global_load_lds_dwordx4 v128, s[92:93]
	s_mov_b32 m0, s18
	s_nop 0
	global_load_lds_dwordx4 v132, s[92:93]
	s_waitcnt vmcnt(8)
	s_waitcnt lgkmcnt(0)
	s_barrier
	s_setprio 1
	s_waitcnt lgkmcnt(0)
	v_mfma_f32_16x16x32_bf16 v[60:63], v[154:157], v[186:189], v[60:63]
	v_mfma_f32_16x16x32_bf16 v[56:59], v[162:165], v[186:189], v[56:59]
	v_mfma_f32_16x16x32_bf16 v[44:47], v[154:157], v[194:197], v[44:47]
	v_mfma_f32_16x16x32_bf16 v[40:43], v[162:165], v[194:197], v[40:43]
	v_mfma_f32_16x16x32_bf16 v[28:31], v[154:157], v[202:205], v[28:31]
	v_mfma_f32_16x16x32_bf16 v[24:27], v[162:165], v[202:205], v[24:27]
	v_mfma_f32_16x16x32_bf16 v[12:15], v[154:157], v[210:213], v[12:15]
	v_mfma_f32_16x16x32_bf16 v[8:11], v[162:165], v[210:213], v[8:11]
	v_mfma_f32_16x16x32_bf16 v[60:63], v[158:161], v[190:193], v[60:63]
	v_mfma_f32_16x16x32_bf16 v[56:59], v[166:169], v[190:193], v[56:59]
	v_mfma_f32_16x16x32_bf16 v[44:47], v[158:161], v[198:201], v[44:47]
	v_mfma_f32_16x16x32_bf16 v[40:43], v[166:169], v[198:201], v[40:43]
	v_mfma_f32_16x16x32_bf16 v[28:31], v[158:161], v[206:209], v[28:31]
	v_mfma_f32_16x16x32_bf16 v[24:27], v[166:169], v[206:209], v[24:27]
	v_mfma_f32_16x16x32_bf16 v[12:15], v[158:161], v[214:217], v[12:15]
	v_mfma_f32_16x16x32_bf16 v[8:11], v[166:169], v[214:217], v[8:11]
	v_mfma_f32_16x16x32_bf16 v[52:55], v[170:173], v[186:189], v[52:55]
	v_mfma_f32_16x16x32_bf16 v[48:51], v[178:181], v[186:189], v[48:51]
	v_mfma_f32_16x16x32_bf16 v[36:39], v[170:173], v[194:197], v[36:39]
	v_mfma_f32_16x16x32_bf16 v[32:35], v[178:181], v[194:197], v[32:35]
	v_mfma_f32_16x16x32_bf16 v[20:23], v[170:173], v[202:205], v[20:23]
	v_mfma_f32_16x16x32_bf16 v[16:19], v[178:181], v[202:205], v[16:19]
	v_mfma_f32_16x16x32_bf16 v[4:7], v[170:173], v[210:213], v[4:7]
	v_mfma_f32_16x16x32_bf16 v[0:3], v[178:181], v[210:213], v[0:3]
	v_mfma_f32_16x16x32_bf16 v[52:55], v[174:177], v[190:193], v[52:55]
	v_mfma_f32_16x16x32_bf16 v[48:51], v[182:185], v[190:193], v[48:51]
	v_mfma_f32_16x16x32_bf16 v[36:39], v[174:177], v[198:201], v[36:39]
	v_mfma_f32_16x16x32_bf16 v[32:35], v[182:185], v[198:201], v[32:35]
	v_mfma_f32_16x16x32_bf16 v[20:23], v[174:177], v[206:209], v[20:23]
	v_mfma_f32_16x16x32_bf16 v[16:19], v[182:185], v[206:209], v[16:19]
	v_mfma_f32_16x16x32_bf16 v[4:7], v[174:177], v[214:217], v[4:7]
	v_mfma_f32_16x16x32_bf16 v[0:3], v[182:185], v[214:217], v[0:3]
	s_setprio 0
	s_barrier
	s_add_i32 s3, 0, 0x18000
	v_add_u32_e32 v153, s3, v149
	s_add_i32 s44, 0, 0x1c000
	ds_read_b128 v[154:157], v153
	ds_read_b128 v[158:161], v153 offset:1024
	ds_read_b128 v[162:165], v153 offset:2048
	ds_read_b128 v[166:169], v153 offset:3072
	v_add_u32_e32 v153, s44, v149
	ds_read_b128 v[170:173], v153
	ds_read_b128 v[174:177], v153 offset:1024
	ds_read_b128 v[178:181], v153 offset:2048
	ds_read_b128 v[182:185], v153 offset:3072
	s_add_u32 s42, s92, 0x80000
	s_addc_u32 s43, s93, 0
	s_mov_b32 m0, s19
	ds_read_b128 v[186:189], v152 offset:32768
	ds_read_b128 v[190:193], v152 offset:33792
	ds_read_b128 v[194:197], v152 offset:34816
	ds_read_b128 v[198:201], v152 offset:35840
	ds_read_b128 v[202:205], v152 offset:36864
	ds_read_b128 v[206:209], v152 offset:37888
	ds_read_b128 v[210:213], v152 offset:38912
	ds_read_b128 v[214:217], v152 offset:39936
	global_load_lds_dwordx4 v128, s[42:43]
	v_lshl_add_u64 v[224:225], s[42:43], 0, v[132:133]
	s_mov_b32 m0, s25
	s_nop 0
	global_load_lds_dwordx4 v[224:225], off
	s_waitcnt vmcnt(8)
	s_waitcnt lgkmcnt(0)
	s_barrier
	s_setprio 1
	s_waitcnt lgkmcnt(0)
	v_mfma_f32_16x16x32_bf16 v[124:127], v[154:157], v[186:189], v[124:127]
	v_mfma_f32_16x16x32_bf16 v[120:123], v[162:165], v[186:189], v[120:123]
	v_mfma_f32_16x16x32_bf16 v[108:111], v[154:157], v[194:197], v[108:111]
	v_mfma_f32_16x16x32_bf16 v[104:107], v[162:165], v[194:197], v[104:107]
	v_mfma_f32_16x16x32_bf16 v[92:95], v[154:157], v[202:205], v[92:95]
	v_mfma_f32_16x16x32_bf16 v[88:91], v[162:165], v[202:205], v[88:91]
	v_mfma_f32_16x16x32_bf16 v[76:79], v[154:157], v[210:213], v[76:79]
	v_mfma_f32_16x16x32_bf16 v[72:75], v[162:165], v[210:213], v[72:75]
	v_mfma_f32_16x16x32_bf16 v[124:127], v[158:161], v[190:193], v[124:127]
	v_mfma_f32_16x16x32_bf16 v[120:123], v[166:169], v[190:193], v[120:123]
	v_mfma_f32_16x16x32_bf16 v[108:111], v[158:161], v[198:201], v[108:111]
	v_mfma_f32_16x16x32_bf16 v[104:107], v[166:169], v[198:201], v[104:107]
	v_mfma_f32_16x16x32_bf16 v[92:95], v[158:161], v[206:209], v[92:95]
	v_mfma_f32_16x16x32_bf16 v[88:91], v[166:169], v[206:209], v[88:91]
	v_mfma_f32_16x16x32_bf16 v[76:79], v[158:161], v[214:217], v[76:79]
	v_mfma_f32_16x16x32_bf16 v[72:75], v[166:169], v[214:217], v[72:75]
	v_mfma_f32_16x16x32_bf16 v[116:119], v[170:173], v[186:189], v[116:119]
	v_mfma_f32_16x16x32_bf16 v[112:115], v[178:181], v[186:189], v[112:115]
	v_mfma_f32_16x16x32_bf16 v[100:103], v[170:173], v[194:197], v[100:103]
	v_mfma_f32_16x16x32_bf16 v[96:99], v[178:181], v[194:197], v[96:99]
	v_mfma_f32_16x16x32_bf16 v[84:87], v[170:173], v[202:205], v[84:87]
	v_mfma_f32_16x16x32_bf16 v[80:83], v[178:181], v[202:205], v[80:83]
	v_mfma_f32_16x16x32_bf16 v[68:71], v[170:173], v[210:213], v[68:71]
	v_mfma_f32_16x16x32_bf16 v[64:67], v[178:181], v[210:213], v[64:67]
	v_mfma_f32_16x16x32_bf16 v[116:119], v[174:177], v[190:193], v[116:119]
	v_mfma_f32_16x16x32_bf16 v[112:115], v[182:185], v[190:193], v[112:115]
	v_mfma_f32_16x16x32_bf16 v[100:103], v[174:177], v[198:201], v[100:103]
	v_mfma_f32_16x16x32_bf16 v[96:99], v[182:185], v[198:201], v[96:99]
	v_mfma_f32_16x16x32_bf16 v[84:87], v[174:177], v[206:209], v[84:87]
	v_mfma_f32_16x16x32_bf16 v[80:83], v[182:185], v[206:209], v[80:83]
	v_mfma_f32_16x16x32_bf16 v[68:71], v[174:177], v[214:217], v[68:71]
	v_mfma_f32_16x16x32_bf16 v[64:67], v[182:185], v[214:217], v[64:67]
	s_setprio 0
	s_barrier
	s_add_i32 s3, s3, s8
	s_add_u32 s42, s90, 0x80
	s_addc_u32 s43, s91, 0
	s_mov_b32 m0, s3
	ds_read_b128 v[186:189], v152 offset:49152
	ds_read_b128 v[190:193], v152 offset:50176
	ds_read_b128 v[194:197], v152 offset:51200
	ds_read_b128 v[198:201], v152 offset:52224
	ds_read_b128 v[202:205], v152 offset:53248
	ds_read_b128 v[206:209], v152 offset:54272
	ds_read_b128 v[210:213], v152 offset:55296
	ds_read_b128 v[214:217], v152 offset:56320
	global_load_lds_dwordx4 v130, s[42:43]
	s_add_i32 m0, s3, 0x2000
	s_add_i32 s3, s44, s8
	global_load_lds_dwordx4 v134, s[42:43]
	s_add_u32 s42, s42, 0x80000
	s_addc_u32 s43, s43, 0
	s_mov_b32 m0, s3
	s_nop 0
	global_load_lds_dwordx4 v130, s[42:43]
	s_add_i32 m0, s3, 0x2000
	s_nop 0
	global_load_lds_dwordx4 v134, s[42:43]
	s_add_u32 s92, s92, 0x80
	s_addc_u32 s93, s93, 0
	s_mov_b32 m0, s30
	s_nop 0
	global_load_lds_dwordx4 v128, s[92:93]
	s_mov_b32 m0, s31
	s_nop 0
	global_load_lds_dwordx4 v132, s[92:93]
	s_waitcnt vmcnt(8)
	s_waitcnt lgkmcnt(0)
	s_barrier
	s_setprio 1
	s_waitcnt lgkmcnt(0)
	v_mfma_f32_16x16x32_bf16 v[60:63], v[154:157], v[186:189], v[60:63]
	v_mfma_f32_16x16x32_bf16 v[56:59], v[162:165], v[186:189], v[56:59]
	v_mfma_f32_16x16x32_bf16 v[44:47], v[154:157], v[194:197], v[44:47]
	v_mfma_f32_16x16x32_bf16 v[40:43], v[162:165], v[194:197], v[40:43]
	v_mfma_f32_16x16x32_bf16 v[28:31], v[154:157], v[202:205], v[28:31]
	v_mfma_f32_16x16x32_bf16 v[24:27], v[162:165], v[202:205], v[24:27]
	v_mfma_f32_16x16x32_bf16 v[12:15], v[154:157], v[210:213], v[12:15]
	v_mfma_f32_16x16x32_bf16 v[8:11], v[162:165], v[210:213], v[8:11]
	v_mfma_f32_16x16x32_bf16 v[60:63], v[158:161], v[190:193], v[60:63]
	v_mfma_f32_16x16x32_bf16 v[56:59], v[166:169], v[190:193], v[56:59]
	v_mfma_f32_16x16x32_bf16 v[44:47], v[158:161], v[198:201], v[44:47]
	v_mfma_f32_16x16x32_bf16 v[40:43], v[166:169], v[198:201], v[40:43]
	v_mfma_f32_16x16x32_bf16 v[28:31], v[158:161], v[206:209], v[28:31]
	v_mfma_f32_16x16x32_bf16 v[24:27], v[166:169], v[206:209], v[24:27]
	v_mfma_f32_16x16x32_bf16 v[12:15], v[158:161], v[214:217], v[12:15]
	v_mfma_f32_16x16x32_bf16 v[8:11], v[166:169], v[214:217], v[8:11]
	v_mfma_f32_16x16x32_bf16 v[52:55], v[170:173], v[186:189], v[52:55]
	v_mfma_f32_16x16x32_bf16 v[48:51], v[178:181], v[186:189], v[48:51]
	v_mfma_f32_16x16x32_bf16 v[36:39], v[170:173], v[194:197], v[36:39]
	v_mfma_f32_16x16x32_bf16 v[32:35], v[178:181], v[194:197], v[32:35]
	v_mfma_f32_16x16x32_bf16 v[20:23], v[170:173], v[202:205], v[20:23]
	v_mfma_f32_16x16x32_bf16 v[16:19], v[178:181], v[202:205], v[16:19]
	v_mfma_f32_16x16x32_bf16 v[4:7], v[170:173], v[210:213], v[4:7]
	v_mfma_f32_16x16x32_bf16 v[0:3], v[178:181], v[210:213], v[0:3]
	v_mfma_f32_16x16x32_bf16 v[52:55], v[174:177], v[190:193], v[52:55]
	v_mfma_f32_16x16x32_bf16 v[48:51], v[182:185], v[190:193], v[48:51]
	v_mfma_f32_16x16x32_bf16 v[36:39], v[174:177], v[198:201], v[36:39]
	v_mfma_f32_16x16x32_bf16 v[32:35], v[182:185], v[198:201], v[32:35]
	v_mfma_f32_16x16x32_bf16 v[20:23], v[174:177], v[206:209], v[20:23]
	v_mfma_f32_16x16x32_bf16 v[16:19], v[182:185], v[206:209], v[16:19]
	v_mfma_f32_16x16x32_bf16 v[4:7], v[174:177], v[214:217], v[4:7]
	v_mfma_f32_16x16x32_bf16 v[0:3], v[182:185], v[214:217], v[0:3]
	s_setprio 0
	s_add_i32 s37, s37, 2
	s_add_u32 s88, s88, 0x100
	s_addc_u32 s89, s89, 0
	s_add_u32 s35, s35, 0x100
	s_addc_u32 s36, s36, 0
	s_cmp_gt_u32 s37, 29
	s_barrier
	s_cbranch_scc0 .LBB0_1624
	s_and_b64 vcc, exec, s[16:17]
	s_cbranch_vccz .LBB0_1627
	s_barrier

.LBB0_1700:
	ds_read_b128 v[140:143], v149
	ds_read_b128 v[152:155], v149 offset:1024
	ds_read_b128 v[156:159], v149 offset:2048
	ds_read_b128 v[160:163], v149 offset:3072
	ds_read_b128 v[164:167], v150
	ds_read_b128 v[168:171], v150 offset:1024
	ds_read_b128 v[172:175], v150 offset:2048
	ds_read_b128 v[176:179], v150 offset:3072
	s_add_u32 s3, s86, 0xffe00080
	s_addc_u32 s37, s87, -1
	s_cmpk_eq_i32 s36, 0x7c
	s_cselect_b32 s91, s0, s37
	s_cselect_b32 s90, s1, s3
	s_cselect_b32 s89, s17, s35
	s_cselect_b32 s88, s27, s33
	s_add_i32 m0, s18, 0xc000
	ds_read_b128 v[180:183], v151
	ds_read_b128 v[184:187], v151 offset:1024
	ds_read_b128 v[188:191], v151 offset:2048
	ds_read_b128 v[192:195], v151 offset:3072
	ds_read_b128 v[196:199], v151 offset:4096
	ds_read_b128 v[200:203], v151 offset:5120
	ds_read_b128 v[204:207], v151 offset:6144
	ds_read_b128 v[208:211], v151 offset:7168
	global_load_lds_dwordx4 v132, s[86:87]
	s_add_i32 m0, s18, 0xe000
	s_nop 0
	global_load_lds_dwordx4 v134, s[86:87]
	s_waitcnt vmcnt(8)
	s_waitcnt lgkmcnt(0)
	s_barrier
	s_setprio 1
	s_waitcnt lgkmcnt(0)
	v_mfma_f32_16x16x32_bf16 v[124:127], v[140:143], v[180:183], v[124:127]
	v_mfma_f32_16x16x32_bf16 v[120:123], v[156:159], v[180:183], v[120:123]
	v_mfma_f32_16x16x32_bf16 v[112:115], v[140:143], v[188:191], v[112:115]
	v_mfma_f32_16x16x32_bf16 v[104:107], v[156:159], v[188:191], v[104:107]
	v_mfma_f32_16x16x32_bf16 v[96:99], v[140:143], v[196:199], v[96:99]
	v_mfma_f32_16x16x32_bf16 v[88:91], v[156:159], v[196:199], v[88:91]
	v_mfma_f32_16x16x32_bf16 v[80:83], v[140:143], v[204:207], v[80:83]
	v_mfma_f32_16x16x32_bf16 v[72:75], v[156:159], v[204:207], v[72:75]
	v_mfma_f32_16x16x32_bf16 v[124:127], v[152:155], v[184:187], v[124:127]
	v_mfma_f32_16x16x32_bf16 v[120:123], v[160:163], v[184:187], v[120:123]
	v_mfma_f32_16x16x32_bf16 v[112:115], v[152:155], v[192:195], v[112:115]
	v_mfma_f32_16x16x32_bf16 v[104:107], v[160:163], v[192:195], v[104:107]
	v_mfma_f32_16x16x32_bf16 v[96:99], v[152:155], v[200:203], v[96:99]
	v_mfma_f32_16x16x32_bf16 v[88:91], v[160:163], v[200:203], v[88:91]
	v_mfma_f32_16x16x32_bf16 v[80:83], v[152:155], v[208:211], v[80:83]
	v_mfma_f32_16x16x32_bf16 v[72:75], v[160:163], v[208:211], v[72:75]
	v_mfma_f32_16x16x32_bf16 v[116:119], v[164:167], v[180:183], v[116:119]
	v_mfma_f32_16x16x32_bf16 v[108:111], v[172:175], v[180:183], v[108:111]
	v_mfma_f32_16x16x32_bf16 v[100:103], v[164:167], v[188:191], v[100:103]
	v_mfma_f32_16x16x32_bf16 v[92:95], v[172:175], v[188:191], v[92:95]
	v_mfma_f32_16x16x32_bf16 v[84:87], v[164:167], v[196:199], v[84:87]
	v_mfma_f32_16x16x32_bf16 v[76:79], v[172:175], v[196:199], v[76:79]
	v_mfma_f32_16x16x32_bf16 v[68:71], v[164:167], v[204:207], v[68:71]
	v_mfma_f32_16x16x32_bf16 v[64:67], v[172:175], v[204:207], v[64:67]
	v_mfma_f32_16x16x32_bf16 v[116:119], v[168:171], v[184:187], v[116:119]
	v_mfma_f32_16x16x32_bf16 v[108:111], v[176:179], v[184:187], v[108:111]
	v_mfma_f32_16x16x32_bf16 v[100:103], v[168:171], v[192:195], v[100:103]
	v_mfma_f32_16x16x32_bf16 v[92:95], v[176:179], v[192:195], v[92:95]
	v_mfma_f32_16x16x32_bf16 v[84:87], v[168:171], v[200:203], v[84:87]
	v_mfma_f32_16x16x32_bf16 v[76:79], v[176:179], v[200:203], v[76:79]
	v_mfma_f32_16x16x32_bf16 v[68:71], v[168:171], v[208:211], v[68:71]
	v_mfma_f32_16x16x32_bf16 v[64:67], v[176:179], v[208:211], v[64:67]
	s_setprio 0
	s_barrier
	s_add_i32 s3, s49, s9
	s_mov_b32 m0, s3
	ds_read_b128 v[180:183], v151 offset:16384
	ds_read_b128 v[184:187], v151 offset:17408
	ds_read_b128 v[188:191], v151 offset:18432
	ds_read_b128 v[192:195], v151 offset:19456
	ds_read_b128 v[196:199], v151 offset:20480
	ds_read_b128 v[200:203], v151 offset:21504
	ds_read_b128 v[204:207], v151 offset:22528
	ds_read_b128 v[208:211], v151 offset:23552
	global_load_lds_dwordx4 v128, s[88:89]
	s_add_i32 m0, s3, 0x2000
	s_add_u32 s42, s88, 0x200000
	s_addc_u32 s43, s89, 0
	s_add_i32 s3, s52, s9
	global_load_lds_dwordx4 v130, s[88:89]
	s_mov_b32 m0, s3
	s_nop 0
	global_load_lds_dwordx4 v128, s[42:43]
	s_add_i32 m0, s3, 0x2000
	s_nop 0
	global_load_lds_dwordx4 v130, s[42:43]
	s_mov_b32 m0, s18
	s_nop 0
	global_load_lds_dwordx4 v128, s[90:91]
	s_mov_b32 m0, s19
	s_nop 0
	global_load_lds_dwordx4 v130, s[90:91]
	s_waitcnt vmcnt(8)
	s_waitcnt lgkmcnt(0)
	s_barrier
	s_setprio 1
	s_waitcnt lgkmcnt(0)
	v_mfma_f32_16x16x32_bf16 v[60:63], v[140:143], v[180:183], v[60:63]
	v_mfma_f32_16x16x32_bf16 v[56:59], v[156:159], v[180:183], v[56:59]
	v_mfma_f32_16x16x32_bf16 v[48:51], v[140:143], v[188:191], v[48:51]
	v_mfma_f32_16x16x32_bf16 v[40:43], v[156:159], v[188:191], v[40:43]
	v_mfma_f32_16x16x32_bf16 v[32:35], v[140:143], v[196:199], v[32:35]
	v_mfma_f32_16x16x32_bf16 v[24:27], v[156:159], v[196:199], v[24:27]
	v_mfma_f32_16x16x32_bf16 v[16:19], v[140:143], v[204:207], v[16:19]
	v_mfma_f32_16x16x32_bf16 v[8:11], v[156:159], v[204:207], v[8:11]
	v_mfma_f32_16x16x32_bf16 v[60:63], v[152:155], v[184:187], v[60:63]
	v_mfma_f32_16x16x32_bf16 v[56:59], v[160:163], v[184:187], v[56:59]
	v_mfma_f32_16x16x32_bf16 v[48:51], v[152:155], v[192:195], v[48:51]
	v_mfma_f32_16x16x32_bf16 v[40:43], v[160:163], v[192:195], v[40:43]
	v_mfma_f32_16x16x32_bf16 v[32:35], v[152:155], v[200:203], v[32:35]
	v_mfma_f32_16x16x32_bf16 v[24:27], v[160:163], v[200:203], v[24:27]
	v_mfma_f32_16x16x32_bf16 v[16:19], v[152:155], v[208:211], v[16:19]
	v_mfma_f32_16x16x32_bf16 v[8:11], v[160:163], v[208:211], v[8:11]
	v_mfma_f32_16x16x32_bf16 v[52:55], v[164:167], v[180:183], v[52:55]
	v_mfma_f32_16x16x32_bf16 v[44:47], v[172:175], v[180:183], v[44:47]
	v_mfma_f32_16x16x32_bf16 v[36:39], v[164:167], v[188:191], v[36:39]
	v_mfma_f32_16x16x32_bf16 v[28:31], v[172:175], v[188:191], v[28:31]
	v_mfma_f32_16x16x32_bf16 v[20:23], v[164:167], v[196:199], v[20:23]
	v_mfma_f32_16x16x32_bf16 v[12:15], v[172:175], v[196:199], v[12:15]
	v_mfma_f32_16x16x32_bf16 v[4:7], v[164:167], v[204:207], v[4:7]
	v_mfma_f32_16x16x32_bf16 v[0:3], v[172:175], v[204:207], v[0:3]
	v_mfma_f32_16x16x32_bf16 v[52:55], v[168:171], v[184:187], v[52:55]
	v_mfma_f32_16x16x32_bf16 v[44:47], v[176:179], v[184:187], v[44:47]
	v_mfma_f32_16x16x32_bf16 v[36:39], v[168:171], v[192:195], v[36:39]
	v_mfma_f32_16x16x32_bf16 v[28:31], v[176:179], v[192:195], v[28:31]
	v_mfma_f32_16x16x32_bf16 v[20:23], v[168:171], v[200:203], v[20:23]
	v_mfma_f32_16x16x32_bf16 v[12:15], v[176:179], v[200:203], v[12:15]
	v_mfma_f32_16x16x32_bf16 v[4:7], v[168:171], v[208:211], v[4:7]
	v_mfma_f32_16x16x32_bf16 v[0:3], v[176:179], v[208:211], v[0:3]
	s_setprio 0
	s_barrier
	s_add_i32 s3, 0, 0x18000
	s_add_i32 s37, 0, 0x1c000
	v_add_u32_e32 v160, s3, v147
	v_add_u32_e32 v176, s37, v147
	ds_read_b128 v[140:143], v160
	ds_read_b128 v[152:155], v160 offset:1024
	ds_read_b128 v[156:159], v160 offset:2048
	ds_read_b128 v[160:163], v160 offset:3072
	ds_read_b128 v[164:167], v176
	ds_read_b128 v[168:171], v176 offset:1024
	ds_read_b128 v[172:175], v176 offset:2048
	ds_read_b128 v[176:179], v176 offset:3072
	s_add_u32 s42, s90, 0x200000
	s_addc_u32 s43, s91, 0
	s_mov_b32 m0, s25
	ds_read_b128 v[180:183], v151 offset:32768
	ds_read_b128 v[184:187], v151 offset:33792
	ds_read_b128 v[188:191], v151 offset:34816
	ds_read_b128 v[192:195], v151 offset:35840
	ds_read_b128 v[196:199], v151 offset:36864
	ds_read_b128 v[200:203], v151 offset:37888
	ds_read_b128 v[204:207], v151 offset:38912
	ds_read_b128 v[208:211], v151 offset:39936
	global_load_lds_dwordx4 v128, s[42:43]
	v_lshl_add_u64 v[218:219], s[42:43], 0, v[130:131]
	s_mov_b32 m0, s30
	s_nop 0
	global_load_lds_dwordx4 v[218:219], off
	s_waitcnt vmcnt(8)
	s_waitcnt lgkmcnt(0)
	s_barrier
	s_setprio 1
	s_waitcnt lgkmcnt(0)
	v_mfma_f32_16x16x32_bf16 v[124:127], v[140:143], v[180:183], v[124:127]
	v_mfma_f32_16x16x32_bf16 v[120:123], v[156:159], v[180:183], v[120:123]
	v_mfma_f32_16x16x32_bf16 v[112:115], v[140:143], v[188:191], v[112:115]
	v_mfma_f32_16x16x32_bf16 v[104:107], v[156:159], v[188:191], v[104:107]
	v_mfma_f32_16x16x32_bf16 v[96:99], v[140:143], v[196:199], v[96:99]
	v_mfma_f32_16x16x32_bf16 v[88:91], v[156:159], v[196:199], v[88:91]
	v_mfma_f32_16x16x32_bf16 v[80:83], v[140:143], v[204:207], v[80:83]
	v_mfma_f32_16x16x32_bf16 v[72:75], v[156:159], v[204:207], v[72:75]
	v_mfma_f32_16x16x32_bf16 v[124:127], v[152:155], v[184:187], v[124:127]
	v_mfma_f32_16x16x32_bf16 v[120:123], v[160:163], v[184:187], v[120:123]
	v_mfma_f32_16x16x32_bf16 v[112:115], v[152:155], v[192:195], v[112:115]
	v_mfma_f32_16x16x32_bf16 v[104:107], v[160:163], v[192:195], v[104:107]
	v_mfma_f32_16x16x32_bf16 v[96:99], v[152:155], v[200:203], v[96:99]
	v_mfma_f32_16x16x32_bf16 v[88:91], v[160:163], v[200:203], v[88:91]
	v_mfma_f32_16x16x32_bf16 v[80:83], v[152:155], v[208:211], v[80:83]
	v_mfma_f32_16x16x32_bf16 v[72:75], v[160:163], v[208:211], v[72:75]
	v_mfma_f32_16x16x32_bf16 v[116:119], v[164:167], v[180:183], v[116:119]
	v_mfma_f32_16x16x32_bf16 v[108:111], v[172:175], v[180:183], v[108:111]
	v_mfma_f32_16x16x32_bf16 v[100:103], v[164:167], v[188:191], v[100:103]
	v_mfma_f32_16x16x32_bf16 v[92:95], v[172:175], v[188:191], v[92:95]
	v_mfma_f32_16x16x32_bf16 v[84:87], v[164:167], v[196:199], v[84:87]
	v_mfma_f32_16x16x32_bf16 v[76:79], v[172:175], v[196:199], v[76:79]
	v_mfma_f32_16x16x32_bf16 v[68:71], v[164:167], v[204:207], v[68:71]
	v_mfma_f32_16x16x32_bf16 v[64:67], v[172:175], v[204:207], v[64:67]
	v_mfma_f32_16x16x32_bf16 v[116:119], v[168:171], v[184:187], v[116:119]
	v_mfma_f32_16x16x32_bf16 v[108:111], v[176:179], v[184:187], v[108:111]
	v_mfma_f32_16x16x32_bf16 v[100:103], v[168:171], v[192:195], v[100:103]
	v_mfma_f32_16x16x32_bf16 v[92:95], v[176:179], v[192:195], v[92:95]
	v_mfma_f32_16x16x32_bf16 v[84:87], v[168:171], v[200:203], v[84:87]
	v_mfma_f32_16x16x32_bf16 v[76:79], v[176:179], v[200:203], v[76:79]
	v_mfma_f32_16x16x32_bf16 v[68:71], v[168:171], v[208:211], v[68:71]
	v_mfma_f32_16x16x32_bf16 v[64:67], v[176:179], v[208:211], v[64:67]
	s_setprio 0
	s_barrier
	s_add_i32 s3, s3, s9
	s_add_u32 s42, s88, 0x80
	s_addc_u32 s43, s89, 0
	s_mov_b32 m0, s3
	ds_read_b128 v[180:183], v151 offset:49152
	ds_read_b128 v[184:187], v151 offset:50176
	ds_read_b128 v[188:191], v151 offset:51200
	ds_read_b128 v[192:195], v151 offset:52224
	ds_read_b128 v[196:199], v151 offset:53248
	ds_read_b128 v[200:203], v151 offset:54272
	ds_read_b128 v[204:207], v151 offset:55296
	ds_read_b128 v[208:211], v151 offset:56320
	global_load_lds_dwordx4 v128, s[42:43]
	s_add_i32 m0, s3, 0x2000
	s_add_i32 s3, s37, s9
	global_load_lds_dwordx4 v130, s[42:43]
	s_add_u32 s42, s42, 0x200000
	s_addc_u32 s43, s43, 0
	s_mov_b32 m0, s3
	s_nop 0
	global_load_lds_dwordx4 v128, s[42:43]
	s_add_i32 m0, s3, 0x2000
	s_nop 0
	global_load_lds_dwordx4 v130, s[42:43]
	s_add_u32 s90, s90, 0x80
	s_addc_u32 s91, s91, 0
	s_mov_b32 m0, s8
	s_nop 0
	global_load_lds_dwordx4 v128, s[90:91]
	s_mov_b32 m0, s48
	s_nop 0
	global_load_lds_dwordx4 v130, s[90:91]
	s_waitcnt vmcnt(8)
	s_waitcnt lgkmcnt(0)
	s_barrier
	s_setprio 1
	s_waitcnt lgkmcnt(0)
	v_mfma_f32_16x16x32_bf16 v[60:63], v[140:143], v[180:183], v[60:63]
	v_mfma_f32_16x16x32_bf16 v[56:59], v[156:159], v[180:183], v[56:59]
	v_mfma_f32_16x16x32_bf16 v[48:51], v[140:143], v[188:191], v[48:51]
	v_mfma_f32_16x16x32_bf16 v[40:43], v[156:159], v[188:191], v[40:43]
	v_mfma_f32_16x16x32_bf16 v[32:35], v[140:143], v[196:199], v[32:35]
	v_mfma_f32_16x16x32_bf16 v[24:27], v[156:159], v[196:199], v[24:27]
	v_mfma_f32_16x16x32_bf16 v[16:19], v[140:143], v[204:207], v[16:19]
	v_mfma_f32_16x16x32_bf16 v[8:11], v[156:159], v[204:207], v[8:11]
	v_mfma_f32_16x16x32_bf16 v[60:63], v[152:155], v[184:187], v[60:63]
	v_mfma_f32_16x16x32_bf16 v[56:59], v[160:163], v[184:187], v[56:59]
	v_mfma_f32_16x16x32_bf16 v[48:51], v[152:155], v[192:195], v[48:51]
	v_mfma_f32_16x16x32_bf16 v[40:43], v[160:163], v[192:195], v[40:43]
	v_mfma_f32_16x16x32_bf16 v[32:35], v[152:155], v[200:203], v[32:35]
	v_mfma_f32_16x16x32_bf16 v[24:27], v[160:163], v[200:203], v[24:27]
	v_mfma_f32_16x16x32_bf16 v[16:19], v[152:155], v[208:211], v[16:19]
	v_mfma_f32_16x16x32_bf16 v[8:11], v[160:163], v[208:211], v[8:11]
	v_mfma_f32_16x16x32_bf16 v[52:55], v[164:167], v[180:183], v[52:55]
	v_mfma_f32_16x16x32_bf16 v[44:47], v[172:175], v[180:183], v[44:47]
	v_mfma_f32_16x16x32_bf16 v[36:39], v[164:167], v[188:191], v[36:39]
	v_mfma_f32_16x16x32_bf16 v[28:31], v[172:175], v[188:191], v[28:31]
	v_mfma_f32_16x16x32_bf16 v[20:23], v[164:167], v[196:199], v[20:23]
	v_mfma_f32_16x16x32_bf16 v[12:15], v[172:175], v[196:199], v[12:15]
	v_mfma_f32_16x16x32_bf16 v[4:7], v[164:167], v[204:207], v[4:7]
	v_mfma_f32_16x16x32_bf16 v[0:3], v[172:175], v[204:207], v[0:3]
	v_mfma_f32_16x16x32_bf16 v[52:55], v[168:171], v[184:187], v[52:55]
	v_mfma_f32_16x16x32_bf16 v[44:47], v[176:179], v[184:187], v[44:47]
	v_mfma_f32_16x16x32_bf16 v[36:39], v[168:171], v[192:195], v[36:39]
	v_mfma_f32_16x16x32_bf16 v[28:31], v[176:179], v[192:195], v[28:31]
	v_mfma_f32_16x16x32_bf16 v[20:23], v[168:171], v[200:203], v[20:23]
	v_mfma_f32_16x16x32_bf16 v[12:15], v[176:179], v[200:203], v[12:15]
	v_mfma_f32_16x16x32_bf16 v[4:7], v[168:171], v[208:211], v[4:7]
	v_mfma_f32_16x16x32_bf16 v[0:3], v[176:179], v[208:211], v[0:3]
	s_setprio 0
	s_add_i32 s36, s36, 2
	s_add_u32 s86, s86, 0x100
	s_addc_u32 s87, s87, 0
	s_add_u32 s33, s33, 0x100
	s_addc_u32 s35, s35, 0
	s_cmpk_gt_u32 s36, 0x7d
	s_barrier
	s_cbranch_scc0 .LBB0_1700
	s_and_b64 vcc, exec, s[14:15]
	s_cbranch_vccz .LBB0_1703
	s_barrier

.LBB0_1773:
	ds_read_b128 v[128:131], v173
	ds_read_b128 v[132:135], v173 offset:1024
	ds_read_b128 v[158:161], v173 offset:2048
	ds_read_b128 v[178:181], v173 offset:3072
	ds_read_b128 v[182:185], v174
	ds_read_b128 v[186:189], v174 offset:1024
	ds_read_b128 v[190:193], v174 offset:2048
	ds_read_b128 v[194:197], v174 offset:3072
	s_add_u32 s3, s34, 0xfff80080
	s_addc_u32 s19, s35, -1
	s_cmp_eq_u32 s18, 28
	s_cselect_b32 vcc_hi, s0, s19
	s_cselect_b32 vcc_lo, s1, s3
	s_cselect_b32 s97, s8, s17
	s_cselect_b32 s96, s9, s15
	s_add_i32 m0, s48, 0xc000
	ds_read_b128 v[198:201], v175
	ds_read_b128 v[202:205], v175 offset:1024
	ds_read_b128 v[206:209], v175 offset:2048
	ds_read_b128 v[210:213], v175 offset:3072
	ds_read_b128 v[214:217], v175 offset:4096
	ds_read_b128 v[218:221], v175 offset:5120
	ds_read_b128 v[222:225], v175 offset:6144
	ds_read_b128 v[230:233], v175 offset:7168
	global_load_lds_dwordx4 v148, s[34:35]
	s_add_i32 m0, s48, 0xe000
	s_nop 0
	global_load_lds_dwordx4 v150, s[34:35]
	s_waitcnt vmcnt(8)
	s_waitcnt lgkmcnt(0)
	s_barrier
	s_setprio 1
	s_waitcnt lgkmcnt(0)
	v_mfma_f32_16x16x32_bf16 v[124:127], v[128:131], v[198:201], v[124:127]
	v_mfma_f32_16x16x32_bf16 v[120:123], v[158:161], v[198:201], v[120:123]
	v_mfma_f32_16x16x32_bf16 v[108:111], v[128:131], v[206:209], v[108:111]
	v_mfma_f32_16x16x32_bf16 v[104:107], v[158:161], v[206:209], v[104:107]
	v_mfma_f32_16x16x32_bf16 v[92:95], v[128:131], v[214:217], v[92:95]
	v_mfma_f32_16x16x32_bf16 v[88:91], v[158:161], v[214:217], v[88:91]
	v_mfma_f32_16x16x32_bf16 v[76:79], v[128:131], v[222:225], v[76:79]
	v_mfma_f32_16x16x32_bf16 v[72:75], v[158:161], v[222:225], v[72:75]
	v_mfma_f32_16x16x32_bf16 v[124:127], v[132:135], v[202:205], v[124:127]
	v_mfma_f32_16x16x32_bf16 v[120:123], v[178:181], v[202:205], v[120:123]
	v_mfma_f32_16x16x32_bf16 v[108:111], v[132:135], v[210:213], v[108:111]
	v_mfma_f32_16x16x32_bf16 v[104:107], v[178:181], v[210:213], v[104:107]
	v_mfma_f32_16x16x32_bf16 v[92:95], v[132:135], v[218:221], v[92:95]
	v_mfma_f32_16x16x32_bf16 v[88:91], v[178:181], v[218:221], v[88:91]
	v_mfma_f32_16x16x32_bf16 v[76:79], v[132:135], v[230:233], v[76:79]
	v_mfma_f32_16x16x32_bf16 v[72:75], v[178:181], v[230:233], v[72:75]
	v_mfma_f32_16x16x32_bf16 v[116:119], v[182:185], v[198:201], v[116:119]
	v_mfma_f32_16x16x32_bf16 v[112:115], v[190:193], v[198:201], v[112:115]
	v_mfma_f32_16x16x32_bf16 v[100:103], v[182:185], v[206:209], v[100:103]
	v_mfma_f32_16x16x32_bf16 v[96:99], v[190:193], v[206:209], v[96:99]
	v_mfma_f32_16x16x32_bf16 v[84:87], v[182:185], v[214:217], v[84:87]
	v_mfma_f32_16x16x32_bf16 v[80:83], v[190:193], v[214:217], v[80:83]
	v_mfma_f32_16x16x32_bf16 v[68:71], v[182:185], v[222:225], v[68:71]
	v_mfma_f32_16x16x32_bf16 v[64:67], v[190:193], v[222:225], v[64:67]
	v_mfma_f32_16x16x32_bf16 v[116:119], v[186:189], v[202:205], v[116:119]
	v_mfma_f32_16x16x32_bf16 v[112:115], v[194:197], v[202:205], v[112:115]
	v_mfma_f32_16x16x32_bf16 v[100:103], v[186:189], v[210:213], v[100:103]
	v_mfma_f32_16x16x32_bf16 v[96:99], v[194:197], v[210:213], v[96:99]
	v_mfma_f32_16x16x32_bf16 v[84:87], v[186:189], v[218:221], v[84:87]
	v_mfma_f32_16x16x32_bf16 v[80:83], v[194:197], v[218:221], v[80:83]
	v_mfma_f32_16x16x32_bf16 v[68:71], v[186:189], v[230:233], v[68:71]
	v_mfma_f32_16x16x32_bf16 v[64:67], v[194:197], v[230:233], v[64:67]
	s_setprio 0
	s_barrier
	s_add_i32 s3, s76, s25
	s_mov_b32 m0, s3
	ds_read_b128 v[198:201], v175 offset:16384
	ds_read_b128 v[202:205], v175 offset:17408
	ds_read_b128 v[206:209], v175 offset:18432
	ds_read_b128 v[210:213], v175 offset:19456
	ds_read_b128 v[214:217], v175 offset:20480
	ds_read_b128 v[218:221], v175 offset:21504
	ds_read_b128 v[222:225], v175 offset:22528
	ds_read_b128 v[230:233], v175 offset:23552
	global_load_lds_dwordx4 v138, s[96:97]
	s_add_i32 m0, s3, 0x2000
	s_add_u32 s36, s96, 0x80000
	s_addc_u32 s37, s97, 0
	s_add_i32 s3, s77, s25
	global_load_lds_dwordx4 v142, s[96:97]
	s_mov_b32 m0, s3
	s_nop 0
	global_load_lds_dwordx4 v138, s[36:37]
	s_add_i32 m0, s3, 0x2000
	s_nop 0
	global_load_lds_dwordx4 v142, s[36:37]
	s_mov_b32 m0, s48
	s_nop 0
	global_load_lds_dwordx4 v136, vcc
	s_mov_b32 m0, s49
	s_nop 0
	global_load_lds_dwordx4 v140, vcc
	s_waitcnt vmcnt(8)
	s_waitcnt lgkmcnt(0)
	s_barrier
	s_setprio 1
	s_waitcnt lgkmcnt(0)
	v_mfma_f32_16x16x32_bf16 v[60:63], v[128:131], v[198:201], v[60:63]
	v_mfma_f32_16x16x32_bf16 v[56:59], v[158:161], v[198:201], v[56:59]
	v_mfma_f32_16x16x32_bf16 v[44:47], v[128:131], v[206:209], v[44:47]
	v_mfma_f32_16x16x32_bf16 v[40:43], v[158:161], v[206:209], v[40:43]
	v_mfma_f32_16x16x32_bf16 v[28:31], v[128:131], v[214:217], v[28:31]
	v_mfma_f32_16x16x32_bf16 v[24:27], v[158:161], v[214:217], v[24:27]
	v_mfma_f32_16x16x32_bf16 v[12:15], v[128:131], v[222:225], v[12:15]
	v_mfma_f32_16x16x32_bf16 v[8:11], v[158:161], v[222:225], v[8:11]
	v_mfma_f32_16x16x32_bf16 v[60:63], v[132:135], v[202:205], v[60:63]
	v_mfma_f32_16x16x32_bf16 v[56:59], v[178:181], v[202:205], v[56:59]
	v_mfma_f32_16x16x32_bf16 v[44:47], v[132:135], v[210:213], v[44:47]
	v_mfma_f32_16x16x32_bf16 v[40:43], v[178:181], v[210:213], v[40:43]
	v_mfma_f32_16x16x32_bf16 v[28:31], v[132:135], v[218:221], v[28:31]
	v_mfma_f32_16x16x32_bf16 v[24:27], v[178:181], v[218:221], v[24:27]
	v_mfma_f32_16x16x32_bf16 v[12:15], v[132:135], v[230:233], v[12:15]
	v_mfma_f32_16x16x32_bf16 v[8:11], v[178:181], v[230:233], v[8:11]
	v_mfma_f32_16x16x32_bf16 v[52:55], v[182:185], v[198:201], v[52:55]
	v_mfma_f32_16x16x32_bf16 v[48:51], v[190:193], v[198:201], v[48:51]
	v_mfma_f32_16x16x32_bf16 v[36:39], v[182:185], v[206:209], v[36:39]
	v_mfma_f32_16x16x32_bf16 v[32:35], v[190:193], v[206:209], v[32:35]
	v_mfma_f32_16x16x32_bf16 v[20:23], v[182:185], v[214:217], v[20:23]
	v_mfma_f32_16x16x32_bf16 v[16:19], v[190:193], v[214:217], v[16:19]
	v_mfma_f32_16x16x32_bf16 v[4:7], v[182:185], v[222:225], v[4:7]
	v_mfma_f32_16x16x32_bf16 v[0:3], v[190:193], v[222:225], v[0:3]
	v_mfma_f32_16x16x32_bf16 v[52:55], v[186:189], v[202:205], v[52:55]
	v_mfma_f32_16x16x32_bf16 v[48:51], v[194:197], v[202:205], v[48:51]
	v_mfma_f32_16x16x32_bf16 v[36:39], v[186:189], v[210:213], v[36:39]
	v_mfma_f32_16x16x32_bf16 v[32:35], v[194:197], v[210:213], v[32:35]
	v_mfma_f32_16x16x32_bf16 v[20:23], v[186:189], v[218:221], v[20:23]
	v_mfma_f32_16x16x32_bf16 v[16:19], v[194:197], v[218:221], v[16:19]
	v_mfma_f32_16x16x32_bf16 v[4:7], v[186:189], v[230:233], v[4:7]
	v_mfma_f32_16x16x32_bf16 v[0:3], v[194:197], v[230:233], v[0:3]
	s_setprio 0
	s_barrier
	s_add_i32 s3, 0, 0x18000
	v_add_u32_e32 v144, s3, v165
	s_add_i32 s19, 0, 0x1c000
	ds_read_b128 v[128:131], v144
	ds_read_b128 v[132:135], v144 offset:1024
	ds_read_b128 v[158:161], v144 offset:2048
	ds_read_b128 v[178:181], v144 offset:3072
	v_add_u32_e32 v144, s19, v165
	ds_read_b128 v[182:185], v144
	ds_read_b128 v[186:189], v144 offset:1024
	ds_read_b128 v[190:193], v144 offset:2048
	ds_read_b128 v[194:197], v144 offset:3072
	s_add_u32 s36, vcc_lo, 0x80000
	s_addc_u32 s37, vcc_hi, 0
	s_mov_b32 m0, s52
	ds_read_b128 v[198:201], v175 offset:32768
	ds_read_b128 v[202:205], v175 offset:33792
	ds_read_b128 v[206:209], v175 offset:34816
	ds_read_b128 v[210:213], v175 offset:35840
	ds_read_b128 v[214:217], v175 offset:36864
	ds_read_b128 v[218:221], v175 offset:37888
	ds_read_b128 v[222:225], v175 offset:38912
	ds_read_b128 v[230:233], v175 offset:39936
	global_load_lds_dwordx4 v136, s[36:37]
	s_mov_b32 m0, s53
	s_nop 0
	global_load_lds_dwordx4 v140, s[36:37]
	s_waitcnt vmcnt(8)
	s_waitcnt lgkmcnt(0)
	s_barrier
	s_setprio 1
	s_waitcnt lgkmcnt(0)
	v_mfma_f32_16x16x32_bf16 v[124:127], v[128:131], v[198:201], v[124:127]
	v_mfma_f32_16x16x32_bf16 v[120:123], v[158:161], v[198:201], v[120:123]
	v_mfma_f32_16x16x32_bf16 v[108:111], v[128:131], v[206:209], v[108:111]
	v_mfma_f32_16x16x32_bf16 v[104:107], v[158:161], v[206:209], v[104:107]
	v_mfma_f32_16x16x32_bf16 v[92:95], v[128:131], v[214:217], v[92:95]
	v_mfma_f32_16x16x32_bf16 v[88:91], v[158:161], v[214:217], v[88:91]
	v_mfma_f32_16x16x32_bf16 v[76:79], v[128:131], v[222:225], v[76:79]
	v_mfma_f32_16x16x32_bf16 v[72:75], v[158:161], v[222:225], v[72:75]
	v_mfma_f32_16x16x32_bf16 v[124:127], v[132:135], v[202:205], v[124:127]
	v_mfma_f32_16x16x32_bf16 v[120:123], v[178:181], v[202:205], v[120:123]
	v_mfma_f32_16x16x32_bf16 v[108:111], v[132:135], v[210:213], v[108:111]
	v_mfma_f32_16x16x32_bf16 v[104:107], v[178:181], v[210:213], v[104:107]
	v_mfma_f32_16x16x32_bf16 v[92:95], v[132:135], v[218:221], v[92:95]
	v_mfma_f32_16x16x32_bf16 v[88:91], v[178:181], v[218:221], v[88:91]
	v_mfma_f32_16x16x32_bf16 v[76:79], v[132:135], v[230:233], v[76:79]
	v_mfma_f32_16x16x32_bf16 v[72:75], v[178:181], v[230:233], v[72:75]
	v_mfma_f32_16x16x32_bf16 v[116:119], v[182:185], v[198:201], v[116:119]
	v_mfma_f32_16x16x32_bf16 v[112:115], v[190:193], v[198:201], v[112:115]
	v_mfma_f32_16x16x32_bf16 v[100:103], v[182:185], v[206:209], v[100:103]
	v_mfma_f32_16x16x32_bf16 v[96:99], v[190:193], v[206:209], v[96:99]
	v_mfma_f32_16x16x32_bf16 v[84:87], v[182:185], v[214:217], v[84:87]
	v_mfma_f32_16x16x32_bf16 v[80:83], v[190:193], v[214:217], v[80:83]
	v_mfma_f32_16x16x32_bf16 v[68:71], v[182:185], v[222:225], v[68:71]
	v_mfma_f32_16x16x32_bf16 v[64:67], v[190:193], v[222:225], v[64:67]
	v_mfma_f32_16x16x32_bf16 v[116:119], v[186:189], v[202:205], v[116:119]
	v_mfma_f32_16x16x32_bf16 v[112:115], v[194:197], v[202:205], v[112:115]
	v_mfma_f32_16x16x32_bf16 v[100:103], v[186:189], v[210:213], v[100:103]
	v_mfma_f32_16x16x32_bf16 v[96:99], v[194:197], v[210:213], v[96:99]
	v_mfma_f32_16x16x32_bf16 v[84:87], v[186:189], v[218:221], v[84:87]
	v_mfma_f32_16x16x32_bf16 v[80:83], v[194:197], v[218:221], v[80:83]
	v_mfma_f32_16x16x32_bf16 v[68:71], v[186:189], v[230:233], v[68:71]
	v_mfma_f32_16x16x32_bf16 v[64:67], v[194:197], v[230:233], v[64:67]
	s_setprio 0
	s_barrier
	s_add_i32 s3, s3, s25
	s_add_u32 s36, s96, 0x80
	s_addc_u32 s37, s97, 0
	s_mov_b32 m0, s3
	ds_read_b128 v[198:201], v175 offset:49152
	ds_read_b128 v[202:205], v175 offset:50176
	ds_read_b128 v[206:209], v175 offset:51200
	ds_read_b128 v[210:213], v175 offset:52224
	ds_read_b128 v[214:217], v175 offset:53248
	ds_read_b128 v[218:221], v175 offset:54272
	ds_read_b128 v[222:225], v175 offset:55296
	ds_read_b128 v[230:233], v175 offset:56320
	global_load_lds_dwordx4 v138, s[36:37]
	s_add_i32 m0, s3, 0x2000
	s_add_i32 s3, s19, s25
	global_load_lds_dwordx4 v142, s[36:37]
	s_add_u32 s36, s36, 0x80000
	s_addc_u32 s37, s37, 0
	s_mov_b32 m0, s3
	s_nop 0
	global_load_lds_dwordx4 v138, s[36:37]
	s_add_i32 m0, s3, 0x2000
	s_nop 0
	global_load_lds_dwordx4 v142, s[36:37]
	s_add_u32 vcc_lo, vcc_lo, 0x80
	s_addc_u32 vcc_hi, vcc_hi, 0
	s_mov_b32 m0, s56
	s_nop 0
	global_load_lds_dwordx4 v136, vcc
	s_mov_b32 m0, s57
	s_nop 0
	global_load_lds_dwordx4 v140, vcc
	s_waitcnt vmcnt(8)
	s_waitcnt lgkmcnt(0)
	s_barrier
	s_setprio 1
	s_waitcnt lgkmcnt(0)
	v_mfma_f32_16x16x32_bf16 v[60:63], v[128:131], v[198:201], v[60:63]
	v_mfma_f32_16x16x32_bf16 v[56:59], v[158:161], v[198:201], v[56:59]
	v_mfma_f32_16x16x32_bf16 v[44:47], v[128:131], v[206:209], v[44:47]
	v_mfma_f32_16x16x32_bf16 v[40:43], v[158:161], v[206:209], v[40:43]
	v_mfma_f32_16x16x32_bf16 v[28:31], v[128:131], v[214:217], v[28:31]
	v_mfma_f32_16x16x32_bf16 v[24:27], v[158:161], v[214:217], v[24:27]
	v_mfma_f32_16x16x32_bf16 v[12:15], v[128:131], v[222:225], v[12:15]
	v_mfma_f32_16x16x32_bf16 v[8:11], v[158:161], v[222:225], v[8:11]
	v_mfma_f32_16x16x32_bf16 v[60:63], v[132:135], v[202:205], v[60:63]
	v_mfma_f32_16x16x32_bf16 v[56:59], v[178:181], v[202:205], v[56:59]
	v_mfma_f32_16x16x32_bf16 v[44:47], v[132:135], v[210:213], v[44:47]
	v_mfma_f32_16x16x32_bf16 v[40:43], v[178:181], v[210:213], v[40:43]
	v_mfma_f32_16x16x32_bf16 v[28:31], v[132:135], v[218:221], v[28:31]
	v_mfma_f32_16x16x32_bf16 v[24:27], v[178:181], v[218:221], v[24:27]
	v_mfma_f32_16x16x32_bf16 v[12:15], v[132:135], v[230:233], v[12:15]
	v_mfma_f32_16x16x32_bf16 v[8:11], v[178:181], v[230:233], v[8:11]
	v_mfma_f32_16x16x32_bf16 v[52:55], v[182:185], v[198:201], v[52:55]
	v_mfma_f32_16x16x32_bf16 v[48:51], v[190:193], v[198:201], v[48:51]
	v_mfma_f32_16x16x32_bf16 v[36:39], v[182:185], v[206:209], v[36:39]
	v_mfma_f32_16x16x32_bf16 v[32:35], v[190:193], v[206:209], v[32:35]
	v_mfma_f32_16x16x32_bf16 v[20:23], v[182:185], v[214:217], v[20:23]
	v_mfma_f32_16x16x32_bf16 v[16:19], v[190:193], v[214:217], v[16:19]
	v_mfma_f32_16x16x32_bf16 v[4:7], v[182:185], v[222:225], v[4:7]
	v_mfma_f32_16x16x32_bf16 v[0:3], v[190:193], v[222:225], v[0:3]
	v_mfma_f32_16x16x32_bf16 v[52:55], v[186:189], v[202:205], v[52:55]
	v_mfma_f32_16x16x32_bf16 v[48:51], v[194:197], v[202:205], v[48:51]
	v_mfma_f32_16x16x32_bf16 v[36:39], v[186:189], v[210:213], v[36:39]
	v_mfma_f32_16x16x32_bf16 v[32:35], v[194:197], v[210:213], v[32:35]
	v_mfma_f32_16x16x32_bf16 v[20:23], v[186:189], v[218:221], v[20:23]
	v_mfma_f32_16x16x32_bf16 v[16:19], v[194:197], v[218:221], v[16:19]
	v_mfma_f32_16x16x32_bf16 v[4:7], v[186:189], v[230:233], v[4:7]
	v_mfma_f32_16x16x32_bf16 v[0:3], v[194:197], v[230:233], v[0:3]
	s_setprio 0
	s_add_i32 s18, s18, 2
	s_add_u32 s34, s34, 0x100
	s_addc_u32 s35, s35, 0
	s_add_u32 s15, s15, 0x100
	s_addc_u32 s17, s17, 0
	s_cmp_gt_u32 s18, 29
	s_barrier
	s_cbranch_scc0 .LBB0_1773
	s_and_b64 vcc, exec, s[84:85]
	s_cbranch_vccz .LBB0_1776
	s_barrier

.LBB0_2248:
	ds_read_b128 v[144:147], v153
	ds_read_b128 v[156:159], v153 offset:1024
	ds_read_b128 v[160:163], v153 offset:2048
	ds_read_b128 v[164:167], v153 offset:3072
	ds_read_b128 v[168:171], v154
	ds_read_b128 v[172:175], v154 offset:1024
	ds_read_b128 v[176:179], v154 offset:2048
	ds_read_b128 v[180:183], v154 offset:3072
	s_add_u32 s3, s52, 0xfffc0080
	s_addc_u32 s45, s53, -1
	s_cmp_eq_u32 s44, 12
	s_cselect_b32 s59, s0, s45
	s_cselect_b32 s58, s1, s3
	s_cselect_b32 s57, s17, s35
	s_cselect_b32 s56, s27, s33
	s_add_i32 m0, s9, 0xc000
	ds_read_b128 v[184:187], v155
	ds_read_b128 v[188:191], v155 offset:1024
	ds_read_b128 v[192:195], v155 offset:2048
	ds_read_b128 v[196:199], v155 offset:3072
	ds_read_b128 v[200:203], v155 offset:4096
	ds_read_b128 v[204:207], v155 offset:5120
	ds_read_b128 v[208:211], v155 offset:6144
	ds_read_b128 v[212:215], v155 offset:7168
	global_load_lds_dwordx4 v136, s[52:53]
	s_add_i32 m0, s9, 0xe000
	s_nop 0
	global_load_lds_dwordx4 v138, s[52:53]
	s_waitcnt vmcnt(8)
	s_waitcnt lgkmcnt(0)
	s_barrier
	s_setprio 1
	s_waitcnt lgkmcnt(0)
	v_mfma_f32_16x16x32_bf16 v[124:127], v[144:147], v[184:187], v[124:127]
	v_mfma_f32_16x16x32_bf16 v[120:123], v[160:163], v[184:187], v[120:123]
	v_mfma_f32_16x16x32_bf16 v[108:111], v[144:147], v[192:195], v[108:111]
	v_mfma_f32_16x16x32_bf16 v[104:107], v[160:163], v[192:195], v[104:107]
	v_mfma_f32_16x16x32_bf16 v[92:95], v[144:147], v[200:203], v[92:95]
	v_mfma_f32_16x16x32_bf16 v[88:91], v[160:163], v[200:203], v[88:91]
	v_mfma_f32_16x16x32_bf16 v[76:79], v[144:147], v[208:211], v[76:79]
	v_mfma_f32_16x16x32_bf16 v[72:75], v[160:163], v[208:211], v[72:75]
	v_mfma_f32_16x16x32_bf16 v[124:127], v[156:159], v[188:191], v[124:127]
	v_mfma_f32_16x16x32_bf16 v[120:123], v[164:167], v[188:191], v[120:123]
	v_mfma_f32_16x16x32_bf16 v[108:111], v[156:159], v[196:199], v[108:111]
	v_mfma_f32_16x16x32_bf16 v[104:107], v[164:167], v[196:199], v[104:107]
	v_mfma_f32_16x16x32_bf16 v[92:95], v[156:159], v[204:207], v[92:95]
	v_mfma_f32_16x16x32_bf16 v[88:91], v[164:167], v[204:207], v[88:91]
	v_mfma_f32_16x16x32_bf16 v[76:79], v[156:159], v[212:215], v[76:79]
	v_mfma_f32_16x16x32_bf16 v[72:75], v[164:167], v[212:215], v[72:75]
	v_mfma_f32_16x16x32_bf16 v[116:119], v[168:171], v[184:187], v[116:119]
	v_mfma_f32_16x16x32_bf16 v[112:115], v[176:179], v[184:187], v[112:115]
	v_mfma_f32_16x16x32_bf16 v[100:103], v[168:171], v[192:195], v[100:103]
	v_mfma_f32_16x16x32_bf16 v[96:99], v[176:179], v[192:195], v[96:99]
	v_mfma_f32_16x16x32_bf16 v[84:87], v[168:171], v[200:203], v[84:87]
	v_mfma_f32_16x16x32_bf16 v[80:83], v[176:179], v[200:203], v[80:83]
	v_mfma_f32_16x16x32_bf16 v[68:71], v[168:171], v[208:211], v[68:71]
	v_mfma_f32_16x16x32_bf16 v[64:67], v[176:179], v[208:211], v[64:67]
	v_mfma_f32_16x16x32_bf16 v[116:119], v[172:175], v[188:191], v[116:119]
	v_mfma_f32_16x16x32_bf16 v[112:115], v[180:183], v[188:191], v[112:115]
	v_mfma_f32_16x16x32_bf16 v[100:103], v[172:175], v[196:199], v[100:103]
	v_mfma_f32_16x16x32_bf16 v[96:99], v[180:183], v[196:199], v[96:99]
	v_mfma_f32_16x16x32_bf16 v[84:87], v[172:175], v[204:207], v[84:87]
	v_mfma_f32_16x16x32_bf16 v[80:83], v[180:183], v[204:207], v[80:83]
	v_mfma_f32_16x16x32_bf16 v[68:71], v[172:175], v[212:215], v[68:71]
	v_mfma_f32_16x16x32_bf16 v[64:67], v[180:183], v[212:215], v[64:67]
	s_setprio 0
	s_barrier
	s_add_i32 s3, s62, s8
	s_mov_b32 m0, s3
	ds_read_b128 v[184:187], v155 offset:16384
	ds_read_b128 v[188:191], v155 offset:17408
	ds_read_b128 v[192:195], v155 offset:18432
	ds_read_b128 v[196:199], v155 offset:19456
	ds_read_b128 v[200:203], v155 offset:20480
	ds_read_b128 v[204:207], v155 offset:21504
	ds_read_b128 v[208:211], v155 offset:22528
	ds_read_b128 v[212:215], v155 offset:23552
	global_load_lds_dwordx4 v130, s[56:57]
	s_add_i32 m0, s3, 0x2000
	s_add_u32 s50, s56, 0x40000
	s_addc_u32 s51, s57, 0
	s_add_i32 s3, s63, s8
	global_load_lds_dwordx4 v134, s[56:57]
	s_mov_b32 m0, s3
	s_nop 0
	global_load_lds_dwordx4 v130, s[50:51]
	s_add_i32 m0, s3, 0x2000
	s_nop 0
	global_load_lds_dwordx4 v134, s[50:51]
	s_mov_b32 m0, s9
	s_nop 0
	global_load_lds_dwordx4 v128, s[58:59]
	s_mov_b32 m0, s18
	s_nop 0
	global_load_lds_dwordx4 v132, s[58:59]
	s_waitcnt vmcnt(8)
	s_waitcnt lgkmcnt(0)
	s_barrier
	s_setprio 1
	s_waitcnt lgkmcnt(0)
	v_mfma_f32_16x16x32_bf16 v[60:63], v[144:147], v[184:187], v[60:63]
	v_mfma_f32_16x16x32_bf16 v[56:59], v[160:163], v[184:187], v[56:59]
	v_mfma_f32_16x16x32_bf16 v[44:47], v[144:147], v[192:195], v[44:47]
	v_mfma_f32_16x16x32_bf16 v[40:43], v[160:163], v[192:195], v[40:43]
	v_mfma_f32_16x16x32_bf16 v[28:31], v[144:147], v[200:203], v[28:31]
	v_mfma_f32_16x16x32_bf16 v[24:27], v[160:163], v[200:203], v[24:27]
	v_mfma_f32_16x16x32_bf16 v[12:15], v[144:147], v[208:211], v[12:15]
	v_mfma_f32_16x16x32_bf16 v[8:11], v[160:163], v[208:211], v[8:11]
	v_mfma_f32_16x16x32_bf16 v[60:63], v[156:159], v[188:191], v[60:63]
	v_mfma_f32_16x16x32_bf16 v[56:59], v[164:167], v[188:191], v[56:59]
	v_mfma_f32_16x16x32_bf16 v[44:47], v[156:159], v[196:199], v[44:47]
	v_mfma_f32_16x16x32_bf16 v[40:43], v[164:167], v[196:199], v[40:43]
	v_mfma_f32_16x16x32_bf16 v[28:31], v[156:159], v[204:207], v[28:31]
	v_mfma_f32_16x16x32_bf16 v[24:27], v[164:167], v[204:207], v[24:27]
	v_mfma_f32_16x16x32_bf16 v[12:15], v[156:159], v[212:215], v[12:15]
	v_mfma_f32_16x16x32_bf16 v[8:11], v[164:167], v[212:215], v[8:11]
	v_mfma_f32_16x16x32_bf16 v[52:55], v[168:171], v[184:187], v[52:55]
	v_mfma_f32_16x16x32_bf16 v[48:51], v[176:179], v[184:187], v[48:51]
	v_mfma_f32_16x16x32_bf16 v[36:39], v[168:171], v[192:195], v[36:39]
	v_mfma_f32_16x16x32_bf16 v[32:35], v[176:179], v[192:195], v[32:35]
	v_mfma_f32_16x16x32_bf16 v[20:23], v[168:171], v[200:203], v[20:23]
	v_mfma_f32_16x16x32_bf16 v[16:19], v[176:179], v[200:203], v[16:19]
	v_mfma_f32_16x16x32_bf16 v[4:7], v[168:171], v[208:211], v[4:7]
	v_mfma_f32_16x16x32_bf16 v[0:3], v[176:179], v[208:211], v[0:3]
	v_mfma_f32_16x16x32_bf16 v[52:55], v[172:175], v[188:191], v[52:55]
	v_mfma_f32_16x16x32_bf16 v[48:51], v[180:183], v[188:191], v[48:51]
	v_mfma_f32_16x16x32_bf16 v[36:39], v[172:175], v[196:199], v[36:39]
	v_mfma_f32_16x16x32_bf16 v[32:35], v[180:183], v[196:199], v[32:35]
	v_mfma_f32_16x16x32_bf16 v[20:23], v[172:175], v[204:207], v[20:23]
	v_mfma_f32_16x16x32_bf16 v[16:19], v[180:183], v[204:207], v[16:19]
	v_mfma_f32_16x16x32_bf16 v[4:7], v[172:175], v[212:215], v[4:7]
	v_mfma_f32_16x16x32_bf16 v[0:3], v[180:183], v[212:215], v[0:3]
	s_setprio 0
	s_barrier
	s_add_i32 s3, 0, 0x18000
	s_add_i32 s45, 0, 0x1c000
	v_add_u32_e32 v164, s3, v151
	v_add_u32_e32 v180, s45, v151
	ds_read_b128 v[144:147], v164
	ds_read_b128 v[156:159], v164 offset:1024
	ds_read_b128 v[160:163], v164 offset:2048
	ds_read_b128 v[164:167], v164 offset:3072
	ds_read_b128 v[168:171], v180
	ds_read_b128 v[172:175], v180 offset:1024
	ds_read_b128 v[176:179], v180 offset:2048
	ds_read_b128 v[180:183], v180 offset:3072
	s_add_u32 s50, s58, 0x40000
	s_addc_u32 s51, s59, 0
	s_mov_b32 m0, s19
	ds_read_b128 v[184:187], v155 offset:32768
	ds_read_b128 v[188:191], v155 offset:33792
	ds_read_b128 v[192:195], v155 offset:34816
	ds_read_b128 v[196:199], v155 offset:35840
	ds_read_b128 v[200:203], v155 offset:36864
	ds_read_b128 v[204:207], v155 offset:37888
	ds_read_b128 v[208:211], v155 offset:38912
	ds_read_b128 v[212:215], v155 offset:39936
	global_load_lds_dwordx4 v128, s[50:51]
	s_mov_b32 m0, s25
	s_nop 0
	global_load_lds_dwordx4 v132, s[50:51]
	s_waitcnt vmcnt(8)
	s_waitcnt lgkmcnt(0)
	s_barrier
	s_setprio 1
	s_waitcnt lgkmcnt(0)
	v_mfma_f32_16x16x32_bf16 v[124:127], v[144:147], v[184:187], v[124:127]
	v_mfma_f32_16x16x32_bf16 v[120:123], v[160:163], v[184:187], v[120:123]
	v_mfma_f32_16x16x32_bf16 v[108:111], v[144:147], v[192:195], v[108:111]
	v_mfma_f32_16x16x32_bf16 v[104:107], v[160:163], v[192:195], v[104:107]
	v_mfma_f32_16x16x32_bf16 v[92:95], v[144:147], v[200:203], v[92:95]
	v_mfma_f32_16x16x32_bf16 v[88:91], v[160:163], v[200:203], v[88:91]
	v_mfma_f32_16x16x32_bf16 v[76:79], v[144:147], v[208:211], v[76:79]
	v_mfma_f32_16x16x32_bf16 v[72:75], v[160:163], v[208:211], v[72:75]
	v_mfma_f32_16x16x32_bf16 v[124:127], v[156:159], v[188:191], v[124:127]
	v_mfma_f32_16x16x32_bf16 v[120:123], v[164:167], v[188:191], v[120:123]
	v_mfma_f32_16x16x32_bf16 v[108:111], v[156:159], v[196:199], v[108:111]
	v_mfma_f32_16x16x32_bf16 v[104:107], v[164:167], v[196:199], v[104:107]
	v_mfma_f32_16x16x32_bf16 v[92:95], v[156:159], v[204:207], v[92:95]
	v_mfma_f32_16x16x32_bf16 v[88:91], v[164:167], v[204:207], v[88:91]
	v_mfma_f32_16x16x32_bf16 v[76:79], v[156:159], v[212:215], v[76:79]
	v_mfma_f32_16x16x32_bf16 v[72:75], v[164:167], v[212:215], v[72:75]
	v_mfma_f32_16x16x32_bf16 v[116:119], v[168:171], v[184:187], v[116:119]
	v_mfma_f32_16x16x32_bf16 v[112:115], v[176:179], v[184:187], v[112:115]
	v_mfma_f32_16x16x32_bf16 v[100:103], v[168:171], v[192:195], v[100:103]
	v_mfma_f32_16x16x32_bf16 v[96:99], v[176:179], v[192:195], v[96:99]
	v_mfma_f32_16x16x32_bf16 v[84:87], v[168:171], v[200:203], v[84:87]
	v_mfma_f32_16x16x32_bf16 v[80:83], v[176:179], v[200:203], v[80:83]
	v_mfma_f32_16x16x32_bf16 v[68:71], v[168:171], v[208:211], v[68:71]
	v_mfma_f32_16x16x32_bf16 v[64:67], v[176:179], v[208:211], v[64:67]
	v_mfma_f32_16x16x32_bf16 v[116:119], v[172:175], v[188:191], v[116:119]
	v_mfma_f32_16x16x32_bf16 v[112:115], v[180:183], v[188:191], v[112:115]
	v_mfma_f32_16x16x32_bf16 v[100:103], v[172:175], v[196:199], v[100:103]
	v_mfma_f32_16x16x32_bf16 v[96:99], v[180:183], v[196:199], v[96:99]
	v_mfma_f32_16x16x32_bf16 v[84:87], v[172:175], v[204:207], v[84:87]
	v_mfma_f32_16x16x32_bf16 v[80:83], v[180:183], v[204:207], v[80:83]
	v_mfma_f32_16x16x32_bf16 v[68:71], v[172:175], v[212:215], v[68:71]
	v_mfma_f32_16x16x32_bf16 v[64:67], v[180:183], v[212:215], v[64:67]
	s_setprio 0
	s_barrier
	s_add_i32 s3, s3, s8
	s_add_u32 s50, s56, 0x80
	s_addc_u32 s51, s57, 0
	s_mov_b32 m0, s3
	ds_read_b128 v[184:187], v155 offset:49152
	ds_read_b128 v[188:191], v155 offset:50176
	ds_read_b128 v[192:195], v155 offset:51200
	ds_read_b128 v[196:199], v155 offset:52224
	ds_read_b128 v[200:203], v155 offset:53248
	ds_read_b128 v[204:207], v155 offset:54272
	ds_read_b128 v[208:211], v155 offset:55296
	ds_read_b128 v[212:215], v155 offset:56320
	global_load_lds_dwordx4 v130, s[50:51]
	s_add_i32 m0, s3, 0x2000
	s_add_i32 s3, s45, s8
	global_load_lds_dwordx4 v134, s[50:51]
	s_add_u32 s50, s50, 0x40000
	s_addc_u32 s51, s51, 0
	s_mov_b32 m0, s3
	s_nop 0
	global_load_lds_dwordx4 v130, s[50:51]
	s_add_i32 m0, s3, 0x2000
	s_nop 0
	global_load_lds_dwordx4 v134, s[50:51]
	s_add_u32 s58, s58, 0x80
	s_addc_u32 s59, s59, 0
	s_mov_b32 m0, s60
	s_nop 0
	global_load_lds_dwordx4 v128, s[58:59]
	s_mov_b32 m0, s61
	s_nop 0
	global_load_lds_dwordx4 v132, s[58:59]
	s_waitcnt vmcnt(8)
	s_waitcnt lgkmcnt(0)
	s_barrier
	s_setprio 1
	s_waitcnt lgkmcnt(0)
	v_mfma_f32_16x16x32_bf16 v[60:63], v[144:147], v[184:187], v[60:63]
	v_mfma_f32_16x16x32_bf16 v[56:59], v[160:163], v[184:187], v[56:59]
	v_mfma_f32_16x16x32_bf16 v[44:47], v[144:147], v[192:195], v[44:47]
	v_mfma_f32_16x16x32_bf16 v[40:43], v[160:163], v[192:195], v[40:43]
	v_mfma_f32_16x16x32_bf16 v[28:31], v[144:147], v[200:203], v[28:31]
	v_mfma_f32_16x16x32_bf16 v[24:27], v[160:163], v[200:203], v[24:27]
	v_mfma_f32_16x16x32_bf16 v[12:15], v[144:147], v[208:211], v[12:15]
	v_mfma_f32_16x16x32_bf16 v[8:11], v[160:163], v[208:211], v[8:11]
	v_mfma_f32_16x16x32_bf16 v[60:63], v[156:159], v[188:191], v[60:63]
	v_mfma_f32_16x16x32_bf16 v[56:59], v[164:167], v[188:191], v[56:59]
	v_mfma_f32_16x16x32_bf16 v[44:47], v[156:159], v[196:199], v[44:47]
	v_mfma_f32_16x16x32_bf16 v[40:43], v[164:167], v[196:199], v[40:43]
	v_mfma_f32_16x16x32_bf16 v[28:31], v[156:159], v[204:207], v[28:31]
	v_mfma_f32_16x16x32_bf16 v[24:27], v[164:167], v[204:207], v[24:27]
	v_mfma_f32_16x16x32_bf16 v[12:15], v[156:159], v[212:215], v[12:15]
	v_mfma_f32_16x16x32_bf16 v[8:11], v[164:167], v[212:215], v[8:11]
	v_mfma_f32_16x16x32_bf16 v[52:55], v[168:171], v[184:187], v[52:55]
	v_mfma_f32_16x16x32_bf16 v[48:51], v[176:179], v[184:187], v[48:51]
	v_mfma_f32_16x16x32_bf16 v[36:39], v[168:171], v[192:195], v[36:39]
	v_mfma_f32_16x16x32_bf16 v[32:35], v[176:179], v[192:195], v[32:35]
	v_mfma_f32_16x16x32_bf16 v[20:23], v[168:171], v[200:203], v[20:23]
	v_mfma_f32_16x16x32_bf16 v[16:19], v[176:179], v[200:203], v[16:19]
	v_mfma_f32_16x16x32_bf16 v[4:7], v[168:171], v[208:211], v[4:7]
	v_mfma_f32_16x16x32_bf16 v[0:3], v[176:179], v[208:211], v[0:3]
	v_mfma_f32_16x16x32_bf16 v[52:55], v[172:175], v[188:191], v[52:55]
	v_mfma_f32_16x16x32_bf16 v[48:51], v[180:183], v[188:191], v[48:51]
	v_mfma_f32_16x16x32_bf16 v[36:39], v[172:175], v[196:199], v[36:39]
	v_mfma_f32_16x16x32_bf16 v[32:35], v[180:183], v[196:199], v[32:35]
	v_mfma_f32_16x16x32_bf16 v[20:23], v[172:175], v[204:207], v[20:23]
	v_mfma_f32_16x16x32_bf16 v[16:19], v[180:183], v[204:207], v[16:19]
	v_mfma_f32_16x16x32_bf16 v[4:7], v[172:175], v[212:215], v[4:7]
	v_mfma_f32_16x16x32_bf16 v[0:3], v[180:183], v[212:215], v[0:3]
	s_setprio 0
	s_add_i32 s44, s44, 2
	s_add_u32 s52, s52, 0x100
	s_addc_u32 s53, s53, 0
	s_add_u32 s33, s33, 0x100
	s_addc_u32 s35, s35, 0
	s_cmp_gt_u32 s44, 13
	s_barrier
	s_cbranch_scc0 .LBB0_2248
	s_and_b64 vcc, exec, s[12:13]
	s_cbranch_vccz .LBB0_2251
	s_barrier

.LBB0_2272:
	ds_read_b128 v[144:147], v155
	ds_read_b128 v[148:151], v155 offset:1024
	ds_read_b128 v[158:161], v155 offset:2048
	ds_read_b128 v[162:165], v155 offset:3072
	ds_read_b128 v[166:169], v156
	ds_read_b128 v[170:173], v156 offset:1024
	ds_read_b128 v[174:177], v156 offset:2048
	ds_read_b128 v[178:181], v156 offset:3072
	s_add_u32 s3, s52, 0xfffe0080
	s_addc_u32 s51, s53, -1
	s_cmp_eq_u32 s50, 4
	s_cselect_b32 s59, s0, s51
	s_cselect_b32 s58, s1, s3
	s_cselect_b32 s57, s17, s45
	s_cselect_b32 s56, s35, s44
	s_add_i32 m0, s9, 0xc000
	ds_read_b128 v[182:185], v157
	ds_read_b128 v[186:189], v157 offset:1024
	ds_read_b128 v[190:193], v157 offset:2048
	ds_read_b128 v[194:197], v157 offset:3072
	ds_read_b128 v[198:201], v157 offset:4096
	ds_read_b128 v[202:205], v157 offset:5120
	ds_read_b128 v[206:209], v157 offset:6144
	ds_read_b128 v[210:213], v157 offset:7168
	global_load_lds_dwordx4 v136, s[52:53]
	s_add_i32 m0, s9, 0xe000
	s_nop 0
	global_load_lds_dwordx4 v138, s[52:53]
	s_waitcnt vmcnt(8)
	s_waitcnt lgkmcnt(0)
	s_barrier
	s_setprio 1
	s_waitcnt lgkmcnt(0)
	v_mfma_f32_16x16x32_bf16 v[124:127], v[144:147], v[182:185], v[124:127]
	v_mfma_f32_16x16x32_bf16 v[120:123], v[158:161], v[182:185], v[120:123]
	v_mfma_f32_16x16x32_bf16 v[108:111], v[144:147], v[190:193], v[108:111]
	v_mfma_f32_16x16x32_bf16 v[104:107], v[158:161], v[190:193], v[104:107]
	v_mfma_f32_16x16x32_bf16 v[92:95], v[144:147], v[198:201], v[92:95]
	v_mfma_f32_16x16x32_bf16 v[88:91], v[158:161], v[198:201], v[88:91]
	v_mfma_f32_16x16x32_bf16 v[76:79], v[144:147], v[206:209], v[76:79]
	v_mfma_f32_16x16x32_bf16 v[72:75], v[158:161], v[206:209], v[72:75]
	v_mfma_f32_16x16x32_bf16 v[124:127], v[148:151], v[186:189], v[124:127]
	v_mfma_f32_16x16x32_bf16 v[120:123], v[162:165], v[186:189], v[120:123]
	v_mfma_f32_16x16x32_bf16 v[108:111], v[148:151], v[194:197], v[108:111]
	v_mfma_f32_16x16x32_bf16 v[104:107], v[162:165], v[194:197], v[104:107]
	v_mfma_f32_16x16x32_bf16 v[92:95], v[148:151], v[202:205], v[92:95]
	v_mfma_f32_16x16x32_bf16 v[88:91], v[162:165], v[202:205], v[88:91]
	v_mfma_f32_16x16x32_bf16 v[76:79], v[148:151], v[210:213], v[76:79]
	v_mfma_f32_16x16x32_bf16 v[72:75], v[162:165], v[210:213], v[72:75]
	v_mfma_f32_16x16x32_bf16 v[116:119], v[166:169], v[182:185], v[116:119]
	v_mfma_f32_16x16x32_bf16 v[112:115], v[174:177], v[182:185], v[112:115]
	v_mfma_f32_16x16x32_bf16 v[100:103], v[166:169], v[190:193], v[100:103]
	v_mfma_f32_16x16x32_bf16 v[96:99], v[174:177], v[190:193], v[96:99]
	v_mfma_f32_16x16x32_bf16 v[84:87], v[166:169], v[198:201], v[84:87]
	v_mfma_f32_16x16x32_bf16 v[80:83], v[174:177], v[198:201], v[80:83]
	v_mfma_f32_16x16x32_bf16 v[68:71], v[166:169], v[206:209], v[68:71]
	v_mfma_f32_16x16x32_bf16 v[64:67], v[174:177], v[206:209], v[64:67]
	v_mfma_f32_16x16x32_bf16 v[116:119], v[170:173], v[186:189], v[116:119]
	v_mfma_f32_16x16x32_bf16 v[112:115], v[178:181], v[186:189], v[112:115]
	v_mfma_f32_16x16x32_bf16 v[100:103], v[170:173], v[194:197], v[100:103]
	v_mfma_f32_16x16x32_bf16 v[96:99], v[178:181], v[194:197], v[96:99]
	v_mfma_f32_16x16x32_bf16 v[84:87], v[170:173], v[202:205], v[84:87]
	v_mfma_f32_16x16x32_bf16 v[80:83], v[178:181], v[202:205], v[80:83]
	v_mfma_f32_16x16x32_bf16 v[68:71], v[170:173], v[210:213], v[68:71]
	v_mfma_f32_16x16x32_bf16 v[64:67], v[178:181], v[210:213], v[64:67]
	s_setprio 0
	s_barrier
	s_add_i32 s3, s61, s8
	s_mov_b32 m0, s3
	ds_read_b128 v[182:185], v157 offset:16384
	ds_read_b128 v[186:189], v157 offset:17408
	ds_read_b128 v[190:193], v157 offset:18432
	ds_read_b128 v[194:197], v157 offset:19456
	ds_read_b128 v[198:201], v157 offset:20480
	ds_read_b128 v[202:205], v157 offset:21504
	ds_read_b128 v[206:209], v157 offset:22528
	ds_read_b128 v[210:213], v157 offset:23552
	global_load_lds_dwordx4 v130, s[56:57]
	s_add_i32 m0, s3, 0x2000
	s_add_u32 s64, s56, 0x20000
	s_addc_u32 s65, s57, 0
	s_add_i32 s3, s62, s8
	global_load_lds_dwordx4 v134, s[56:57]
	s_mov_b32 m0, s3
	s_nop 0
	global_load_lds_dwordx4 v130, s[64:65]
	s_add_i32 m0, s3, 0x2000
	s_nop 0
	global_load_lds_dwordx4 v134, s[64:65]
	s_mov_b32 m0, s9
	s_nop 0
	global_load_lds_dwordx4 v128, s[58:59]
	s_mov_b32 m0, s18
	s_nop 0
	global_load_lds_dwordx4 v132, s[58:59]
	s_waitcnt vmcnt(8)
	s_waitcnt lgkmcnt(0)
	s_barrier
	s_setprio 1
	s_waitcnt lgkmcnt(0)
	v_mfma_f32_16x16x32_bf16 v[60:63], v[144:147], v[182:185], v[60:63]
	v_mfma_f32_16x16x32_bf16 v[56:59], v[158:161], v[182:185], v[56:59]
	v_mfma_f32_16x16x32_bf16 v[44:47], v[144:147], v[190:193], v[44:47]
	v_mfma_f32_16x16x32_bf16 v[40:43], v[158:161], v[190:193], v[40:43]
	v_mfma_f32_16x16x32_bf16 v[28:31], v[144:147], v[198:201], v[28:31]
	v_mfma_f32_16x16x32_bf16 v[24:27], v[158:161], v[198:201], v[24:27]
	v_mfma_f32_16x16x32_bf16 v[12:15], v[144:147], v[206:209], v[12:15]
	v_mfma_f32_16x16x32_bf16 v[8:11], v[158:161], v[206:209], v[8:11]
	v_mfma_f32_16x16x32_bf16 v[60:63], v[148:151], v[186:189], v[60:63]
	v_mfma_f32_16x16x32_bf16 v[56:59], v[162:165], v[186:189], v[56:59]
	v_mfma_f32_16x16x32_bf16 v[44:47], v[148:151], v[194:197], v[44:47]
	v_mfma_f32_16x16x32_bf16 v[40:43], v[162:165], v[194:197], v[40:43]
	v_mfma_f32_16x16x32_bf16 v[28:31], v[148:151], v[202:205], v[28:31]
	v_mfma_f32_16x16x32_bf16 v[24:27], v[162:165], v[202:205], v[24:27]
	v_mfma_f32_16x16x32_bf16 v[12:15], v[148:151], v[210:213], v[12:15]
	v_mfma_f32_16x16x32_bf16 v[8:11], v[162:165], v[210:213], v[8:11]
	v_mfma_f32_16x16x32_bf16 v[52:55], v[166:169], v[182:185], v[52:55]
	v_mfma_f32_16x16x32_bf16 v[48:51], v[174:177], v[182:185], v[48:51]
	v_mfma_f32_16x16x32_bf16 v[36:39], v[166:169], v[190:193], v[36:39]
	v_mfma_f32_16x16x32_bf16 v[32:35], v[174:177], v[190:193], v[32:35]
	v_mfma_f32_16x16x32_bf16 v[20:23], v[166:169], v[198:201], v[20:23]
	v_mfma_f32_16x16x32_bf16 v[16:19], v[174:177], v[198:201], v[16:19]
	v_mfma_f32_16x16x32_bf16 v[4:7], v[166:169], v[206:209], v[4:7]
	v_mfma_f32_16x16x32_bf16 v[0:3], v[174:177], v[206:209], v[0:3]
	v_mfma_f32_16x16x32_bf16 v[52:55], v[170:173], v[186:189], v[52:55]
	v_mfma_f32_16x16x32_bf16 v[48:51], v[178:181], v[186:189], v[48:51]
	v_mfma_f32_16x16x32_bf16 v[36:39], v[170:173], v[194:197], v[36:39]
	v_mfma_f32_16x16x32_bf16 v[32:35], v[178:181], v[194:197], v[32:35]
	v_mfma_f32_16x16x32_bf16 v[20:23], v[170:173], v[202:205], v[20:23]
	v_mfma_f32_16x16x32_bf16 v[16:19], v[178:181], v[202:205], v[16:19]
	v_mfma_f32_16x16x32_bf16 v[4:7], v[170:173], v[210:213], v[4:7]
	v_mfma_f32_16x16x32_bf16 v[0:3], v[178:181], v[210:213], v[0:3]
	s_setprio 0
	s_barrier
	s_add_i32 s3, 0, 0x18000
	s_add_i32 s51, 0, 0x1c000
	v_add_u32_e32 v162, s3, v153
	v_add_u32_e32 v178, s51, v153
	ds_read_b128 v[144:147], v162
	ds_read_b128 v[148:151], v162 offset:1024
	ds_read_b128 v[158:161], v162 offset:2048
	ds_read_b128 v[162:165], v162 offset:3072
	ds_read_b128 v[166:169], v178
	ds_read_b128 v[170:173], v178 offset:1024
	ds_read_b128 v[174:177], v178 offset:2048
	ds_read_b128 v[178:181], v178 offset:3072
	s_add_u32 s58, s58, 0x20000
	s_addc_u32 s59, s59, 0
	s_mov_b32 m0, s19
	ds_read_b128 v[182:185], v157 offset:32768
	ds_read_b128 v[186:189], v157 offset:33792
	ds_read_b128 v[190:193], v157 offset:34816
	ds_read_b128 v[194:197], v157 offset:35840
	ds_read_b128 v[198:201], v157 offset:36864
	ds_read_b128 v[202:205], v157 offset:37888
	ds_read_b128 v[206:209], v157 offset:38912
	ds_read_b128 v[210:213], v157 offset:39936
	global_load_lds_dwordx4 v128, s[58:59]
	s_mov_b32 m0, s25
	s_nop 0
	global_load_lds_dwordx4 v132, s[58:59]
	s_waitcnt vmcnt(8)
	s_waitcnt lgkmcnt(0)
	s_barrier
	s_setprio 1
	s_waitcnt lgkmcnt(0)
	v_mfma_f32_16x16x32_bf16 v[124:127], v[144:147], v[182:185], v[124:127]
	v_mfma_f32_16x16x32_bf16 v[120:123], v[158:161], v[182:185], v[120:123]
	v_mfma_f32_16x16x32_bf16 v[108:111], v[144:147], v[190:193], v[108:111]
	v_mfma_f32_16x16x32_bf16 v[104:107], v[158:161], v[190:193], v[104:107]
	v_mfma_f32_16x16x32_bf16 v[92:95], v[144:147], v[198:201], v[92:95]
	v_mfma_f32_16x16x32_bf16 v[88:91], v[158:161], v[198:201], v[88:91]
	v_mfma_f32_16x16x32_bf16 v[76:79], v[144:147], v[206:209], v[76:79]
	v_mfma_f32_16x16x32_bf16 v[72:75], v[158:161], v[206:209], v[72:75]
	v_mfma_f32_16x16x32_bf16 v[124:127], v[148:151], v[186:189], v[124:127]
	v_mfma_f32_16x16x32_bf16 v[120:123], v[162:165], v[186:189], v[120:123]
	v_mfma_f32_16x16x32_bf16 v[108:111], v[148:151], v[194:197], v[108:111]
	v_mfma_f32_16x16x32_bf16 v[104:107], v[162:165], v[194:197], v[104:107]
	v_mfma_f32_16x16x32_bf16 v[92:95], v[148:151], v[202:205], v[92:95]
	v_mfma_f32_16x16x32_bf16 v[88:91], v[162:165], v[202:205], v[88:91]
	v_mfma_f32_16x16x32_bf16 v[76:79], v[148:151], v[210:213], v[76:79]
	v_mfma_f32_16x16x32_bf16 v[72:75], v[162:165], v[210:213], v[72:75]
	v_mfma_f32_16x16x32_bf16 v[116:119], v[166:169], v[182:185], v[116:119]
	v_mfma_f32_16x16x32_bf16 v[112:115], v[174:177], v[182:185], v[112:115]
	v_mfma_f32_16x16x32_bf16 v[100:103], v[166:169], v[190:193], v[100:103]
	v_mfma_f32_16x16x32_bf16 v[96:99], v[174:177], v[190:193], v[96:99]
	v_mfma_f32_16x16x32_bf16 v[84:87], v[166:169], v[198:201], v[84:87]
	v_mfma_f32_16x16x32_bf16 v[80:83], v[174:177], v[198:201], v[80:83]
	v_mfma_f32_16x16x32_bf16 v[68:71], v[166:169], v[206:209], v[68:71]
	v_mfma_f32_16x16x32_bf16 v[64:67], v[174:177], v[206:209], v[64:67]
	v_mfma_f32_16x16x32_bf16 v[116:119], v[170:173], v[186:189], v[116:119]
	v_mfma_f32_16x16x32_bf16 v[112:115], v[178:181], v[186:189], v[112:115]
	v_mfma_f32_16x16x32_bf16 v[100:103], v[170:173], v[194:197], v[100:103]
	v_mfma_f32_16x16x32_bf16 v[96:99], v[178:181], v[194:197], v[96:99]
	v_mfma_f32_16x16x32_bf16 v[84:87], v[170:173], v[202:205], v[84:87]
	v_mfma_f32_16x16x32_bf16 v[80:83], v[178:181], v[202:205], v[80:83]
	v_mfma_f32_16x16x32_bf16 v[68:71], v[170:173], v[210:213], v[68:71]
	v_mfma_f32_16x16x32_bf16 v[64:67], v[178:181], v[210:213], v[64:67]
	s_setprio 0
	s_barrier
	s_add_i32 s3, s3, s8
	s_add_u32 s56, s56, 0x80
	s_addc_u32 s57, s57, 0
	s_mov_b32 m0, s3
	ds_read_b128 v[182:185], v157 offset:49152
	ds_read_b128 v[186:189], v157 offset:50176
	ds_read_b128 v[190:193], v157 offset:51200
	ds_read_b128 v[194:197], v157 offset:52224
	ds_read_b128 v[198:201], v157 offset:53248
	ds_read_b128 v[202:205], v157 offset:54272
	ds_read_b128 v[206:209], v157 offset:55296
	ds_read_b128 v[210:213], v157 offset:56320
	global_load_lds_dwordx4 v130, s[56:57]
	s_add_i32 m0, s3, 0x2000
	s_add_i32 s3, s51, s8
	global_load_lds_dwordx4 v134, s[56:57]
	s_add_u32 s56, s56, 0x20000
	s_addc_u32 s57, s57, 0
	s_mov_b32 m0, s3
	s_nop 0
	global_load_lds_dwordx4 v130, s[56:57]
	s_add_i32 m0, s3, 0x2000
	s_nop 0
	global_load_lds_dwordx4 v134, s[56:57]
	s_add_u32 s58, s58, 0xfffe0080
	s_addc_u32 s59, s59, -1
	s_mov_b32 m0, s49
	s_nop 0
	global_load_lds_dwordx4 v128, s[58:59]
	s_mov_b32 m0, s60
	s_nop 0
	global_load_lds_dwordx4 v132, s[58:59]
	s_waitcnt vmcnt(8)
	s_waitcnt lgkmcnt(0)
	s_barrier
	s_setprio 1
	s_waitcnt lgkmcnt(0)
	v_mfma_f32_16x16x32_bf16 v[60:63], v[144:147], v[182:185], v[60:63]
	v_mfma_f32_16x16x32_bf16 v[56:59], v[158:161], v[182:185], v[56:59]
	v_mfma_f32_16x16x32_bf16 v[44:47], v[144:147], v[190:193], v[44:47]
	v_mfma_f32_16x16x32_bf16 v[40:43], v[158:161], v[190:193], v[40:43]
	v_mfma_f32_16x16x32_bf16 v[28:31], v[144:147], v[198:201], v[28:31]
	v_mfma_f32_16x16x32_bf16 v[24:27], v[158:161], v[198:201], v[24:27]
	v_mfma_f32_16x16x32_bf16 v[12:15], v[144:147], v[206:209], v[12:15]
	v_mfma_f32_16x16x32_bf16 v[8:11], v[158:161], v[206:209], v[8:11]
	v_mfma_f32_16x16x32_bf16 v[60:63], v[148:151], v[186:189], v[60:63]
	v_mfma_f32_16x16x32_bf16 v[56:59], v[162:165], v[186:189], v[56:59]
	v_mfma_f32_16x16x32_bf16 v[44:47], v[148:151], v[194:197], v[44:47]
	v_mfma_f32_16x16x32_bf16 v[40:43], v[162:165], v[194:197], v[40:43]
	v_mfma_f32_16x16x32_bf16 v[28:31], v[148:151], v[202:205], v[28:31]
	v_mfma_f32_16x16x32_bf16 v[24:27], v[162:165], v[202:205], v[24:27]
	v_mfma_f32_16x16x32_bf16 v[12:15], v[148:151], v[210:213], v[12:15]
	v_mfma_f32_16x16x32_bf16 v[8:11], v[162:165], v[210:213], v[8:11]
	v_mfma_f32_16x16x32_bf16 v[52:55], v[166:169], v[182:185], v[52:55]
	v_mfma_f32_16x16x32_bf16 v[48:51], v[174:177], v[182:185], v[48:51]
	v_mfma_f32_16x16x32_bf16 v[36:39], v[166:169], v[190:193], v[36:39]
	v_mfma_f32_16x16x32_bf16 v[32:35], v[174:177], v[190:193], v[32:35]
	v_mfma_f32_16x16x32_bf16 v[20:23], v[166:169], v[198:201], v[20:23]
	v_mfma_f32_16x16x32_bf16 v[16:19], v[174:177], v[198:201], v[16:19]
	v_mfma_f32_16x16x32_bf16 v[4:7], v[166:169], v[206:209], v[4:7]
	v_mfma_f32_16x16x32_bf16 v[0:3], v[174:177], v[206:209], v[0:3]
	v_mfma_f32_16x16x32_bf16 v[52:55], v[170:173], v[186:189], v[52:55]
	v_mfma_f32_16x16x32_bf16 v[48:51], v[178:181], v[186:189], v[48:51]
	v_mfma_f32_16x16x32_bf16 v[36:39], v[170:173], v[194:197], v[36:39]
	v_mfma_f32_16x16x32_bf16 v[32:35], v[178:181], v[194:197], v[32:35]
	v_mfma_f32_16x16x32_bf16 v[20:23], v[170:173], v[202:205], v[20:23]
	v_mfma_f32_16x16x32_bf16 v[16:19], v[178:181], v[202:205], v[16:19]
	v_mfma_f32_16x16x32_bf16 v[4:7], v[170:173], v[210:213], v[4:7]
	v_mfma_f32_16x16x32_bf16 v[0:3], v[178:181], v[210:213], v[0:3]
	s_setprio 0
	s_add_i32 s50, s50, 2
	s_add_u32 s52, s52, 0x100
	s_addc_u32 s53, s53, 0
	s_add_u32 s44, s44, 0x100
	s_addc_u32 s45, s45, 0
	s_cmp_gt_u32 s50, 5
	s_barrier
	s_cbranch_scc0 .LBB0_2272
	s_and_b64 vcc, exec, s[12:13]
	s_cbranch_vccz .LBB0_2275
	s_barrier

.LBB0_2348:
	ds_read_b128 v[140:143], v149
	ds_read_b128 v[152:155], v149 offset:1024
	ds_read_b128 v[156:159], v149 offset:2048
	ds_read_b128 v[160:163], v149 offset:3072
	ds_read_b128 v[164:167], v150
	ds_read_b128 v[168:171], v150 offset:1024
	ds_read_b128 v[172:175], v150 offset:2048
	ds_read_b128 v[176:179], v150 offset:3072
	s_add_u32 s3, s66, 0xfff80080
	s_addc_u32 s59, s67, -1
	s_cmp_eq_u32 s57, 28
	s_cselect_b32 s75, s0, s59
	s_cselect_b32 s74, s1, s3
	s_cselect_b32 s73, s44, s51
	s_cselect_b32 s72, s45, s50
	s_add_i32 m0, s9, 0xc000
	ds_read_b128 v[180:183], v151
	ds_read_b128 v[184:187], v151 offset:1024
	ds_read_b128 v[188:191], v151 offset:2048
	ds_read_b128 v[192:195], v151 offset:3072
	ds_read_b128 v[196:199], v151 offset:4096
	ds_read_b128 v[200:203], v151 offset:5120
	ds_read_b128 v[204:207], v151 offset:6144
	ds_read_b128 v[208:211], v151 offset:7168
	global_load_lds_dwordx4 v132, s[66:67]
	s_add_i32 m0, s9, 0xe000
	s_nop 0
	global_load_lds_dwordx4 v134, s[66:67]
	s_waitcnt vmcnt(8)
	s_waitcnt lgkmcnt(0)
	s_barrier
	s_setprio 1
	s_waitcnt lgkmcnt(0)
	v_mfma_f32_16x16x32_bf16 v[124:127], v[140:143], v[180:183], v[124:127]
	v_mfma_f32_16x16x32_bf16 v[120:123], v[156:159], v[180:183], v[120:123]
	v_mfma_f32_16x16x32_bf16 v[108:111], v[140:143], v[188:191], v[108:111]
	v_mfma_f32_16x16x32_bf16 v[104:107], v[156:159], v[188:191], v[104:107]
	v_mfma_f32_16x16x32_bf16 v[92:95], v[140:143], v[196:199], v[92:95]
	v_mfma_f32_16x16x32_bf16 v[88:91], v[156:159], v[196:199], v[88:91]
	v_mfma_f32_16x16x32_bf16 v[76:79], v[140:143], v[204:207], v[76:79]
	v_mfma_f32_16x16x32_bf16 v[72:75], v[156:159], v[204:207], v[72:75]
	v_mfma_f32_16x16x32_bf16 v[124:127], v[152:155], v[184:187], v[124:127]
	v_mfma_f32_16x16x32_bf16 v[120:123], v[160:163], v[184:187], v[120:123]
	v_mfma_f32_16x16x32_bf16 v[108:111], v[152:155], v[192:195], v[108:111]
	v_mfma_f32_16x16x32_bf16 v[104:107], v[160:163], v[192:195], v[104:107]
	v_mfma_f32_16x16x32_bf16 v[92:95], v[152:155], v[200:203], v[92:95]
	v_mfma_f32_16x16x32_bf16 v[88:91], v[160:163], v[200:203], v[88:91]
	v_mfma_f32_16x16x32_bf16 v[76:79], v[152:155], v[208:211], v[76:79]
	v_mfma_f32_16x16x32_bf16 v[72:75], v[160:163], v[208:211], v[72:75]
	v_mfma_f32_16x16x32_bf16 v[116:119], v[164:167], v[180:183], v[116:119]
	v_mfma_f32_16x16x32_bf16 v[112:115], v[172:175], v[180:183], v[112:115]
	v_mfma_f32_16x16x32_bf16 v[100:103], v[164:167], v[188:191], v[100:103]
	v_mfma_f32_16x16x32_bf16 v[96:99], v[172:175], v[188:191], v[96:99]
	v_mfma_f32_16x16x32_bf16 v[84:87], v[164:167], v[196:199], v[84:87]
	v_mfma_f32_16x16x32_bf16 v[80:83], v[172:175], v[196:199], v[80:83]
	v_mfma_f32_16x16x32_bf16 v[68:71], v[164:167], v[204:207], v[68:71]
	v_mfma_f32_16x16x32_bf16 v[64:67], v[172:175], v[204:207], v[64:67]
	v_mfma_f32_16x16x32_bf16 v[116:119], v[168:171], v[184:187], v[116:119]
	v_mfma_f32_16x16x32_bf16 v[112:115], v[176:179], v[184:187], v[112:115]
	v_mfma_f32_16x16x32_bf16 v[100:103], v[168:171], v[192:195], v[100:103]
	v_mfma_f32_16x16x32_bf16 v[96:99], v[176:179], v[192:195], v[96:99]
	v_mfma_f32_16x16x32_bf16 v[84:87], v[168:171], v[200:203], v[84:87]
	v_mfma_f32_16x16x32_bf16 v[80:83], v[176:179], v[200:203], v[80:83]
	v_mfma_f32_16x16x32_bf16 v[68:71], v[168:171], v[208:211], v[68:71]
	v_mfma_f32_16x16x32_bf16 v[64:67], v[176:179], v[208:211], v[64:67]
	s_setprio 0
	s_barrier
	s_add_i32 s3, s68, s8
	s_mov_b32 m0, s3
	ds_read_b128 v[180:183], v151 offset:16384
	ds_read_b128 v[184:187], v151 offset:17408
	ds_read_b128 v[188:191], v151 offset:18432
	ds_read_b128 v[192:195], v151 offset:19456
	ds_read_b128 v[196:199], v151 offset:20480
	ds_read_b128 v[200:203], v151 offset:21504
	ds_read_b128 v[204:207], v151 offset:22528
	ds_read_b128 v[208:211], v151 offset:23552
	global_load_lds_dwordx4 v128, s[72:73]
	s_add_i32 m0, s3, 0x2000
	s_add_u32 s70, s72, 0x80000
	s_addc_u32 s71, s73, 0
	s_add_i32 s3, s69, s8
	global_load_lds_dwordx4 v130, s[72:73]
	s_mov_b32 m0, s3
	s_nop 0
	global_load_lds_dwordx4 v128, s[70:71]
	s_add_i32 m0, s3, 0x2000
	s_nop 0
	global_load_lds_dwordx4 v130, s[70:71]
	s_mov_b32 m0, s9
	s_nop 0
	global_load_lds_dwordx4 v128, s[74:75]
	s_mov_b32 m0, s18
	s_nop 0
	global_load_lds_dwordx4 v130, s[74:75]
	s_waitcnt vmcnt(8)
	s_waitcnt lgkmcnt(0)
	s_barrier
	s_setprio 1
	s_waitcnt lgkmcnt(0)
	v_mfma_f32_16x16x32_bf16 v[60:63], v[140:143], v[180:183], v[60:63]
	v_mfma_f32_16x16x32_bf16 v[56:59], v[156:159], v[180:183], v[56:59]
	v_mfma_f32_16x16x32_bf16 v[44:47], v[140:143], v[188:191], v[44:47]
	v_mfma_f32_16x16x32_bf16 v[40:43], v[156:159], v[188:191], v[40:43]
	v_mfma_f32_16x16x32_bf16 v[28:31], v[140:143], v[196:199], v[28:31]
	v_mfma_f32_16x16x32_bf16 v[24:27], v[156:159], v[196:199], v[24:27]
	v_mfma_f32_16x16x32_bf16 v[12:15], v[140:143], v[204:207], v[12:15]
	v_mfma_f32_16x16x32_bf16 v[8:11], v[156:159], v[204:207], v[8:11]
	v_mfma_f32_16x16x32_bf16 v[60:63], v[152:155], v[184:187], v[60:63]
	v_mfma_f32_16x16x32_bf16 v[56:59], v[160:163], v[184:187], v[56:59]
	v_mfma_f32_16x16x32_bf16 v[44:47], v[152:155], v[192:195], v[44:47]
	v_mfma_f32_16x16x32_bf16 v[40:43], v[160:163], v[192:195], v[40:43]
	v_mfma_f32_16x16x32_bf16 v[28:31], v[152:155], v[200:203], v[28:31]
	v_mfma_f32_16x16x32_bf16 v[24:27], v[160:163], v[200:203], v[24:27]
	v_mfma_f32_16x16x32_bf16 v[12:15], v[152:155], v[208:211], v[12:15]
	v_mfma_f32_16x16x32_bf16 v[8:11], v[160:163], v[208:211], v[8:11]
	v_mfma_f32_16x16x32_bf16 v[52:55], v[164:167], v[180:183], v[52:55]
	v_mfma_f32_16x16x32_bf16 v[48:51], v[172:175], v[180:183], v[48:51]
	v_mfma_f32_16x16x32_bf16 v[36:39], v[164:167], v[188:191], v[36:39]
	v_mfma_f32_16x16x32_bf16 v[32:35], v[172:175], v[188:191], v[32:35]
	v_mfma_f32_16x16x32_bf16 v[20:23], v[164:167], v[196:199], v[20:23]
	v_mfma_f32_16x16x32_bf16 v[16:19], v[172:175], v[196:199], v[16:19]
	v_mfma_f32_16x16x32_bf16 v[4:7], v[164:167], v[204:207], v[4:7]
	v_mfma_f32_16x16x32_bf16 v[0:3], v[172:175], v[204:207], v[0:3]
	v_mfma_f32_16x16x32_bf16 v[52:55], v[168:171], v[184:187], v[52:55]
	v_mfma_f32_16x16x32_bf16 v[48:51], v[176:179], v[184:187], v[48:51]
	v_mfma_f32_16x16x32_bf16 v[36:39], v[168:171], v[192:195], v[36:39]
	v_mfma_f32_16x16x32_bf16 v[32:35], v[176:179], v[192:195], v[32:35]
	v_mfma_f32_16x16x32_bf16 v[20:23], v[168:171], v[200:203], v[20:23]
	v_mfma_f32_16x16x32_bf16 v[16:19], v[176:179], v[200:203], v[16:19]
	v_mfma_f32_16x16x32_bf16 v[4:7], v[168:171], v[208:211], v[4:7]
	v_mfma_f32_16x16x32_bf16 v[0:3], v[176:179], v[208:211], v[0:3]
	s_setprio 0
	s_barrier
	s_add_i32 s3, 0, 0x18000
	s_add_i32 s59, 0, 0x1c000
	v_add_u32_e32 v160, s3, v147
	v_add_u32_e32 v176, s59, v147
	ds_read_b128 v[140:143], v160
	ds_read_b128 v[152:155], v160 offset:1024
	ds_read_b128 v[156:159], v160 offset:2048
	ds_read_b128 v[160:163], v160 offset:3072
	ds_read_b128 v[164:167], v176
	ds_read_b128 v[168:171], v176 offset:1024
	ds_read_b128 v[172:175], v176 offset:2048
	ds_read_b128 v[176:179], v176 offset:3072
	s_add_u32 s70, s74, 0x80000
	s_addc_u32 s71, s75, 0
	s_mov_b32 m0, s19
	ds_read_b128 v[180:183], v151 offset:32768
	ds_read_b128 v[184:187], v151 offset:33792
	ds_read_b128 v[188:191], v151 offset:34816
	ds_read_b128 v[192:195], v151 offset:35840
	ds_read_b128 v[196:199], v151 offset:36864
	ds_read_b128 v[200:203], v151 offset:37888
	ds_read_b128 v[204:207], v151 offset:38912
	ds_read_b128 v[208:211], v151 offset:39936
	global_load_lds_dwordx4 v128, s[70:71]
	s_mov_b32 m0, s25
	s_nop 0
	global_load_lds_dwordx4 v130, s[70:71]
	s_waitcnt vmcnt(8)
	s_waitcnt lgkmcnt(0)
	s_barrier
	s_setprio 1
	s_waitcnt lgkmcnt(0)
	v_mfma_f32_16x16x32_bf16 v[124:127], v[140:143], v[180:183], v[124:127]
	v_mfma_f32_16x16x32_bf16 v[120:123], v[156:159], v[180:183], v[120:123]
	v_mfma_f32_16x16x32_bf16 v[108:111], v[140:143], v[188:191], v[108:111]
	v_mfma_f32_16x16x32_bf16 v[104:107], v[156:159], v[188:191], v[104:107]
	v_mfma_f32_16x16x32_bf16 v[92:95], v[140:143], v[196:199], v[92:95]
	v_mfma_f32_16x16x32_bf16 v[88:91], v[156:159], v[196:199], v[88:91]
	v_mfma_f32_16x16x32_bf16 v[76:79], v[140:143], v[204:207], v[76:79]
	v_mfma_f32_16x16x32_bf16 v[72:75], v[156:159], v[204:207], v[72:75]
	v_mfma_f32_16x16x32_bf16 v[124:127], v[152:155], v[184:187], v[124:127]
	v_mfma_f32_16x16x32_bf16 v[120:123], v[160:163], v[184:187], v[120:123]
	v_mfma_f32_16x16x32_bf16 v[108:111], v[152:155], v[192:195], v[108:111]
	v_mfma_f32_16x16x32_bf16 v[104:107], v[160:163], v[192:195], v[104:107]
	v_mfma_f32_16x16x32_bf16 v[92:95], v[152:155], v[200:203], v[92:95]
	v_mfma_f32_16x16x32_bf16 v[88:91], v[160:163], v[200:203], v[88:91]
	v_mfma_f32_16x16x32_bf16 v[76:79], v[152:155], v[208:211], v[76:79]
	v_mfma_f32_16x16x32_bf16 v[72:75], v[160:163], v[208:211], v[72:75]
	v_mfma_f32_16x16x32_bf16 v[116:119], v[164:167], v[180:183], v[116:119]
	v_mfma_f32_16x16x32_bf16 v[112:115], v[172:175], v[180:183], v[112:115]
	v_mfma_f32_16x16x32_bf16 v[100:103], v[164:167], v[188:191], v[100:103]
	v_mfma_f32_16x16x32_bf16 v[96:99], v[172:175], v[188:191], v[96:99]
	v_mfma_f32_16x16x32_bf16 v[84:87], v[164:167], v[196:199], v[84:87]
	v_mfma_f32_16x16x32_bf16 v[80:83], v[172:175], v[196:199], v[80:83]
	v_mfma_f32_16x16x32_bf16 v[68:71], v[164:167], v[204:207], v[68:71]
	v_mfma_f32_16x16x32_bf16 v[64:67], v[172:175], v[204:207], v[64:67]
	v_mfma_f32_16x16x32_bf16 v[116:119], v[168:171], v[184:187], v[116:119]
	v_mfma_f32_16x16x32_bf16 v[112:115], v[176:179], v[184:187], v[112:115]
	v_mfma_f32_16x16x32_bf16 v[100:103], v[168:171], v[192:195], v[100:103]
	v_mfma_f32_16x16x32_bf16 v[96:99], v[176:179], v[192:195], v[96:99]
	v_mfma_f32_16x16x32_bf16 v[84:87], v[168:171], v[200:203], v[84:87]
	v_mfma_f32_16x16x32_bf16 v[80:83], v[176:179], v[200:203], v[80:83]
	v_mfma_f32_16x16x32_bf16 v[68:71], v[168:171], v[208:211], v[68:71]
	v_mfma_f32_16x16x32_bf16 v[64:67], v[176:179], v[208:211], v[64:67]
	s_setprio 0
	s_barrier
	s_add_i32 s3, s3, s8
	s_add_u32 s70, s72, 0x80
	s_addc_u32 s71, s73, 0
	s_mov_b32 m0, s3
	ds_read_b128 v[180:183], v151 offset:49152
	ds_read_b128 v[184:187], v151 offset:50176
	ds_read_b128 v[188:191], v151 offset:51200
	ds_read_b128 v[192:195], v151 offset:52224
	ds_read_b128 v[196:199], v151 offset:53248
	ds_read_b128 v[200:203], v151 offset:54272
	ds_read_b128 v[204:207], v151 offset:55296
	ds_read_b128 v[208:211], v151 offset:56320
	global_load_lds_dwordx4 v128, s[70:71]
	s_add_i32 m0, s3, 0x2000
	s_add_i32 s3, s59, s8
	global_load_lds_dwordx4 v130, s[70:71]
	s_add_u32 s70, s70, 0x80000
	s_addc_u32 s71, s71, 0
	s_mov_b32 m0, s3
	s_nop 0
	global_load_lds_dwordx4 v128, s[70:71]
	s_add_i32 m0, s3, 0x2000
	s_nop 0
	global_load_lds_dwordx4 v130, s[70:71]
	s_add_u32 s74, s74, 0x80
	s_addc_u32 s75, s75, 0
	s_mov_b32 m0, s33
	s_nop 0
	global_load_lds_dwordx4 v128, s[74:75]
	s_mov_b32 m0, s65
	s_nop 0
	global_load_lds_dwordx4 v130, s[74:75]
	s_waitcnt vmcnt(8)
	s_waitcnt lgkmcnt(0)
	s_barrier
	s_setprio 1
	s_waitcnt lgkmcnt(0)
	v_mfma_f32_16x16x32_bf16 v[60:63], v[140:143], v[180:183], v[60:63]
	v_mfma_f32_16x16x32_bf16 v[56:59], v[156:159], v[180:183], v[56:59]
	v_mfma_f32_16x16x32_bf16 v[44:47], v[140:143], v[188:191], v[44:47]
	v_mfma_f32_16x16x32_bf16 v[40:43], v[156:159], v[188:191], v[40:43]
	v_mfma_f32_16x16x32_bf16 v[28:31], v[140:143], v[196:199], v[28:31]
	v_mfma_f32_16x16x32_bf16 v[24:27], v[156:159], v[196:199], v[24:27]
	v_mfma_f32_16x16x32_bf16 v[12:15], v[140:143], v[204:207], v[12:15]
	v_mfma_f32_16x16x32_bf16 v[8:11], v[156:159], v[204:207], v[8:11]
	v_mfma_f32_16x16x32_bf16 v[60:63], v[152:155], v[184:187], v[60:63]
	v_mfma_f32_16x16x32_bf16 v[56:59], v[160:163], v[184:187], v[56:59]
	v_mfma_f32_16x16x32_bf16 v[44:47], v[152:155], v[192:195], v[44:47]
	v_mfma_f32_16x16x32_bf16 v[40:43], v[160:163], v[192:195], v[40:43]
	v_mfma_f32_16x16x32_bf16 v[28:31], v[152:155], v[200:203], v[28:31]
	v_mfma_f32_16x16x32_bf16 v[24:27], v[160:163], v[200:203], v[24:27]
	v_mfma_f32_16x16x32_bf16 v[12:15], v[152:155], v[208:211], v[12:15]
	v_mfma_f32_16x16x32_bf16 v[8:11], v[160:163], v[208:211], v[8:11]
	v_mfma_f32_16x16x32_bf16 v[52:55], v[164:167], v[180:183], v[52:55]
	v_mfma_f32_16x16x32_bf16 v[48:51], v[172:175], v[180:183], v[48:51]
	v_mfma_f32_16x16x32_bf16 v[36:39], v[164:167], v[188:191], v[36:39]
	v_mfma_f32_16x16x32_bf16 v[32:35], v[172:175], v[188:191], v[32:35]
	v_mfma_f32_16x16x32_bf16 v[20:23], v[164:167], v[196:199], v[20:23]
	v_mfma_f32_16x16x32_bf16 v[16:19], v[172:175], v[196:199], v[16:19]
	v_mfma_f32_16x16x32_bf16 v[4:7], v[164:167], v[204:207], v[4:7]
	v_mfma_f32_16x16x32_bf16 v[0:3], v[172:175], v[204:207], v[0:3]
	v_mfma_f32_16x16x32_bf16 v[52:55], v[168:171], v[184:187], v[52:55]
	v_mfma_f32_16x16x32_bf16 v[48:51], v[176:179], v[184:187], v[48:51]
	v_mfma_f32_16x16x32_bf16 v[36:39], v[168:171], v[192:195], v[36:39]
	v_mfma_f32_16x16x32_bf16 v[32:35], v[176:179], v[192:195], v[32:35]
	v_mfma_f32_16x16x32_bf16 v[20:23], v[168:171], v[200:203], v[20:23]
	v_mfma_f32_16x16x32_bf16 v[16:19], v[176:179], v[200:203], v[16:19]
	v_mfma_f32_16x16x32_bf16 v[4:7], v[168:171], v[208:211], v[4:7]
	v_mfma_f32_16x16x32_bf16 v[0:3], v[176:179], v[208:211], v[0:3]
	s_setprio 0
	s_add_i32 s57, s57, 2
	s_add_u32 s66, s66, 0x100
	s_addc_u32 s67, s67, 0
	s_add_u32 s50, s50, 0x100
	s_addc_u32 s51, s51, 0
	s_cmp_gt_u32 s57, 29
	s_barrier
	s_cbranch_scc0 .LBB0_2348
	s_and_b64 vcc, exec, s[14:15]
	s_cbranch_vccz .LBB0_2351
	s_barrier

.LBB0_2479:
	ds_read_b128 v[154:157], v150
	ds_read_b128 v[158:161], v150 offset:1024
	ds_read_b128 v[162:165], v150 offset:2048
	ds_read_b128 v[166:169], v150 offset:3072
	ds_read_b128 v[170:173], v151
	ds_read_b128 v[174:177], v151 offset:1024
	ds_read_b128 v[178:181], v151 offset:2048
	ds_read_b128 v[182:185], v151 offset:3072
	s_add_u32 s3, s42, 0xfff80080
	s_addc_u32 s44, s43, -1
	s_cmp_eq_u32 s51, 28
	s_cselect_b32 s49, s0, s44
	s_cselect_b32 s48, s1, s3
	s_cselect_b32 s45, s15, s50
	s_cselect_b32 s44, s17, s41
	s_add_i32 m0, s19, 0xc000
	ds_read_b128 v[186:189], v152
	ds_read_b128 v[190:193], v152 offset:1024
	ds_read_b128 v[194:197], v152 offset:2048
	ds_read_b128 v[198:201], v152 offset:3072
	ds_read_b128 v[202:205], v152 offset:4096
	ds_read_b128 v[206:209], v152 offset:5120
	ds_read_b128 v[210:213], v152 offset:6144
	ds_read_b128 v[214:217], v152 offset:7168
	global_load_lds_dwordx4 v138, s[42:43]
	s_add_i32 m0, s19, 0xe000
	s_nop 0
	global_load_lds_dwordx4 v140, s[42:43]
	s_waitcnt vmcnt(8)
	s_waitcnt lgkmcnt(0)
	s_barrier
	s_setprio 1
	s_waitcnt lgkmcnt(0)
	v_mfma_f32_16x16x32_bf16 v[124:127], v[154:157], v[186:189], v[124:127]
	v_mfma_f32_16x16x32_bf16 v[120:123], v[162:165], v[186:189], v[120:123]
	v_mfma_f32_16x16x32_bf16 v[108:111], v[154:157], v[194:197], v[108:111]
	v_mfma_f32_16x16x32_bf16 v[104:107], v[162:165], v[194:197], v[104:107]
	v_mfma_f32_16x16x32_bf16 v[92:95], v[154:157], v[202:205], v[92:95]
	v_mfma_f32_16x16x32_bf16 v[88:91], v[162:165], v[202:205], v[88:91]
	v_mfma_f32_16x16x32_bf16 v[76:79], v[154:157], v[210:213], v[76:79]
	v_mfma_f32_16x16x32_bf16 v[72:75], v[162:165], v[210:213], v[72:75]
	v_mfma_f32_16x16x32_bf16 v[124:127], v[158:161], v[190:193], v[124:127]
	v_mfma_f32_16x16x32_bf16 v[120:123], v[166:169], v[190:193], v[120:123]
	v_mfma_f32_16x16x32_bf16 v[108:111], v[158:161], v[198:201], v[108:111]
	v_mfma_f32_16x16x32_bf16 v[104:107], v[166:169], v[198:201], v[104:107]
	v_mfma_f32_16x16x32_bf16 v[92:95], v[158:161], v[206:209], v[92:95]
	v_mfma_f32_16x16x32_bf16 v[88:91], v[166:169], v[206:209], v[88:91]
	v_mfma_f32_16x16x32_bf16 v[76:79], v[158:161], v[214:217], v[76:79]
	v_mfma_f32_16x16x32_bf16 v[72:75], v[166:169], v[214:217], v[72:75]
	v_mfma_f32_16x16x32_bf16 v[116:119], v[170:173], v[186:189], v[116:119]
	v_mfma_f32_16x16x32_bf16 v[112:115], v[178:181], v[186:189], v[112:115]
	v_mfma_f32_16x16x32_bf16 v[100:103], v[170:173], v[194:197], v[100:103]
	v_mfma_f32_16x16x32_bf16 v[96:99], v[178:181], v[194:197], v[96:99]
	v_mfma_f32_16x16x32_bf16 v[84:87], v[170:173], v[202:205], v[84:87]
	v_mfma_f32_16x16x32_bf16 v[80:83], v[178:181], v[202:205], v[80:83]
	v_mfma_f32_16x16x32_bf16 v[68:71], v[170:173], v[210:213], v[68:71]
	v_mfma_f32_16x16x32_bf16 v[64:67], v[178:181], v[210:213], v[64:67]
	v_mfma_f32_16x16x32_bf16 v[116:119], v[174:177], v[190:193], v[116:119]
	v_mfma_f32_16x16x32_bf16 v[112:115], v[182:185], v[190:193], v[112:115]
	v_mfma_f32_16x16x32_bf16 v[100:103], v[174:177], v[198:201], v[100:103]
	v_mfma_f32_16x16x32_bf16 v[96:99], v[182:185], v[198:201], v[96:99]
	v_mfma_f32_16x16x32_bf16 v[84:87], v[174:177], v[206:209], v[84:87]
	v_mfma_f32_16x16x32_bf16 v[80:83], v[182:185], v[206:209], v[80:83]
	v_mfma_f32_16x16x32_bf16 v[68:71], v[174:177], v[214:217], v[68:71]
	v_mfma_f32_16x16x32_bf16 v[64:67], v[182:185], v[214:217], v[64:67]
	s_setprio 0
	s_barrier
	s_add_i32 s3, s54, s18
	s_mov_b32 m0, s3
	ds_read_b128 v[186:189], v152 offset:16384
	ds_read_b128 v[190:193], v152 offset:17408
	ds_read_b128 v[194:197], v152 offset:18432
	ds_read_b128 v[198:201], v152 offset:19456
	ds_read_b128 v[202:205], v152 offset:20480
	ds_read_b128 v[206:209], v152 offset:21504
	ds_read_b128 v[210:213], v152 offset:22528
	ds_read_b128 v[214:217], v152 offset:23552
	global_load_lds_dwordx4 v130, s[44:45]
	s_add_i32 m0, s3, 0x2000
	s_add_u32 s58, s44, 0x80000
	s_addc_u32 s59, s45, 0
	s_add_i32 s3, s55, s18
	global_load_lds_dwordx4 v134, s[44:45]
	s_mov_b32 m0, s3
	s_nop 0
	global_load_lds_dwordx4 v130, s[58:59]
	s_add_i32 m0, s3, 0x2000
	s_nop 0
	global_load_lds_dwordx4 v134, s[58:59]
	s_mov_b32 m0, s19
	s_nop 0
	global_load_lds_dwordx4 v128, s[48:49]
	s_mov_b32 m0, s25
	s_nop 0
	global_load_lds_dwordx4 v132, s[48:49]
	s_waitcnt vmcnt(8)
	s_waitcnt lgkmcnt(0)
	s_barrier
	s_setprio 1
	s_waitcnt lgkmcnt(0)
	v_mfma_f32_16x16x32_bf16 v[60:63], v[154:157], v[186:189], v[60:63]
	v_mfma_f32_16x16x32_bf16 v[56:59], v[162:165], v[186:189], v[56:59]
	v_mfma_f32_16x16x32_bf16 v[44:47], v[154:157], v[194:197], v[44:47]
	v_mfma_f32_16x16x32_bf16 v[40:43], v[162:165], v[194:197], v[40:43]
	v_mfma_f32_16x16x32_bf16 v[28:31], v[154:157], v[202:205], v[28:31]
	v_mfma_f32_16x16x32_bf16 v[24:27], v[162:165], v[202:205], v[24:27]
	v_mfma_f32_16x16x32_bf16 v[12:15], v[154:157], v[210:213], v[12:15]
	v_mfma_f32_16x16x32_bf16 v[8:11], v[162:165], v[210:213], v[8:11]
	v_mfma_f32_16x16x32_bf16 v[60:63], v[158:161], v[190:193], v[60:63]
	v_mfma_f32_16x16x32_bf16 v[56:59], v[166:169], v[190:193], v[56:59]
	v_mfma_f32_16x16x32_bf16 v[44:47], v[158:161], v[198:201], v[44:47]
	v_mfma_f32_16x16x32_bf16 v[40:43], v[166:169], v[198:201], v[40:43]
	v_mfma_f32_16x16x32_bf16 v[28:31], v[158:161], v[206:209], v[28:31]
	v_mfma_f32_16x16x32_bf16 v[24:27], v[166:169], v[206:209], v[24:27]
	v_mfma_f32_16x16x32_bf16 v[12:15], v[158:161], v[214:217], v[12:15]
	v_mfma_f32_16x16x32_bf16 v[8:11], v[166:169], v[214:217], v[8:11]
	v_mfma_f32_16x16x32_bf16 v[52:55], v[170:173], v[186:189], v[52:55]
	v_mfma_f32_16x16x32_bf16 v[48:51], v[178:181], v[186:189], v[48:51]
	v_mfma_f32_16x16x32_bf16 v[36:39], v[170:173], v[194:197], v[36:39]
	v_mfma_f32_16x16x32_bf16 v[32:35], v[178:181], v[194:197], v[32:35]
	v_mfma_f32_16x16x32_bf16 v[20:23], v[170:173], v[202:205], v[20:23]
	v_mfma_f32_16x16x32_bf16 v[16:19], v[178:181], v[202:205], v[16:19]
	v_mfma_f32_16x16x32_bf16 v[4:7], v[170:173], v[210:213], v[4:7]
	v_mfma_f32_16x16x32_bf16 v[0:3], v[178:181], v[210:213], v[0:3]
	v_mfma_f32_16x16x32_bf16 v[52:55], v[174:177], v[190:193], v[52:55]
	v_mfma_f32_16x16x32_bf16 v[48:51], v[182:185], v[190:193], v[48:51]
	v_mfma_f32_16x16x32_bf16 v[36:39], v[174:177], v[198:201], v[36:39]
	v_mfma_f32_16x16x32_bf16 v[32:35], v[182:185], v[198:201], v[32:35]
	v_mfma_f32_16x16x32_bf16 v[20:23], v[174:177], v[206:209], v[20:23]
	v_mfma_f32_16x16x32_bf16 v[16:19], v[182:185], v[206:209], v[16:19]
	v_mfma_f32_16x16x32_bf16 v[4:7], v[174:177], v[214:217], v[4:7]
	v_mfma_f32_16x16x32_bf16 v[0:3], v[182:185], v[214:217], v[0:3]
	s_setprio 0
	s_barrier
	s_add_i32 s3, 0, 0x18000
	v_add_u32_e32 v153, s3, v149
	s_add_i32 s57, 0, 0x1c000
	ds_read_b128 v[154:157], v153
	ds_read_b128 v[158:161], v153 offset:1024
	ds_read_b128 v[162:165], v153 offset:2048
	ds_read_b128 v[166:169], v153 offset:3072
	v_add_u32_e32 v153, s57, v149
	ds_read_b128 v[170:173], v153
	ds_read_b128 v[174:177], v153 offset:1024
	ds_read_b128 v[178:181], v153 offset:2048
	ds_read_b128 v[182:185], v153 offset:3072
	s_add_u32 s48, s48, 0x80000
	s_addc_u32 s49, s49, 0
	s_mov_b32 m0, s27
	ds_read_b128 v[186:189], v152 offset:32768
	ds_read_b128 v[190:193], v152 offset:33792
	ds_read_b128 v[194:197], v152 offset:34816
	ds_read_b128 v[198:201], v152 offset:35840
	ds_read_b128 v[202:205], v152 offset:36864
	ds_read_b128 v[206:209], v152 offset:37888
	ds_read_b128 v[210:213], v152 offset:38912
	ds_read_b128 v[214:217], v152 offset:39936
	global_load_lds_dwordx4 v128, s[48:49]
	s_mov_b32 m0, s33
	s_nop 0
	global_load_lds_dwordx4 v132, s[48:49]
	s_waitcnt vmcnt(8)
	s_waitcnt lgkmcnt(0)
	s_barrier
	s_setprio 1
	s_waitcnt lgkmcnt(0)
	v_mfma_f32_16x16x32_bf16 v[124:127], v[154:157], v[186:189], v[124:127]
	v_mfma_f32_16x16x32_bf16 v[120:123], v[162:165], v[186:189], v[120:123]
	v_mfma_f32_16x16x32_bf16 v[108:111], v[154:157], v[194:197], v[108:111]
	v_mfma_f32_16x16x32_bf16 v[104:107], v[162:165], v[194:197], v[104:107]
	v_mfma_f32_16x16x32_bf16 v[92:95], v[154:157], v[202:205], v[92:95]
	v_mfma_f32_16x16x32_bf16 v[88:91], v[162:165], v[202:205], v[88:91]
	v_mfma_f32_16x16x32_bf16 v[76:79], v[154:157], v[210:213], v[76:79]
	v_mfma_f32_16x16x32_bf16 v[72:75], v[162:165], v[210:213], v[72:75]
	v_mfma_f32_16x16x32_bf16 v[124:127], v[158:161], v[190:193], v[124:127]
	v_mfma_f32_16x16x32_bf16 v[120:123], v[166:169], v[190:193], v[120:123]
	v_mfma_f32_16x16x32_bf16 v[108:111], v[158:161], v[198:201], v[108:111]
	v_mfma_f32_16x16x32_bf16 v[104:107], v[166:169], v[198:201], v[104:107]
	v_mfma_f32_16x16x32_bf16 v[92:95], v[158:161], v[206:209], v[92:95]
	v_mfma_f32_16x16x32_bf16 v[88:91], v[166:169], v[206:209], v[88:91]
	v_mfma_f32_16x16x32_bf16 v[76:79], v[158:161], v[214:217], v[76:79]
	v_mfma_f32_16x16x32_bf16 v[72:75], v[166:169], v[214:217], v[72:75]
	v_mfma_f32_16x16x32_bf16 v[116:119], v[170:173], v[186:189], v[116:119]
	v_mfma_f32_16x16x32_bf16 v[112:115], v[178:181], v[186:189], v[112:115]
	v_mfma_f32_16x16x32_bf16 v[100:103], v[170:173], v[194:197], v[100:103]
	v_mfma_f32_16x16x32_bf16 v[96:99], v[178:181], v[194:197], v[96:99]
	v_mfma_f32_16x16x32_bf16 v[84:87], v[170:173], v[202:205], v[84:87]
	v_mfma_f32_16x16x32_bf16 v[80:83], v[178:181], v[202:205], v[80:83]
	v_mfma_f32_16x16x32_bf16 v[68:71], v[170:173], v[210:213], v[68:71]
	v_mfma_f32_16x16x32_bf16 v[64:67], v[178:181], v[210:213], v[64:67]
	v_mfma_f32_16x16x32_bf16 v[116:119], v[174:177], v[190:193], v[116:119]
	v_mfma_f32_16x16x32_bf16 v[112:115], v[182:185], v[190:193], v[112:115]
	v_mfma_f32_16x16x32_bf16 v[100:103], v[174:177], v[198:201], v[100:103]
	v_mfma_f32_16x16x32_bf16 v[96:99], v[182:185], v[198:201], v[96:99]
	v_mfma_f32_16x16x32_bf16 v[84:87], v[174:177], v[206:209], v[84:87]
	v_mfma_f32_16x16x32_bf16 v[80:83], v[182:185], v[206:209], v[80:83]
	v_mfma_f32_16x16x32_bf16 v[68:71], v[174:177], v[214:217], v[68:71]
	v_mfma_f32_16x16x32_bf16 v[64:67], v[182:185], v[214:217], v[64:67]
	s_setprio 0
	s_barrier
	s_add_i32 s3, s3, s18
	s_add_u32 s44, s44, 0x80
	s_addc_u32 s45, s45, 0
	s_mov_b32 m0, s3
	ds_read_b128 v[186:189], v152 offset:49152
	ds_read_b128 v[190:193], v152 offset:50176
	ds_read_b128 v[194:197], v152 offset:51200
	ds_read_b128 v[198:201], v152 offset:52224
	ds_read_b128 v[202:205], v152 offset:53248
	ds_read_b128 v[206:209], v152 offset:54272
	ds_read_b128 v[210:213], v152 offset:55296
	ds_read_b128 v[214:217], v152 offset:56320
	global_load_lds_dwordx4 v130, s[44:45]
	s_add_i32 m0, s3, 0x2000
	s_add_i32 s3, s57, s18
	global_load_lds_dwordx4 v134, s[44:45]
	s_add_u32 s44, s44, 0x80000
	s_addc_u32 s45, s45, 0
	s_mov_b32 m0, s3
	s_nop 0
	global_load_lds_dwordx4 v130, s[44:45]
	s_add_i32 m0, s3, 0x2000
	s_nop 0
	global_load_lds_dwordx4 v134, s[44:45]
	s_add_u32 s48, s48, 0xfff80080
	s_addc_u32 s49, s49, -1
	s_mov_b32 m0, s52
	s_nop 0
	global_load_lds_dwordx4 v128, s[48:49]
	s_mov_b32 m0, s53
	s_nop 0
	global_load_lds_dwordx4 v132, s[48:49]
	s_waitcnt vmcnt(8)
	s_waitcnt lgkmcnt(0)
	s_barrier
	s_setprio 1
	s_waitcnt lgkmcnt(0)
	v_mfma_f32_16x16x32_bf16 v[60:63], v[154:157], v[186:189], v[60:63]
	v_mfma_f32_16x16x32_bf16 v[56:59], v[162:165], v[186:189], v[56:59]
	v_mfma_f32_16x16x32_bf16 v[44:47], v[154:157], v[194:197], v[44:47]
	v_mfma_f32_16x16x32_bf16 v[40:43], v[162:165], v[194:197], v[40:43]
	v_mfma_f32_16x16x32_bf16 v[28:31], v[154:157], v[202:205], v[28:31]
	v_mfma_f32_16x16x32_bf16 v[24:27], v[162:165], v[202:205], v[24:27]
	v_mfma_f32_16x16x32_bf16 v[12:15], v[154:157], v[210:213], v[12:15]
	v_mfma_f32_16x16x32_bf16 v[8:11], v[162:165], v[210:213], v[8:11]
	v_mfma_f32_16x16x32_bf16 v[60:63], v[158:161], v[190:193], v[60:63]
	v_mfma_f32_16x16x32_bf16 v[56:59], v[166:169], v[190:193], v[56:59]
	v_mfma_f32_16x16x32_bf16 v[44:47], v[158:161], v[198:201], v[44:47]
	v_mfma_f32_16x16x32_bf16 v[40:43], v[166:169], v[198:201], v[40:43]
	v_mfma_f32_16x16x32_bf16 v[28:31], v[158:161], v[206:209], v[28:31]
	v_mfma_f32_16x16x32_bf16 v[24:27], v[166:169], v[206:209], v[24:27]
	v_mfma_f32_16x16x32_bf16 v[12:15], v[158:161], v[214:217], v[12:15]
	v_mfma_f32_16x16x32_bf16 v[8:11], v[166:169], v[214:217], v[8:11]
	v_mfma_f32_16x16x32_bf16 v[52:55], v[170:173], v[186:189], v[52:55]
	v_mfma_f32_16x16x32_bf16 v[48:51], v[178:181], v[186:189], v[48:51]
	v_mfma_f32_16x16x32_bf16 v[36:39], v[170:173], v[194:197], v[36:39]
	v_mfma_f32_16x16x32_bf16 v[32:35], v[178:181], v[194:197], v[32:35]
	v_mfma_f32_16x16x32_bf16 v[20:23], v[170:173], v[202:205], v[20:23]
	v_mfma_f32_16x16x32_bf16 v[16:19], v[178:181], v[202:205], v[16:19]
	v_mfma_f32_16x16x32_bf16 v[4:7], v[170:173], v[210:213], v[4:7]
	v_mfma_f32_16x16x32_bf16 v[0:3], v[178:181], v[210:213], v[0:3]
	v_mfma_f32_16x16x32_bf16 v[52:55], v[174:177], v[190:193], v[52:55]
	v_mfma_f32_16x16x32_bf16 v[48:51], v[182:185], v[190:193], v[48:51]
	v_mfma_f32_16x16x32_bf16 v[36:39], v[174:177], v[198:201], v[36:39]
	v_mfma_f32_16x16x32_bf16 v[32:35], v[182:185], v[198:201], v[32:35]
	v_mfma_f32_16x16x32_bf16 v[20:23], v[174:177], v[206:209], v[20:23]
	v_mfma_f32_16x16x32_bf16 v[16:19], v[182:185], v[206:209], v[16:19]
	v_mfma_f32_16x16x32_bf16 v[4:7], v[174:177], v[214:217], v[4:7]
	v_mfma_f32_16x16x32_bf16 v[0:3], v[182:185], v[214:217], v[0:3]
	s_setprio 0
	s_add_i32 s51, s51, 2
	s_add_u32 s42, s42, 0x100
	s_addc_u32 s43, s43, 0
	s_add_u32 s41, s41, 0x100
	s_addc_u32 s50, s50, 0
	s_cmp_gt_u32 s51, 29
	s_barrier
	s_cbranch_scc0 .LBB0_2479
	s_and_b64 vcc, exec, s[12:13]
	s_cbranch_vccz .LBB0_2482
	s_barrier

.LBB0_2555:
	ds_read_b128 v[140:143], v149
	ds_read_b128 v[152:155], v149 offset:1024
	ds_read_b128 v[156:159], v149 offset:2048
	ds_read_b128 v[160:163], v149 offset:3072
	ds_read_b128 v[164:167], v150
	ds_read_b128 v[168:171], v150 offset:1024
	ds_read_b128 v[172:175], v150 offset:2048
	ds_read_b128 v[176:179], v150 offset:3072
	s_add_u32 s3, s48, 0xffe00080
	s_addc_u32 s52, s49, -1
	s_cmpk_eq_i32 s64, 0x7c
	s_cselect_b32 s55, s0, s52
	s_cselect_b32 s54, s1, s3
	s_cselect_b32 s53, s35, s51
	s_cselect_b32 s52, s37, s50
	s_add_i32 m0, s27, 0xc000
	ds_read_b128 v[180:183], v151
	ds_read_b128 v[184:187], v151 offset:1024
	ds_read_b128 v[188:191], v151 offset:2048
	ds_read_b128 v[192:195], v151 offset:3072
	ds_read_b128 v[196:199], v151 offset:4096
	ds_read_b128 v[200:203], v151 offset:5120
	ds_read_b128 v[204:207], v151 offset:6144
	ds_read_b128 v[208:211], v151 offset:7168
	global_load_lds_dwordx4 v132, s[48:49]
	s_add_i32 m0, s27, 0xe000
	s_nop 0
	global_load_lds_dwordx4 v134, s[48:49]
	s_waitcnt vmcnt(8)
	s_waitcnt lgkmcnt(0)
	s_barrier
	s_setprio 1
	s_waitcnt lgkmcnt(0)
	v_mfma_f32_16x16x32_bf16 v[124:127], v[140:143], v[180:183], v[124:127]
	v_mfma_f32_16x16x32_bf16 v[120:123], v[156:159], v[180:183], v[120:123]
	v_mfma_f32_16x16x32_bf16 v[112:115], v[140:143], v[188:191], v[112:115]
	v_mfma_f32_16x16x32_bf16 v[104:107], v[156:159], v[188:191], v[104:107]
	v_mfma_f32_16x16x32_bf16 v[96:99], v[140:143], v[196:199], v[96:99]
	v_mfma_f32_16x16x32_bf16 v[88:91], v[156:159], v[196:199], v[88:91]
	v_mfma_f32_16x16x32_bf16 v[80:83], v[140:143], v[204:207], v[80:83]
	v_mfma_f32_16x16x32_bf16 v[72:75], v[156:159], v[204:207], v[72:75]
	v_mfma_f32_16x16x32_bf16 v[124:127], v[152:155], v[184:187], v[124:127]
	v_mfma_f32_16x16x32_bf16 v[120:123], v[160:163], v[184:187], v[120:123]
	v_mfma_f32_16x16x32_bf16 v[112:115], v[152:155], v[192:195], v[112:115]
	v_mfma_f32_16x16x32_bf16 v[104:107], v[160:163], v[192:195], v[104:107]
	v_mfma_f32_16x16x32_bf16 v[96:99], v[152:155], v[200:203], v[96:99]
	v_mfma_f32_16x16x32_bf16 v[88:91], v[160:163], v[200:203], v[88:91]
	v_mfma_f32_16x16x32_bf16 v[80:83], v[152:155], v[208:211], v[80:83]
	v_mfma_f32_16x16x32_bf16 v[72:75], v[160:163], v[208:211], v[72:75]
	v_mfma_f32_16x16x32_bf16 v[116:119], v[164:167], v[180:183], v[116:119]
	v_mfma_f32_16x16x32_bf16 v[108:111], v[172:175], v[180:183], v[108:111]
	v_mfma_f32_16x16x32_bf16 v[100:103], v[164:167], v[188:191], v[100:103]
	v_mfma_f32_16x16x32_bf16 v[92:95], v[172:175], v[188:191], v[92:95]
	v_mfma_f32_16x16x32_bf16 v[84:87], v[164:167], v[196:199], v[84:87]
	v_mfma_f32_16x16x32_bf16 v[76:79], v[172:175], v[196:199], v[76:79]
	v_mfma_f32_16x16x32_bf16 v[68:71], v[164:167], v[204:207], v[68:71]
	v_mfma_f32_16x16x32_bf16 v[64:67], v[172:175], v[204:207], v[64:67]
	v_mfma_f32_16x16x32_bf16 v[116:119], v[168:171], v[184:187], v[116:119]
	v_mfma_f32_16x16x32_bf16 v[108:111], v[176:179], v[184:187], v[108:111]
	v_mfma_f32_16x16x32_bf16 v[100:103], v[168:171], v[192:195], v[100:103]
	v_mfma_f32_16x16x32_bf16 v[92:95], v[176:179], v[192:195], v[92:95]
	v_mfma_f32_16x16x32_bf16 v[84:87], v[168:171], v[200:203], v[84:87]
	v_mfma_f32_16x16x32_bf16 v[76:79], v[176:179], v[200:203], v[76:79]
	v_mfma_f32_16x16x32_bf16 v[68:71], v[168:171], v[208:211], v[68:71]
	v_mfma_f32_16x16x32_bf16 v[64:67], v[176:179], v[208:211], v[64:67]
	s_setprio 0
	s_barrier
	s_add_i32 s3, s58, s25
	s_mov_b32 m0, s3
	ds_read_b128 v[180:183], v151 offset:16384
	ds_read_b128 v[184:187], v151 offset:17408
	ds_read_b128 v[188:191], v151 offset:18432
	ds_read_b128 v[192:195], v151 offset:19456
	ds_read_b128 v[196:199], v151 offset:20480
	ds_read_b128 v[200:203], v151 offset:21504
	ds_read_b128 v[204:207], v151 offset:22528
	ds_read_b128 v[208:211], v151 offset:23552
	global_load_lds_dwordx4 v128, s[52:53]
	s_add_i32 m0, s3, 0x2000
	s_add_u32 s66, s52, 0x200000
	s_addc_u32 s67, s53, 0
	s_add_i32 s3, s59, s25
	global_load_lds_dwordx4 v130, s[52:53]
	s_mov_b32 m0, s3
	s_nop 0
	global_load_lds_dwordx4 v128, s[66:67]
	s_add_i32 m0, s3, 0x2000
	s_nop 0
	global_load_lds_dwordx4 v130, s[66:67]
	s_mov_b32 m0, s27
	s_nop 0
	global_load_lds_dwordx4 v128, s[54:55]
	s_mov_b32 m0, s30
	s_nop 0
	global_load_lds_dwordx4 v130, s[54:55]
	s_waitcnt vmcnt(8)
	s_waitcnt lgkmcnt(0)
	s_barrier
	s_setprio 1
	s_waitcnt lgkmcnt(0)
	v_mfma_f32_16x16x32_bf16 v[60:63], v[140:143], v[180:183], v[60:63]
	v_mfma_f32_16x16x32_bf16 v[56:59], v[156:159], v[180:183], v[56:59]
	v_mfma_f32_16x16x32_bf16 v[48:51], v[140:143], v[188:191], v[48:51]
	v_mfma_f32_16x16x32_bf16 v[40:43], v[156:159], v[188:191], v[40:43]
	v_mfma_f32_16x16x32_bf16 v[32:35], v[140:143], v[196:199], v[32:35]
	v_mfma_f32_16x16x32_bf16 v[24:27], v[156:159], v[196:199], v[24:27]
	v_mfma_f32_16x16x32_bf16 v[16:19], v[140:143], v[204:207], v[16:19]
	v_mfma_f32_16x16x32_bf16 v[8:11], v[156:159], v[204:207], v[8:11]
	v_mfma_f32_16x16x32_bf16 v[60:63], v[152:155], v[184:187], v[60:63]
	v_mfma_f32_16x16x32_bf16 v[56:59], v[160:163], v[184:187], v[56:59]
	v_mfma_f32_16x16x32_bf16 v[48:51], v[152:155], v[192:195], v[48:51]
	v_mfma_f32_16x16x32_bf16 v[40:43], v[160:163], v[192:195], v[40:43]
	v_mfma_f32_16x16x32_bf16 v[32:35], v[152:155], v[200:203], v[32:35]
	v_mfma_f32_16x16x32_bf16 v[24:27], v[160:163], v[200:203], v[24:27]
	v_mfma_f32_16x16x32_bf16 v[16:19], v[152:155], v[208:211], v[16:19]
	v_mfma_f32_16x16x32_bf16 v[8:11], v[160:163], v[208:211], v[8:11]
	v_mfma_f32_16x16x32_bf16 v[52:55], v[164:167], v[180:183], v[52:55]
	v_mfma_f32_16x16x32_bf16 v[44:47], v[172:175], v[180:183], v[44:47]
	v_mfma_f32_16x16x32_bf16 v[36:39], v[164:167], v[188:191], v[36:39]
	v_mfma_f32_16x16x32_bf16 v[28:31], v[172:175], v[188:191], v[28:31]
	v_mfma_f32_16x16x32_bf16 v[20:23], v[164:167], v[196:199], v[20:23]
	v_mfma_f32_16x16x32_bf16 v[12:15], v[172:175], v[196:199], v[12:15]
	v_mfma_f32_16x16x32_bf16 v[4:7], v[164:167], v[204:207], v[4:7]
	v_mfma_f32_16x16x32_bf16 v[0:3], v[172:175], v[204:207], v[0:3]
	v_mfma_f32_16x16x32_bf16 v[52:55], v[168:171], v[184:187], v[52:55]
	v_mfma_f32_16x16x32_bf16 v[44:47], v[176:179], v[184:187], v[44:47]
	v_mfma_f32_16x16x32_bf16 v[36:39], v[168:171], v[192:195], v[36:39]
	v_mfma_f32_16x16x32_bf16 v[28:31], v[176:179], v[192:195], v[28:31]
	v_mfma_f32_16x16x32_bf16 v[20:23], v[168:171], v[200:203], v[20:23]
	v_mfma_f32_16x16x32_bf16 v[12:15], v[176:179], v[200:203], v[12:15]
	v_mfma_f32_16x16x32_bf16 v[4:7], v[168:171], v[208:211], v[4:7]
	v_mfma_f32_16x16x32_bf16 v[0:3], v[176:179], v[208:211], v[0:3]
	s_setprio 0
	s_barrier
	s_add_i32 s3, 0, 0x18000
	s_add_i32 s65, 0, 0x1c000
	v_add_u32_e32 v160, s3, v147
	v_add_u32_e32 v176, s65, v147
	ds_read_b128 v[140:143], v160
	ds_read_b128 v[152:155], v160 offset:1024
	ds_read_b128 v[156:159], v160 offset:2048
	ds_read_b128 v[160:163], v160 offset:3072
	ds_read_b128 v[164:167], v176
	ds_read_b128 v[168:171], v176 offset:1024
	ds_read_b128 v[172:175], v176 offset:2048
	ds_read_b128 v[176:179], v176 offset:3072
	s_add_u32 s54, s54, 0x200000
	s_addc_u32 s55, s55, 0
	s_mov_b32 m0, s31
	ds_read_b128 v[180:183], v151 offset:32768
	ds_read_b128 v[184:187], v151 offset:33792
	ds_read_b128 v[188:191], v151 offset:34816
	ds_read_b128 v[192:195], v151 offset:35840
	ds_read_b128 v[196:199], v151 offset:36864
	ds_read_b128 v[200:203], v151 offset:37888
	ds_read_b128 v[204:207], v151 offset:38912
	ds_read_b128 v[208:211], v151 offset:39936
	global_load_lds_dwordx4 v128, s[54:55]
	s_mov_b32 m0, s33
	s_nop 0
	global_load_lds_dwordx4 v130, s[54:55]
	s_waitcnt vmcnt(8)
	s_waitcnt lgkmcnt(0)
	s_barrier
	s_setprio 1
	s_waitcnt lgkmcnt(0)
	v_mfma_f32_16x16x32_bf16 v[124:127], v[140:143], v[180:183], v[124:127]
	v_mfma_f32_16x16x32_bf16 v[120:123], v[156:159], v[180:183], v[120:123]
	v_mfma_f32_16x16x32_bf16 v[112:115], v[140:143], v[188:191], v[112:115]
	v_mfma_f32_16x16x32_bf16 v[104:107], v[156:159], v[188:191], v[104:107]
	v_mfma_f32_16x16x32_bf16 v[96:99], v[140:143], v[196:199], v[96:99]
	v_mfma_f32_16x16x32_bf16 v[88:91], v[156:159], v[196:199], v[88:91]
	v_mfma_f32_16x16x32_bf16 v[80:83], v[140:143], v[204:207], v[80:83]
	v_mfma_f32_16x16x32_bf16 v[72:75], v[156:159], v[204:207], v[72:75]
	v_mfma_f32_16x16x32_bf16 v[124:127], v[152:155], v[184:187], v[124:127]
	v_mfma_f32_16x16x32_bf16 v[120:123], v[160:163], v[184:187], v[120:123]
	v_mfma_f32_16x16x32_bf16 v[112:115], v[152:155], v[192:195], v[112:115]
	v_mfma_f32_16x16x32_bf16 v[104:107], v[160:163], v[192:195], v[104:107]
	v_mfma_f32_16x16x32_bf16 v[96:99], v[152:155], v[200:203], v[96:99]
	v_mfma_f32_16x16x32_bf16 v[88:91], v[160:163], v[200:203], v[88:91]
	v_mfma_f32_16x16x32_bf16 v[80:83], v[152:155], v[208:211], v[80:83]
	v_mfma_f32_16x16x32_bf16 v[72:75], v[160:163], v[208:211], v[72:75]
	v_mfma_f32_16x16x32_bf16 v[116:119], v[164:167], v[180:183], v[116:119]
	v_mfma_f32_16x16x32_bf16 v[108:111], v[172:175], v[180:183], v[108:111]
	v_mfma_f32_16x16x32_bf16 v[100:103], v[164:167], v[188:191], v[100:103]
	v_mfma_f32_16x16x32_bf16 v[92:95], v[172:175], v[188:191], v[92:95]
	v_mfma_f32_16x16x32_bf16 v[84:87], v[164:167], v[196:199], v[84:87]
	v_mfma_f32_16x16x32_bf16 v[76:79], v[172:175], v[196:199], v[76:79]
	v_mfma_f32_16x16x32_bf16 v[68:71], v[164:167], v[204:207], v[68:71]
	v_mfma_f32_16x16x32_bf16 v[64:67], v[172:175], v[204:207], v[64:67]
	v_mfma_f32_16x16x32_bf16 v[116:119], v[168:171], v[184:187], v[116:119]
	v_mfma_f32_16x16x32_bf16 v[108:111], v[176:179], v[184:187], v[108:111]
	v_mfma_f32_16x16x32_bf16 v[100:103], v[168:171], v[192:195], v[100:103]
	v_mfma_f32_16x16x32_bf16 v[92:95], v[176:179], v[192:195], v[92:95]
	v_mfma_f32_16x16x32_bf16 v[84:87], v[168:171], v[200:203], v[84:87]
	v_mfma_f32_16x16x32_bf16 v[76:79], v[176:179], v[200:203], v[76:79]
	v_mfma_f32_16x16x32_bf16 v[68:71], v[168:171], v[208:211], v[68:71]
	v_mfma_f32_16x16x32_bf16 v[64:67], v[176:179], v[208:211], v[64:67]
	s_setprio 0
	s_barrier
	s_add_i32 s3, s3, s25
	s_add_u32 s52, s52, 0x80
	s_addc_u32 s53, s53, 0
	s_mov_b32 m0, s3
	ds_read_b128 v[180:183], v151 offset:49152
	ds_read_b128 v[184:187], v151 offset:50176
	ds_read_b128 v[188:191], v151 offset:51200
	ds_read_b128 v[192:195], v151 offset:52224
	ds_read_b128 v[196:199], v151 offset:53248
	ds_read_b128 v[200:203], v151 offset:54272
	ds_read_b128 v[204:207], v151 offset:55296
	ds_read_b128 v[208:211], v151 offset:56320
	global_load_lds_dwordx4 v128, s[52:53]
	s_add_i32 m0, s3, 0x2000
	s_add_i32 s3, s65, s25
	global_load_lds_dwordx4 v130, s[52:53]
	s_add_u32 s52, s52, 0x200000
	s_addc_u32 s53, s53, 0
	s_mov_b32 m0, s3
	s_nop 0
	global_load_lds_dwordx4 v128, s[52:53]
	s_add_i32 m0, s3, 0x2000
	s_nop 0
	global_load_lds_dwordx4 v130, s[52:53]
	s_add_u32 s54, s54, 0xffe00080
	s_addc_u32 s55, s55, -1
	s_mov_b32 m0, s56
	s_nop 0
	global_load_lds_dwordx4 v128, s[54:55]
	s_mov_b32 m0, s57
	s_nop 0
	global_load_lds_dwordx4 v130, s[54:55]
	s_waitcnt vmcnt(8)
	s_waitcnt lgkmcnt(0)
	s_barrier
	s_setprio 1
	s_waitcnt lgkmcnt(0)
	v_mfma_f32_16x16x32_bf16 v[60:63], v[140:143], v[180:183], v[60:63]
	v_mfma_f32_16x16x32_bf16 v[56:59], v[156:159], v[180:183], v[56:59]
	v_mfma_f32_16x16x32_bf16 v[48:51], v[140:143], v[188:191], v[48:51]
	v_mfma_f32_16x16x32_bf16 v[40:43], v[156:159], v[188:191], v[40:43]
	v_mfma_f32_16x16x32_bf16 v[32:35], v[140:143], v[196:199], v[32:35]
	v_mfma_f32_16x16x32_bf16 v[24:27], v[156:159], v[196:199], v[24:27]
	v_mfma_f32_16x16x32_bf16 v[16:19], v[140:143], v[204:207], v[16:19]
	v_mfma_f32_16x16x32_bf16 v[8:11], v[156:159], v[204:207], v[8:11]
	v_mfma_f32_16x16x32_bf16 v[60:63], v[152:155], v[184:187], v[60:63]
	v_mfma_f32_16x16x32_bf16 v[56:59], v[160:163], v[184:187], v[56:59]
	v_mfma_f32_16x16x32_bf16 v[48:51], v[152:155], v[192:195], v[48:51]
	v_mfma_f32_16x16x32_bf16 v[40:43], v[160:163], v[192:195], v[40:43]
	v_mfma_f32_16x16x32_bf16 v[32:35], v[152:155], v[200:203], v[32:35]
	v_mfma_f32_16x16x32_bf16 v[24:27], v[160:163], v[200:203], v[24:27]
	v_mfma_f32_16x16x32_bf16 v[16:19], v[152:155], v[208:211], v[16:19]
	v_mfma_f32_16x16x32_bf16 v[8:11], v[160:163], v[208:211], v[8:11]
	v_mfma_f32_16x16x32_bf16 v[52:55], v[164:167], v[180:183], v[52:55]
	v_mfma_f32_16x16x32_bf16 v[44:47], v[172:175], v[180:183], v[44:47]
	v_mfma_f32_16x16x32_bf16 v[36:39], v[164:167], v[188:191], v[36:39]
	v_mfma_f32_16x16x32_bf16 v[28:31], v[172:175], v[188:191], v[28:31]
	v_mfma_f32_16x16x32_bf16 v[20:23], v[164:167], v[196:199], v[20:23]
	v_mfma_f32_16x16x32_bf16 v[12:15], v[172:175], v[196:199], v[12:15]
	v_mfma_f32_16x16x32_bf16 v[4:7], v[164:167], v[204:207], v[4:7]
	v_mfma_f32_16x16x32_bf16 v[0:3], v[172:175], v[204:207], v[0:3]
	v_mfma_f32_16x16x32_bf16 v[52:55], v[168:171], v[184:187], v[52:55]
	v_mfma_f32_16x16x32_bf16 v[44:47], v[176:179], v[184:187], v[44:47]
	v_mfma_f32_16x16x32_bf16 v[36:39], v[168:171], v[192:195], v[36:39]
	v_mfma_f32_16x16x32_bf16 v[28:31], v[176:179], v[192:195], v[28:31]
	v_mfma_f32_16x16x32_bf16 v[20:23], v[168:171], v[200:203], v[20:23]
	v_mfma_f32_16x16x32_bf16 v[12:15], v[176:179], v[200:203], v[12:15]
	v_mfma_f32_16x16x32_bf16 v[4:7], v[168:171], v[208:211], v[4:7]
	v_mfma_f32_16x16x32_bf16 v[0:3], v[176:179], v[208:211], v[0:3]
	s_setprio 0
	s_add_i32 s64, s64, 2
	s_add_u32 s48, s48, 0x100
	s_addc_u32 s49, s49, 0
	s_add_u32 s50, s50, 0x100
	s_addc_u32 s51, s51, 0
	s_cmpk_gt_u32 s64, 0x7d
	s_barrier
	s_cbranch_scc0 .LBB0_2555
	s_and_b64 vcc, exec, s[10:11]
	s_cbranch_vccz .LBB0_2558
	s_barrier
